# GEMM blocks: accumulator pairs in snake order over (n,m) so adjacent pairs always share one fragment; attention main loop: P.V MFMAs as 4-long accumulator chains; all bit-identical
# speedup vs baseline: 1.0112x; 1.0027x over previous
.LBB0_90:
	s_add_u32 s29, s76, 0xfff80080
	s_addc_u32 s30, s77, -1
	s_add_i32 s31, 0, 0x10000
	s_cmp_eq_u32 s28, 28
	s_cselect_b32 s85, s22, s30
	s_cselect_b32 s84, s23, s29
	v_add_u32_e32 v158, s31, v160
	s_cselect_b32 s55, s24, s27
	s_cselect_b32 s54, s25, s26
	s_add_i32 s29, 0, 0x14000
	ds_read_b128 v[154:157], v158
	ds_read_b128 v[180:183], v158 offset:1024
	ds_read_b128 v[184:187], v158 offset:2048
	ds_read_b128 v[188:191], v158 offset:3072
	v_add_u32_e32 v158, s29, v160
	ds_read_b128 v[192:195], v158
	ds_read_b128 v[196:199], v158 offset:1024
	ds_read_b128 v[200:203], v158 offset:2048
	ds_read_b128 v[204:207], v158 offset:3072
	v_lshl_add_u64 v[158:159], s[76:77], 0, v[152:153]
	s_add_i32 m0, s13, 0xc000
	ds_read_b128 v[208:211], v162
	ds_read_b128 v[212:215], v162 offset:1024
	ds_read_b128 v[216:219], v162 offset:2048
	ds_read_b128 v[222:225], v162 offset:3072
	ds_read_b128 v[226:229], v162 offset:4096
	ds_read_b128 v[230:233], v162 offset:5120
	ds_read_b128 v[234:237], v162 offset:6144
	ds_read_b128 v[238:241], v162 offset:7168
	global_load_lds_dwordx4 v[158:159], off
	v_lshl_add_u64 v[158:159], s[76:77], 0, v[150:151]
	s_add_i32 m0, s13, 0xe000
	s_nop 0
	global_load_lds_dwordx4 v[158:159], off
	s_waitcnt vmcnt(8)
	s_waitcnt lgkmcnt(0)
	s_barrier
	s_setprio 1
	s_waitcnt lgkmcnt(0)
	v_mfma_f32_16x16x32_bf16 v[128:131], v[154:157], v[208:211], v[128:131]
	v_mfma_f32_16x16x32_bf16 v[128:131], v[180:183], v[212:215], v[128:131]
	v_mfma_f32_16x16x32_bf16 v[120:123], v[154:157], v[216:219], v[120:123]
	v_mfma_f32_16x16x32_bf16 v[120:123], v[180:183], v[222:225], v[120:123]
	v_mfma_f32_16x16x32_bf16 v[104:107], v[154:157], v[226:229], v[104:107]
	v_mfma_f32_16x16x32_bf16 v[104:107], v[180:183], v[230:233], v[104:107]
	v_mfma_f32_16x16x32_bf16 v[88:91], v[154:157], v[234:237], v[88:91]
	v_mfma_f32_16x16x32_bf16 v[88:91], v[180:183], v[238:241], v[88:91]
	v_mfma_f32_16x16x32_bf16 v[80:83], v[184:187], v[234:237], v[80:83]
	v_mfma_f32_16x16x32_bf16 v[80:83], v[188:191], v[238:241], v[80:83]
	v_mfma_f32_16x16x32_bf16 v[96:99], v[184:187], v[226:229], v[96:99]
	v_mfma_f32_16x16x32_bf16 v[96:99], v[188:191], v[230:233], v[96:99]
	v_mfma_f32_16x16x32_bf16 v[112:115], v[184:187], v[216:219], v[112:115]
	v_mfma_f32_16x16x32_bf16 v[112:115], v[188:191], v[222:225], v[112:115]
	v_mfma_f32_16x16x32_bf16 v[124:127], v[184:187], v[208:211], v[124:127]
	v_mfma_f32_16x16x32_bf16 v[124:127], v[188:191], v[212:215], v[124:127]
	s_setprio 0
	s_setprio 1
	v_mfma_f32_16x16x32_bf16 v[116:119], v[192:195], v[208:211], v[116:119]
	v_mfma_f32_16x16x32_bf16 v[116:119], v[196:199], v[212:215], v[116:119]
	v_mfma_f32_16x16x32_bf16 v[100:103], v[192:195], v[216:219], v[100:103]
	v_mfma_f32_16x16x32_bf16 v[100:103], v[196:199], v[222:225], v[100:103]
	v_mfma_f32_16x16x32_bf16 v[84:87], v[192:195], v[226:229], v[84:87]
	v_mfma_f32_16x16x32_bf16 v[84:87], v[196:199], v[230:233], v[84:87]
	v_mfma_f32_16x16x32_bf16 v[72:75], v[192:195], v[234:237], v[72:75]
	v_mfma_f32_16x16x32_bf16 v[72:75], v[196:199], v[238:241], v[72:75]
	v_mfma_f32_16x16x32_bf16 v[68:71], v[200:203], v[234:237], v[68:71]
	v_mfma_f32_16x16x32_bf16 v[68:71], v[204:207], v[238:241], v[68:71]
	v_mfma_f32_16x16x32_bf16 v[76:79], v[200:203], v[226:229], v[76:79]
	v_mfma_f32_16x16x32_bf16 v[76:79], v[204:207], v[230:233], v[76:79]
	v_mfma_f32_16x16x32_bf16 v[92:95], v[200:203], v[216:219], v[92:95]
	v_mfma_f32_16x16x32_bf16 v[92:95], v[204:207], v[222:225], v[92:95]
	v_mfma_f32_16x16x32_bf16 v[108:111], v[200:203], v[208:211], v[108:111]
	v_mfma_f32_16x16x32_bf16 v[108:111], v[204:207], v[212:215], v[108:111]
	s_setprio 0
	s_barrier
	s_add_i32 s30, s31, s12
	v_lshl_add_u64 v[158:159], s[54:55], 0, v[34:35]
	s_mov_b32 m0, s30
	ds_read_b128 v[208:211], v162 offset:16384
	ds_read_b128 v[212:215], v162 offset:17408
	ds_read_b128 v[216:219], v162 offset:18432
	ds_read_b128 v[222:225], v162 offset:19456
	ds_read_b128 v[226:229], v162 offset:20480
	ds_read_b128 v[230:233], v162 offset:21504
	ds_read_b128 v[234:237], v162 offset:22528
	ds_read_b128 v[238:241], v162 offset:23552
	global_load_lds_dwordx4 v[158:159], off
	s_add_i32 m0, s30, 0x2000
	s_add_u32 s30, s54, 0x80000
	v_lshl_add_u64 v[242:243], s[54:55], 0, v[146:147]
	s_addc_u32 s31, s55, 0
	s_add_i32 s29, s29, s12
	global_load_lds_dwordx4 v[242:243], off
	v_lshl_add_u64 v[244:245], s[30:31], 0, v[34:35]
	s_mov_b32 m0, s29
	v_lshl_add_u64 v[246:247], s[84:85], 0, v[144:145]
	global_load_lds_dwordx4 v[244:245], off
	v_lshl_add_u64 v[244:245], s[30:31], 0, v[146:147]
	s_add_i32 m0, s29, 0x2000
	s_nop 0
	global_load_lds_dwordx4 v[244:245], off
	v_lshl_add_u64 v[244:245], s[84:85], 0, v[142:143]
	s_mov_b32 m0, s13
	s_nop 0
	global_load_lds_dwordx4 v[244:245], off
	s_mov_b32 m0, s14
	s_nop 0
	global_load_lds_dwordx4 v[246:247], off
	s_waitcnt vmcnt(8)
	s_waitcnt lgkmcnt(0)
	s_barrier
	s_setprio 1
	s_waitcnt lgkmcnt(0)
	v_mfma_f32_16x16x32_bf16 v[64:67], v[154:157], v[208:211], v[64:67]
	v_mfma_f32_16x16x32_bf16 v[64:67], v[180:183], v[212:215], v[64:67]
	v_mfma_f32_16x16x32_bf16 v[56:59], v[154:157], v[216:219], v[56:59]
	v_mfma_f32_16x16x32_bf16 v[56:59], v[180:183], v[222:225], v[56:59]
	v_mfma_f32_16x16x32_bf16 v[40:43], v[154:157], v[226:229], v[40:43]
	v_mfma_f32_16x16x32_bf16 v[40:43], v[180:183], v[230:233], v[40:43]
	v_mfma_f32_16x16x32_bf16 v[22:25], v[154:157], v[234:237], v[22:25]
	v_mfma_f32_16x16x32_bf16 v[22:25], v[180:183], v[238:241], v[22:25]
	v_mfma_f32_16x16x32_bf16 v[14:17], v[184:187], v[234:237], v[14:17]
	v_mfma_f32_16x16x32_bf16 v[14:17], v[188:191], v[238:241], v[14:17]
	v_mfma_f32_16x16x32_bf16 v[30:33], v[184:187], v[226:229], v[30:33]
	v_mfma_f32_16x16x32_bf16 v[30:33], v[188:191], v[230:233], v[30:33]
	v_mfma_f32_16x16x32_bf16 v[48:51], v[184:187], v[216:219], v[48:51]
	v_mfma_f32_16x16x32_bf16 v[48:51], v[188:191], v[222:225], v[48:51]
	v_mfma_f32_16x16x32_bf16 v[60:63], v[184:187], v[208:211], v[60:63]
	v_mfma_f32_16x16x32_bf16 v[60:63], v[188:191], v[212:215], v[60:63]
	s_setprio 0
	s_setprio 1
	v_mfma_f32_16x16x32_bf16 v[52:55], v[192:195], v[208:211], v[52:55]
	v_mfma_f32_16x16x32_bf16 v[52:55], v[196:199], v[212:215], v[52:55]
	v_mfma_f32_16x16x32_bf16 v[36:39], v[192:195], v[216:219], v[36:39]
	v_mfma_f32_16x16x32_bf16 v[36:39], v[196:199], v[222:225], v[36:39]
	v_mfma_f32_16x16x32_bf16 v[18:21], v[192:195], v[226:229], v[18:21]
	v_mfma_f32_16x16x32_bf16 v[18:21], v[196:199], v[230:233], v[18:21]
	v_mfma_f32_16x16x32_bf16 v[6:9], v[192:195], v[234:237], v[6:9]
	v_mfma_f32_16x16x32_bf16 v[6:9], v[196:199], v[238:241], v[6:9]
	v_mfma_f32_16x16x32_bf16 v[2:5], v[200:203], v[234:237], v[2:5]
	v_mfma_f32_16x16x32_bf16 v[2:5], v[204:207], v[238:241], v[2:5]
	v_mfma_f32_16x16x32_bf16 v[10:13], v[200:203], v[226:229], v[10:13]
	v_mfma_f32_16x16x32_bf16 v[10:13], v[204:207], v[230:233], v[10:13]
	v_mfma_f32_16x16x32_bf16 v[26:29], v[200:203], v[216:219], v[26:29]
	v_mfma_f32_16x16x32_bf16 v[26:29], v[204:207], v[222:225], v[26:29]
	v_mfma_f32_16x16x32_bf16 v[44:47], v[200:203], v[208:211], v[44:47]
	v_mfma_f32_16x16x32_bf16 v[44:47], v[204:207], v[212:215], v[44:47]
	s_setprio 0
	s_barrier
	s_add_i32 s29, 0, 0x18000
	v_add_u32_e32 v163, s29, v160
	s_add_i32 s39, 0, 0x1c000
	ds_read_b128 v[154:157], v163
	ds_read_b128 v[180:183], v163 offset:1024
	ds_read_b128 v[184:187], v163 offset:2048
	ds_read_b128 v[188:191], v163 offset:3072
	v_add_u32_e32 v163, s39, v160
	ds_read_b128 v[192:195], v163
	ds_read_b128 v[196:199], v163 offset:1024
	ds_read_b128 v[200:203], v163 offset:2048
	ds_read_b128 v[204:207], v163 offset:3072
	s_add_u32 s30, s84, 0x80000
	s_addc_u32 s31, s85, 0
	s_mov_b32 m0, s15
	v_lshl_add_u64 v[248:249], s[30:31], 0, v[142:143]
	ds_read_b128 v[208:211], v162 offset:32768
	ds_read_b128 v[212:215], v162 offset:33792
	ds_read_b128 v[216:219], v162 offset:34816
	ds_read_b128 v[222:225], v162 offset:35840
	ds_read_b128 v[226:229], v162 offset:36864
	ds_read_b128 v[230:233], v162 offset:37888
	ds_read_b128 v[234:237], v162 offset:38912
	ds_read_b128 v[238:241], v162 offset:39936
	global_load_lds_dwordx4 v[248:249], off
	v_lshl_add_u64 v[248:249], s[30:31], 0, v[144:145]
	s_mov_b32 m0, s16
	s_nop 0
	global_load_lds_dwordx4 v[248:249], off
	s_waitcnt vmcnt(8)
	s_waitcnt lgkmcnt(0)
	s_barrier
	s_setprio 1
	s_waitcnt lgkmcnt(0)
	v_mfma_f32_16x16x32_bf16 v[128:131], v[154:157], v[208:211], v[128:131]
	v_mfma_f32_16x16x32_bf16 v[128:131], v[180:183], v[212:215], v[128:131]
	v_mfma_f32_16x16x32_bf16 v[120:123], v[154:157], v[216:219], v[120:123]
	v_mfma_f32_16x16x32_bf16 v[120:123], v[180:183], v[222:225], v[120:123]
	v_mfma_f32_16x16x32_bf16 v[104:107], v[154:157], v[226:229], v[104:107]
	v_mfma_f32_16x16x32_bf16 v[104:107], v[180:183], v[230:233], v[104:107]
	v_mfma_f32_16x16x32_bf16 v[88:91], v[154:157], v[234:237], v[88:91]
	v_mfma_f32_16x16x32_bf16 v[88:91], v[180:183], v[238:241], v[88:91]
	v_mfma_f32_16x16x32_bf16 v[80:83], v[184:187], v[234:237], v[80:83]
	v_mfma_f32_16x16x32_bf16 v[80:83], v[188:191], v[238:241], v[80:83]
	v_mfma_f32_16x16x32_bf16 v[96:99], v[184:187], v[226:229], v[96:99]
	v_mfma_f32_16x16x32_bf16 v[96:99], v[188:191], v[230:233], v[96:99]
	v_mfma_f32_16x16x32_bf16 v[112:115], v[184:187], v[216:219], v[112:115]
	v_mfma_f32_16x16x32_bf16 v[112:115], v[188:191], v[222:225], v[112:115]
	v_mfma_f32_16x16x32_bf16 v[124:127], v[184:187], v[208:211], v[124:127]
	v_mfma_f32_16x16x32_bf16 v[124:127], v[188:191], v[212:215], v[124:127]
	s_setprio 0
	s_setprio 1
	v_mfma_f32_16x16x32_bf16 v[116:119], v[192:195], v[208:211], v[116:119]
	v_mfma_f32_16x16x32_bf16 v[116:119], v[196:199], v[212:215], v[116:119]
	v_mfma_f32_16x16x32_bf16 v[100:103], v[192:195], v[216:219], v[100:103]
	v_mfma_f32_16x16x32_bf16 v[100:103], v[196:199], v[222:225], v[100:103]
	v_mfma_f32_16x16x32_bf16 v[84:87], v[192:195], v[226:229], v[84:87]
	v_mfma_f32_16x16x32_bf16 v[84:87], v[196:199], v[230:233], v[84:87]
	v_mfma_f32_16x16x32_bf16 v[72:75], v[192:195], v[234:237], v[72:75]
	v_mfma_f32_16x16x32_bf16 v[72:75], v[196:199], v[238:241], v[72:75]
	v_mfma_f32_16x16x32_bf16 v[68:71], v[200:203], v[234:237], v[68:71]
	v_mfma_f32_16x16x32_bf16 v[68:71], v[204:207], v[238:241], v[68:71]
	v_mfma_f32_16x16x32_bf16 v[76:79], v[200:203], v[226:229], v[76:79]
	v_mfma_f32_16x16x32_bf16 v[76:79], v[204:207], v[230:233], v[76:79]
	v_mfma_f32_16x16x32_bf16 v[92:95], v[200:203], v[216:219], v[92:95]
	v_mfma_f32_16x16x32_bf16 v[92:95], v[204:207], v[222:225], v[92:95]
	v_mfma_f32_16x16x32_bf16 v[108:111], v[200:203], v[208:211], v[108:111]
	v_mfma_f32_16x16x32_bf16 v[108:111], v[204:207], v[212:215], v[108:111]
	s_setprio 0
	s_barrier
	s_add_i32 s29, s29, s12
	v_lshl_add_u64 v[158:159], v[158:159], 0, s[78:79]
	s_mov_b32 m0, s29
	ds_read_b128 v[208:211], v162 offset:49152
	ds_read_b128 v[212:215], v162 offset:50176
	ds_read_b128 v[216:219], v162 offset:51200
	ds_read_b128 v[222:225], v162 offset:52224
	ds_read_b128 v[226:229], v162 offset:53248
	ds_read_b128 v[230:233], v162 offset:54272
	ds_read_b128 v[234:237], v162 offset:55296
	ds_read_b128 v[238:241], v162 offset:56320
	global_load_lds_dwordx4 v[158:159], off
	s_add_i32 m0, s29, 0x2000
	s_add_u32 s30, s54, 0x80080
	v_lshl_add_u64 v[158:159], v[242:243], 0, s[78:79]
	s_addc_u32 s31, s55, 0
	s_add_i32 s29, s39, s12
	global_load_lds_dwordx4 v[158:159], off
	v_lshl_add_u64 v[158:159], s[30:31], 0, v[34:35]
	s_mov_b32 m0, s29
	s_nop 0
	global_load_lds_dwordx4 v[158:159], off
	v_lshl_add_u64 v[158:159], s[30:31], 0, v[146:147]
	s_add_i32 m0, s29, 0x2000
	s_nop 0
	global_load_lds_dwordx4 v[158:159], off
	v_lshl_add_u64 v[158:159], v[244:245], 0, s[78:79]
	s_mov_b32 m0, s18
	s_nop 0
	global_load_lds_dwordx4 v[158:159], off
	v_lshl_add_u64 v[158:159], v[246:247], 0, s[78:79]
	s_mov_b32 m0, s19
	s_nop 0
	global_load_lds_dwordx4 v[158:159], off
	s_waitcnt vmcnt(8)
	s_waitcnt lgkmcnt(0)
	s_barrier
	s_setprio 1
	s_waitcnt lgkmcnt(0)
	v_mfma_f32_16x16x32_bf16 v[64:67], v[154:157], v[208:211], v[64:67]
	v_mfma_f32_16x16x32_bf16 v[64:67], v[180:183], v[212:215], v[64:67]
	v_mfma_f32_16x16x32_bf16 v[56:59], v[154:157], v[216:219], v[56:59]
	v_mfma_f32_16x16x32_bf16 v[56:59], v[180:183], v[222:225], v[56:59]
	v_mfma_f32_16x16x32_bf16 v[40:43], v[154:157], v[226:229], v[40:43]
	v_mfma_f32_16x16x32_bf16 v[40:43], v[180:183], v[230:233], v[40:43]
	v_mfma_f32_16x16x32_bf16 v[22:25], v[154:157], v[234:237], v[22:25]
	v_mfma_f32_16x16x32_bf16 v[22:25], v[180:183], v[238:241], v[22:25]
	v_mfma_f32_16x16x32_bf16 v[14:17], v[184:187], v[234:237], v[14:17]
	v_mfma_f32_16x16x32_bf16 v[14:17], v[188:191], v[238:241], v[14:17]
	v_mfma_f32_16x16x32_bf16 v[30:33], v[184:187], v[226:229], v[30:33]
	v_mfma_f32_16x16x32_bf16 v[30:33], v[188:191], v[230:233], v[30:33]
	v_mfma_f32_16x16x32_bf16 v[48:51], v[184:187], v[216:219], v[48:51]
	v_mfma_f32_16x16x32_bf16 v[48:51], v[188:191], v[222:225], v[48:51]
	v_mfma_f32_16x16x32_bf16 v[60:63], v[184:187], v[208:211], v[60:63]
	v_mfma_f32_16x16x32_bf16 v[60:63], v[188:191], v[212:215], v[60:63]
	s_setprio 0
	s_setprio 1
	v_mfma_f32_16x16x32_bf16 v[52:55], v[192:195], v[208:211], v[52:55]
	v_mfma_f32_16x16x32_bf16 v[52:55], v[196:199], v[212:215], v[52:55]
	v_mfma_f32_16x16x32_bf16 v[36:39], v[192:195], v[216:219], v[36:39]
	v_mfma_f32_16x16x32_bf16 v[36:39], v[196:199], v[222:225], v[36:39]
	v_mfma_f32_16x16x32_bf16 v[18:21], v[192:195], v[226:229], v[18:21]
	v_mfma_f32_16x16x32_bf16 v[18:21], v[196:199], v[230:233], v[18:21]
	v_mfma_f32_16x16x32_bf16 v[6:9], v[192:195], v[234:237], v[6:9]
	v_mfma_f32_16x16x32_bf16 v[6:9], v[196:199], v[238:241], v[6:9]
	v_mfma_f32_16x16x32_bf16 v[2:5], v[200:203], v[234:237], v[2:5]
	v_mfma_f32_16x16x32_bf16 v[2:5], v[204:207], v[238:241], v[2:5]
	v_mfma_f32_16x16x32_bf16 v[10:13], v[200:203], v[226:229], v[10:13]
	v_mfma_f32_16x16x32_bf16 v[10:13], v[204:207], v[230:233], v[10:13]
	v_mfma_f32_16x16x32_bf16 v[26:29], v[200:203], v[216:219], v[26:29]
	v_mfma_f32_16x16x32_bf16 v[26:29], v[204:207], v[222:225], v[26:29]
	v_mfma_f32_16x16x32_bf16 v[44:47], v[200:203], v[208:211], v[44:47]
	v_mfma_f32_16x16x32_bf16 v[44:47], v[204:207], v[212:215], v[44:47]
	s_setprio 0
	s_barrier
	s_add_i32 s28, s28, 2
	s_add_u32 s26, s26, 0x100
	s_addc_u32 s27, s27, 0
	s_add_u32 s76, s76, 0x100
	s_addc_u32 s77, s77, 0
	s_cmp_gt_u32 s28, 29
	s_cbranch_scc0 .LBB0_90
	s_and_b64 vcc, exec, s[52:53]
	s_cbranch_vccz .LBB0_93
	s_barrier

.LBB0_844:
	s_add_u32 s27, s62, 0xffe00080
	s_addc_u32 s28, s63, -1
	s_add_i32 s29, 0, 0x10000
	s_cmp_eq_u32 s26, 28
	s_cselect_b32 s67, s20, s28
	s_cselect_b32 s66, s21, s27
	v_add_u32_e32 v152, s29, v154
	s_cselect_b32 s55, s22, s25
	s_cselect_b32 s54, s23, s24
	s_add_i32 s27, 0, 0x14000
	ds_read_b128 v[158:161], v152
	ds_read_b128 v[180:183], v152 offset:1024
	ds_read_b128 v[184:187], v152 offset:2048
	ds_read_b128 v[188:191], v152 offset:3072
	v_add_u32_e32 v152, s27, v154
	ds_read_b128 v[192:195], v152
	ds_read_b128 v[196:199], v152 offset:1024
	ds_read_b128 v[200:203], v152 offset:2048
	ds_read_b128 v[204:207], v152 offset:3072
	v_lshl_add_u64 v[152:153], s[62:63], 0, v[150:151]
	s_add_i32 m0, s12, 0xc000
	ds_read_b128 v[208:211], v156
	ds_read_b128 v[212:215], v156 offset:1024
	ds_read_b128 v[216:219], v156 offset:2048
	ds_read_b128 v[222:225], v156 offset:3072
	ds_read_b128 v[226:229], v156 offset:4096
	ds_read_b128 v[230:233], v156 offset:5120
	ds_read_b128 v[234:237], v156 offset:6144
	ds_read_b128 v[238:241], v156 offset:7168
	global_load_lds_dwordx4 v[152:153], off
	v_lshl_add_u64 v[152:153], s[62:63], 0, v[148:149]
	s_add_i32 m0, s12, 0xe000
	s_nop 0
	global_load_lds_dwordx4 v[152:153], off
	s_waitcnt vmcnt(8)
	s_waitcnt lgkmcnt(0)
	s_barrier
	s_setprio 1
	s_waitcnt lgkmcnt(0)
	v_mfma_f32_16x16x32_bf16 v[128:131], v[158:161], v[208:211], v[128:131]
	v_mfma_f32_16x16x32_bf16 v[128:131], v[180:183], v[212:215], v[128:131]
	v_mfma_f32_16x16x32_bf16 v[120:123], v[158:161], v[216:219], v[120:123]
	v_mfma_f32_16x16x32_bf16 v[120:123], v[180:183], v[222:225], v[120:123]
	v_mfma_f32_16x16x32_bf16 v[104:107], v[158:161], v[226:229], v[104:107]
	v_mfma_f32_16x16x32_bf16 v[104:107], v[180:183], v[230:233], v[104:107]
	v_mfma_f32_16x16x32_bf16 v[88:91], v[158:161], v[234:237], v[88:91]
	v_mfma_f32_16x16x32_bf16 v[88:91], v[180:183], v[238:241], v[88:91]
	v_mfma_f32_16x16x32_bf16 v[80:83], v[184:187], v[234:237], v[80:83]
	v_mfma_f32_16x16x32_bf16 v[80:83], v[188:191], v[238:241], v[80:83]
	v_mfma_f32_16x16x32_bf16 v[96:99], v[184:187], v[226:229], v[96:99]
	v_mfma_f32_16x16x32_bf16 v[96:99], v[188:191], v[230:233], v[96:99]
	v_mfma_f32_16x16x32_bf16 v[112:115], v[184:187], v[216:219], v[112:115]
	v_mfma_f32_16x16x32_bf16 v[112:115], v[188:191], v[222:225], v[112:115]
	v_mfma_f32_16x16x32_bf16 v[124:127], v[184:187], v[208:211], v[124:127]
	v_mfma_f32_16x16x32_bf16 v[124:127], v[188:191], v[212:215], v[124:127]
	s_setprio 0
	s_setprio 1
	v_mfma_f32_16x16x32_bf16 v[116:119], v[192:195], v[208:211], v[116:119]
	v_mfma_f32_16x16x32_bf16 v[116:119], v[196:199], v[212:215], v[116:119]
	v_mfma_f32_16x16x32_bf16 v[100:103], v[192:195], v[216:219], v[100:103]
	v_mfma_f32_16x16x32_bf16 v[100:103], v[196:199], v[222:225], v[100:103]
	v_mfma_f32_16x16x32_bf16 v[84:87], v[192:195], v[226:229], v[84:87]
	v_mfma_f32_16x16x32_bf16 v[84:87], v[196:199], v[230:233], v[84:87]
	v_mfma_f32_16x16x32_bf16 v[72:75], v[192:195], v[234:237], v[72:75]
	v_mfma_f32_16x16x32_bf16 v[72:75], v[196:199], v[238:241], v[72:75]
	v_mfma_f32_16x16x32_bf16 v[68:71], v[200:203], v[234:237], v[68:71]
	v_mfma_f32_16x16x32_bf16 v[68:71], v[204:207], v[238:241], v[68:71]
	v_mfma_f32_16x16x32_bf16 v[76:79], v[200:203], v[226:229], v[76:79]
	v_mfma_f32_16x16x32_bf16 v[76:79], v[204:207], v[230:233], v[76:79]
	v_mfma_f32_16x16x32_bf16 v[92:95], v[200:203], v[216:219], v[92:95]
	v_mfma_f32_16x16x32_bf16 v[92:95], v[204:207], v[222:225], v[92:95]
	v_mfma_f32_16x16x32_bf16 v[108:111], v[200:203], v[208:211], v[108:111]
	v_mfma_f32_16x16x32_bf16 v[108:111], v[204:207], v[212:215], v[108:111]
	s_setprio 0
	s_barrier
	s_add_i32 s28, s29, s11
	v_lshl_add_u64 v[152:153], s[54:55], 0, v[34:35]
	s_mov_b32 m0, s28
	ds_read_b128 v[208:211], v156 offset:16384
	ds_read_b128 v[212:215], v156 offset:17408
	ds_read_b128 v[216:219], v156 offset:18432
	ds_read_b128 v[222:225], v156 offset:19456
	ds_read_b128 v[226:229], v156 offset:20480
	ds_read_b128 v[230:233], v156 offset:21504
	ds_read_b128 v[234:237], v156 offset:22528
	ds_read_b128 v[238:241], v156 offset:23552
	global_load_lds_dwordx4 v[152:153], off
	s_add_i32 m0, s28, 0x2000
	s_add_u32 s28, s54, 0x80000
	v_lshl_add_u64 v[162:163], s[54:55], 0, v[146:147]
	s_addc_u32 s29, s55, 0
	s_add_i32 s27, s27, s11
	global_load_lds_dwordx4 v[162:163], off
	v_lshl_add_u64 v[242:243], s[28:29], 0, v[34:35]
	s_mov_b32 m0, s27
	v_lshl_add_u64 v[244:245], s[66:67], 0, v[144:145]
	global_load_lds_dwordx4 v[242:243], off
	v_lshl_add_u64 v[242:243], s[28:29], 0, v[146:147]
	s_add_i32 m0, s27, 0x2000
	s_nop 0
	global_load_lds_dwordx4 v[242:243], off
	v_lshl_add_u64 v[242:243], s[66:67], 0, v[142:143]
	s_mov_b32 m0, s12
	s_nop 0
	global_load_lds_dwordx4 v[242:243], off
	s_mov_b32 m0, s13
	s_nop 0
	global_load_lds_dwordx4 v[244:245], off
	s_waitcnt vmcnt(8)
	s_waitcnt lgkmcnt(0)
	s_barrier
	s_setprio 1
	s_waitcnt lgkmcnt(0)
	v_mfma_f32_16x16x32_bf16 v[64:67], v[158:161], v[208:211], v[64:67]
	v_mfma_f32_16x16x32_bf16 v[64:67], v[180:183], v[212:215], v[64:67]
	v_mfma_f32_16x16x32_bf16 v[56:59], v[158:161], v[216:219], v[56:59]
	v_mfma_f32_16x16x32_bf16 v[56:59], v[180:183], v[222:225], v[56:59]
	v_mfma_f32_16x16x32_bf16 v[40:43], v[158:161], v[226:229], v[40:43]
	v_mfma_f32_16x16x32_bf16 v[40:43], v[180:183], v[230:233], v[40:43]
	v_mfma_f32_16x16x32_bf16 v[22:25], v[158:161], v[234:237], v[22:25]
	v_mfma_f32_16x16x32_bf16 v[22:25], v[180:183], v[238:241], v[22:25]
	v_mfma_f32_16x16x32_bf16 v[14:17], v[184:187], v[234:237], v[14:17]
	v_mfma_f32_16x16x32_bf16 v[14:17], v[188:191], v[238:241], v[14:17]
	v_mfma_f32_16x16x32_bf16 v[30:33], v[184:187], v[226:229], v[30:33]
	v_mfma_f32_16x16x32_bf16 v[30:33], v[188:191], v[230:233], v[30:33]
	v_mfma_f32_16x16x32_bf16 v[48:51], v[184:187], v[216:219], v[48:51]
	v_mfma_f32_16x16x32_bf16 v[48:51], v[188:191], v[222:225], v[48:51]
	v_mfma_f32_16x16x32_bf16 v[60:63], v[184:187], v[208:211], v[60:63]
	v_mfma_f32_16x16x32_bf16 v[60:63], v[188:191], v[212:215], v[60:63]
	s_setprio 0
	s_setprio 1
	v_mfma_f32_16x16x32_bf16 v[52:55], v[192:195], v[208:211], v[52:55]
	v_mfma_f32_16x16x32_bf16 v[52:55], v[196:199], v[212:215], v[52:55]
	v_mfma_f32_16x16x32_bf16 v[36:39], v[192:195], v[216:219], v[36:39]
	v_mfma_f32_16x16x32_bf16 v[36:39], v[196:199], v[222:225], v[36:39]
	v_mfma_f32_16x16x32_bf16 v[18:21], v[192:195], v[226:229], v[18:21]
	v_mfma_f32_16x16x32_bf16 v[18:21], v[196:199], v[230:233], v[18:21]
	v_mfma_f32_16x16x32_bf16 v[6:9], v[192:195], v[234:237], v[6:9]
	v_mfma_f32_16x16x32_bf16 v[6:9], v[196:199], v[238:241], v[6:9]
	v_mfma_f32_16x16x32_bf16 v[2:5], v[200:203], v[234:237], v[2:5]
	v_mfma_f32_16x16x32_bf16 v[2:5], v[204:207], v[238:241], v[2:5]
	v_mfma_f32_16x16x32_bf16 v[10:13], v[200:203], v[226:229], v[10:13]
	v_mfma_f32_16x16x32_bf16 v[10:13], v[204:207], v[230:233], v[10:13]
	v_mfma_f32_16x16x32_bf16 v[26:29], v[200:203], v[216:219], v[26:29]
	v_mfma_f32_16x16x32_bf16 v[26:29], v[204:207], v[222:225], v[26:29]
	v_mfma_f32_16x16x32_bf16 v[44:47], v[200:203], v[208:211], v[44:47]
	v_mfma_f32_16x16x32_bf16 v[44:47], v[204:207], v[212:215], v[44:47]
	s_setprio 0
	s_barrier
	s_add_i32 s27, 0, 0x18000
	v_add_u32_e32 v157, s27, v154
	s_add_i32 s30, 0, 0x1c000
	ds_read_b128 v[158:161], v157
	ds_read_b128 v[180:183], v157 offset:1024
	ds_read_b128 v[184:187], v157 offset:2048
	ds_read_b128 v[188:191], v157 offset:3072
	v_add_u32_e32 v157, s30, v154
	ds_read_b128 v[192:195], v157
	ds_read_b128 v[196:199], v157 offset:1024
	ds_read_b128 v[200:203], v157 offset:2048
	ds_read_b128 v[204:207], v157 offset:3072
	s_add_u32 s28, s66, 0x200000
	s_addc_u32 s29, s67, 0
	s_mov_b32 m0, s14
	v_lshl_add_u64 v[246:247], s[28:29], 0, v[142:143]
	ds_read_b128 v[208:211], v156 offset:32768
	ds_read_b128 v[212:215], v156 offset:33792
	ds_read_b128 v[216:219], v156 offset:34816
	ds_read_b128 v[222:225], v156 offset:35840
	ds_read_b128 v[226:229], v156 offset:36864
	ds_read_b128 v[230:233], v156 offset:37888
	ds_read_b128 v[234:237], v156 offset:38912
	ds_read_b128 v[238:241], v156 offset:39936
	global_load_lds_dwordx4 v[246:247], off
	v_lshl_add_u64 v[246:247], s[28:29], 0, v[144:145]
	s_mov_b32 m0, s15
	s_nop 0
	global_load_lds_dwordx4 v[246:247], off
	s_waitcnt vmcnt(8)
	s_waitcnt lgkmcnt(0)
	s_barrier
	s_setprio 1
	s_waitcnt lgkmcnt(0)
	v_mfma_f32_16x16x32_bf16 v[128:131], v[158:161], v[208:211], v[128:131]
	v_mfma_f32_16x16x32_bf16 v[128:131], v[180:183], v[212:215], v[128:131]
	v_mfma_f32_16x16x32_bf16 v[120:123], v[158:161], v[216:219], v[120:123]
	v_mfma_f32_16x16x32_bf16 v[120:123], v[180:183], v[222:225], v[120:123]
	v_mfma_f32_16x16x32_bf16 v[104:107], v[158:161], v[226:229], v[104:107]
	v_mfma_f32_16x16x32_bf16 v[104:107], v[180:183], v[230:233], v[104:107]
	v_mfma_f32_16x16x32_bf16 v[88:91], v[158:161], v[234:237], v[88:91]
	v_mfma_f32_16x16x32_bf16 v[88:91], v[180:183], v[238:241], v[88:91]
	v_mfma_f32_16x16x32_bf16 v[80:83], v[184:187], v[234:237], v[80:83]
	v_mfma_f32_16x16x32_bf16 v[80:83], v[188:191], v[238:241], v[80:83]
	v_mfma_f32_16x16x32_bf16 v[96:99], v[184:187], v[226:229], v[96:99]
	v_mfma_f32_16x16x32_bf16 v[96:99], v[188:191], v[230:233], v[96:99]
	v_mfma_f32_16x16x32_bf16 v[112:115], v[184:187], v[216:219], v[112:115]
	v_mfma_f32_16x16x32_bf16 v[112:115], v[188:191], v[222:225], v[112:115]
	v_mfma_f32_16x16x32_bf16 v[124:127], v[184:187], v[208:211], v[124:127]
	v_mfma_f32_16x16x32_bf16 v[124:127], v[188:191], v[212:215], v[124:127]
	s_setprio 0
	s_setprio 1
	v_mfma_f32_16x16x32_bf16 v[116:119], v[192:195], v[208:211], v[116:119]
	v_mfma_f32_16x16x32_bf16 v[116:119], v[196:199], v[212:215], v[116:119]
	v_mfma_f32_16x16x32_bf16 v[100:103], v[192:195], v[216:219], v[100:103]
	v_mfma_f32_16x16x32_bf16 v[100:103], v[196:199], v[222:225], v[100:103]
	v_mfma_f32_16x16x32_bf16 v[84:87], v[192:195], v[226:229], v[84:87]
	v_mfma_f32_16x16x32_bf16 v[84:87], v[196:199], v[230:233], v[84:87]
	v_mfma_f32_16x16x32_bf16 v[72:75], v[192:195], v[234:237], v[72:75]
	v_mfma_f32_16x16x32_bf16 v[72:75], v[196:199], v[238:241], v[72:75]
	v_mfma_f32_16x16x32_bf16 v[68:71], v[200:203], v[234:237], v[68:71]
	v_mfma_f32_16x16x32_bf16 v[68:71], v[204:207], v[238:241], v[68:71]
	v_mfma_f32_16x16x32_bf16 v[76:79], v[200:203], v[226:229], v[76:79]
	v_mfma_f32_16x16x32_bf16 v[76:79], v[204:207], v[230:233], v[76:79]
	v_mfma_f32_16x16x32_bf16 v[92:95], v[200:203], v[216:219], v[92:95]
	v_mfma_f32_16x16x32_bf16 v[92:95], v[204:207], v[222:225], v[92:95]
	v_mfma_f32_16x16x32_bf16 v[108:111], v[200:203], v[208:211], v[108:111]
	v_mfma_f32_16x16x32_bf16 v[108:111], v[204:207], v[212:215], v[108:111]
	s_setprio 0
	s_barrier
	s_add_i32 s27, s27, s11
	v_lshl_add_u64 v[152:153], v[152:153], 0, s[78:79]
	s_mov_b32 m0, s27
	ds_read_b128 v[208:211], v156 offset:49152
	ds_read_b128 v[212:215], v156 offset:50176
	ds_read_b128 v[216:219], v156 offset:51200
	ds_read_b128 v[222:225], v156 offset:52224
	ds_read_b128 v[226:229], v156 offset:53248
	ds_read_b128 v[230:233], v156 offset:54272
	ds_read_b128 v[234:237], v156 offset:55296
	ds_read_b128 v[238:241], v156 offset:56320
	global_load_lds_dwordx4 v[152:153], off
	s_add_i32 m0, s27, 0x2000
	s_add_u32 s28, s54, 0x80080
	v_lshl_add_u64 v[152:153], v[162:163], 0, s[78:79]
	s_addc_u32 s29, s55, 0
	s_add_i32 s27, s30, s11
	global_load_lds_dwordx4 v[152:153], off
	v_lshl_add_u64 v[152:153], s[28:29], 0, v[34:35]
	s_mov_b32 m0, s27
	s_nop 0
	global_load_lds_dwordx4 v[152:153], off
	v_lshl_add_u64 v[152:153], s[28:29], 0, v[146:147]
	s_add_i32 m0, s27, 0x2000
	s_nop 0
	global_load_lds_dwordx4 v[152:153], off
	v_lshl_add_u64 v[152:153], v[242:243], 0, s[78:79]
	s_mov_b32 m0, s16
	s_nop 0
	global_load_lds_dwordx4 v[152:153], off
	v_lshl_add_u64 v[152:153], v[244:245], 0, s[78:79]
	s_mov_b32 m0, s17
	s_nop 0
	global_load_lds_dwordx4 v[152:153], off
	s_waitcnt vmcnt(8)
	s_waitcnt lgkmcnt(0)
	s_barrier
	s_setprio 1
	s_waitcnt lgkmcnt(0)
	v_mfma_f32_16x16x32_bf16 v[64:67], v[158:161], v[208:211], v[64:67]
	v_mfma_f32_16x16x32_bf16 v[64:67], v[180:183], v[212:215], v[64:67]
	v_mfma_f32_16x16x32_bf16 v[56:59], v[158:161], v[216:219], v[56:59]
	v_mfma_f32_16x16x32_bf16 v[56:59], v[180:183], v[222:225], v[56:59]
	v_mfma_f32_16x16x32_bf16 v[40:43], v[158:161], v[226:229], v[40:43]
	v_mfma_f32_16x16x32_bf16 v[40:43], v[180:183], v[230:233], v[40:43]
	v_mfma_f32_16x16x32_bf16 v[22:25], v[158:161], v[234:237], v[22:25]
	v_mfma_f32_16x16x32_bf16 v[22:25], v[180:183], v[238:241], v[22:25]
	v_mfma_f32_16x16x32_bf16 v[14:17], v[184:187], v[234:237], v[14:17]
	v_mfma_f32_16x16x32_bf16 v[14:17], v[188:191], v[238:241], v[14:17]
	v_mfma_f32_16x16x32_bf16 v[30:33], v[184:187], v[226:229], v[30:33]
	v_mfma_f32_16x16x32_bf16 v[30:33], v[188:191], v[230:233], v[30:33]
	v_mfma_f32_16x16x32_bf16 v[48:51], v[184:187], v[216:219], v[48:51]
	v_mfma_f32_16x16x32_bf16 v[48:51], v[188:191], v[222:225], v[48:51]
	v_mfma_f32_16x16x32_bf16 v[60:63], v[184:187], v[208:211], v[60:63]
	v_mfma_f32_16x16x32_bf16 v[60:63], v[188:191], v[212:215], v[60:63]
	s_setprio 0
	s_setprio 1
	v_mfma_f32_16x16x32_bf16 v[52:55], v[192:195], v[208:211], v[52:55]
	v_mfma_f32_16x16x32_bf16 v[52:55], v[196:199], v[212:215], v[52:55]
	v_mfma_f32_16x16x32_bf16 v[36:39], v[192:195], v[216:219], v[36:39]
	v_mfma_f32_16x16x32_bf16 v[36:39], v[196:199], v[222:225], v[36:39]
	v_mfma_f32_16x16x32_bf16 v[18:21], v[192:195], v[226:229], v[18:21]
	v_mfma_f32_16x16x32_bf16 v[18:21], v[196:199], v[230:233], v[18:21]
	v_mfma_f32_16x16x32_bf16 v[6:9], v[192:195], v[234:237], v[6:9]
	v_mfma_f32_16x16x32_bf16 v[6:9], v[196:199], v[238:241], v[6:9]
	v_mfma_f32_16x16x32_bf16 v[2:5], v[200:203], v[234:237], v[2:5]
	v_mfma_f32_16x16x32_bf16 v[2:5], v[204:207], v[238:241], v[2:5]
	v_mfma_f32_16x16x32_bf16 v[10:13], v[200:203], v[226:229], v[10:13]
	v_mfma_f32_16x16x32_bf16 v[10:13], v[204:207], v[230:233], v[10:13]
	v_mfma_f32_16x16x32_bf16 v[26:29], v[200:203], v[216:219], v[26:29]
	v_mfma_f32_16x16x32_bf16 v[26:29], v[204:207], v[222:225], v[26:29]
	v_mfma_f32_16x16x32_bf16 v[44:47], v[200:203], v[208:211], v[44:47]
	v_mfma_f32_16x16x32_bf16 v[44:47], v[204:207], v[212:215], v[44:47]
	s_setprio 0
	s_barrier
	s_add_i32 s26, s26, 2
	s_add_u32 s24, s24, 0x100
	s_addc_u32 s25, s25, 0
	s_add_u32 s62, s62, 0x100
	s_addc_u32 s63, s63, 0
	s_cmp_gt_u32 s26, 29
	s_cbranch_scc0 .LBB0_844
	s_and_b64 vcc, exec, s[44:45]
	s_cbranch_vccz .LBB0_847
	s_barrier

.LBB0_985:
	s_add_u32 s27, s62, 0xfff80080
	s_addc_u32 s28, s63, -1
	s_add_i32 s29, 0, 0x10000
	s_cmp_eq_u32 s26, 28
	s_cselect_b32 s67, s20, s28
	s_cselect_b32 s66, s21, s27
	v_add_u32_e32 v152, s29, v154
	s_cselect_b32 s55, s22, s25
	s_cselect_b32 s54, s23, s24
	s_add_i32 s27, 0, 0x14000
	ds_read_b128 v[158:161], v152
	ds_read_b128 v[180:183], v152 offset:1024
	ds_read_b128 v[184:187], v152 offset:2048
	ds_read_b128 v[188:191], v152 offset:3072
	v_add_u32_e32 v152, s27, v154
	ds_read_b128 v[192:195], v152
	ds_read_b128 v[196:199], v152 offset:1024
	ds_read_b128 v[200:203], v152 offset:2048
	ds_read_b128 v[204:207], v152 offset:3072
	v_lshl_add_u64 v[152:153], s[62:63], 0, v[150:151]
	s_add_i32 m0, s12, 0xc000
	ds_read_b128 v[208:211], v156
	ds_read_b128 v[212:215], v156 offset:1024
	ds_read_b128 v[216:219], v156 offset:2048
	ds_read_b128 v[222:225], v156 offset:3072
	ds_read_b128 v[226:229], v156 offset:4096
	ds_read_b128 v[230:233], v156 offset:5120
	ds_read_b128 v[234:237], v156 offset:6144
	ds_read_b128 v[238:241], v156 offset:7168
	global_load_lds_dwordx4 v[152:153], off
	v_lshl_add_u64 v[152:153], s[62:63], 0, v[148:149]
	s_add_i32 m0, s12, 0xe000
	s_nop 0
	global_load_lds_dwordx4 v[152:153], off
	s_waitcnt vmcnt(8)
	s_waitcnt lgkmcnt(0)
	s_barrier
	s_setprio 1
	s_waitcnt lgkmcnt(0)
	v_mfma_f32_16x16x32_bf16 v[128:131], v[158:161], v[208:211], v[128:131]
	v_mfma_f32_16x16x32_bf16 v[128:131], v[180:183], v[212:215], v[128:131]
	v_mfma_f32_16x16x32_bf16 v[112:115], v[158:161], v[216:219], v[112:115]
	v_mfma_f32_16x16x32_bf16 v[112:115], v[180:183], v[222:225], v[112:115]
	v_mfma_f32_16x16x32_bf16 v[96:99], v[158:161], v[226:229], v[96:99]
	v_mfma_f32_16x16x32_bf16 v[96:99], v[180:183], v[230:233], v[96:99]
	v_mfma_f32_16x16x32_bf16 v[80:83], v[158:161], v[234:237], v[80:83]
	v_mfma_f32_16x16x32_bf16 v[80:83], v[180:183], v[238:241], v[80:83]
	v_mfma_f32_16x16x32_bf16 v[76:79], v[184:187], v[234:237], v[76:79]
	v_mfma_f32_16x16x32_bf16 v[76:79], v[188:191], v[238:241], v[76:79]
	v_mfma_f32_16x16x32_bf16 v[92:95], v[184:187], v[226:229], v[92:95]
	v_mfma_f32_16x16x32_bf16 v[92:95], v[188:191], v[230:233], v[92:95]
	v_mfma_f32_16x16x32_bf16 v[108:111], v[184:187], v[216:219], v[108:111]
	v_mfma_f32_16x16x32_bf16 v[108:111], v[188:191], v[222:225], v[108:111]
	v_mfma_f32_16x16x32_bf16 v[124:127], v[184:187], v[208:211], v[124:127]
	v_mfma_f32_16x16x32_bf16 v[124:127], v[188:191], v[212:215], v[124:127]
	s_setprio 0
	s_setprio 1
	v_mfma_f32_16x16x32_bf16 v[120:123], v[192:195], v[208:211], v[120:123]
	v_mfma_f32_16x16x32_bf16 v[120:123], v[196:199], v[212:215], v[120:123]
	v_mfma_f32_16x16x32_bf16 v[104:107], v[192:195], v[216:219], v[104:107]
	v_mfma_f32_16x16x32_bf16 v[104:107], v[196:199], v[222:225], v[104:107]
	v_mfma_f32_16x16x32_bf16 v[88:91], v[192:195], v[226:229], v[88:91]
	v_mfma_f32_16x16x32_bf16 v[88:91], v[196:199], v[230:233], v[88:91]
	v_mfma_f32_16x16x32_bf16 v[72:75], v[192:195], v[234:237], v[72:75]
	v_mfma_f32_16x16x32_bf16 v[72:75], v[196:199], v[238:241], v[72:75]
	v_mfma_f32_16x16x32_bf16 v[68:71], v[200:203], v[234:237], v[68:71]
	v_mfma_f32_16x16x32_bf16 v[68:71], v[204:207], v[238:241], v[68:71]
	v_mfma_f32_16x16x32_bf16 v[84:87], v[200:203], v[226:229], v[84:87]
	v_mfma_f32_16x16x32_bf16 v[84:87], v[204:207], v[230:233], v[84:87]
	v_mfma_f32_16x16x32_bf16 v[100:103], v[200:203], v[216:219], v[100:103]
	v_mfma_f32_16x16x32_bf16 v[100:103], v[204:207], v[222:225], v[100:103]
	v_mfma_f32_16x16x32_bf16 v[116:119], v[200:203], v[208:211], v[116:119]
	v_mfma_f32_16x16x32_bf16 v[116:119], v[204:207], v[212:215], v[116:119]
	s_setprio 0
	s_barrier
	s_add_i32 s28, s29, s11
	v_lshl_add_u64 v[152:153], s[54:55], 0, v[34:35]
	s_mov_b32 m0, s28
	ds_read_b128 v[208:211], v156 offset:16384
	ds_read_b128 v[212:215], v156 offset:17408
	ds_read_b128 v[216:219], v156 offset:18432
	ds_read_b128 v[222:225], v156 offset:19456
	ds_read_b128 v[226:229], v156 offset:20480
	ds_read_b128 v[230:233], v156 offset:21504
	ds_read_b128 v[234:237], v156 offset:22528
	ds_read_b128 v[238:241], v156 offset:23552
	global_load_lds_dwordx4 v[152:153], off
	s_add_i32 m0, s28, 0x2000
	s_add_u32 s28, s54, 0x80000
	v_lshl_add_u64 v[162:163], s[54:55], 0, v[146:147]
	s_addc_u32 s29, s55, 0
	s_add_i32 s27, s27, s11
	global_load_lds_dwordx4 v[162:163], off
	v_lshl_add_u64 v[242:243], s[28:29], 0, v[34:35]
	s_mov_b32 m0, s27
	v_lshl_add_u64 v[244:245], s[66:67], 0, v[144:145]
	global_load_lds_dwordx4 v[242:243], off
	v_lshl_add_u64 v[242:243], s[28:29], 0, v[146:147]
	s_add_i32 m0, s27, 0x2000
	s_nop 0
	global_load_lds_dwordx4 v[242:243], off
	v_lshl_add_u64 v[242:243], s[66:67], 0, v[142:143]
	s_mov_b32 m0, s12
	s_nop 0
	global_load_lds_dwordx4 v[242:243], off
	s_mov_b32 m0, s13
	s_nop 0
	global_load_lds_dwordx4 v[244:245], off
	s_waitcnt vmcnt(8)
	s_waitcnt lgkmcnt(0)
	s_barrier
	s_setprio 1
	s_waitcnt lgkmcnt(0)
	v_mfma_f32_16x16x32_bf16 v[64:67], v[158:161], v[208:211], v[64:67]
	v_mfma_f32_16x16x32_bf16 v[64:67], v[180:183], v[212:215], v[64:67]
	v_mfma_f32_16x16x32_bf16 v[48:51], v[158:161], v[216:219], v[48:51]
	v_mfma_f32_16x16x32_bf16 v[48:51], v[180:183], v[222:225], v[48:51]
	v_mfma_f32_16x16x32_bf16 v[30:33], v[158:161], v[226:229], v[30:33]
	v_mfma_f32_16x16x32_bf16 v[30:33], v[180:183], v[230:233], v[30:33]
	v_mfma_f32_16x16x32_bf16 v[14:17], v[158:161], v[234:237], v[14:17]
	v_mfma_f32_16x16x32_bf16 v[14:17], v[180:183], v[238:241], v[14:17]
	v_mfma_f32_16x16x32_bf16 v[10:13], v[184:187], v[234:237], v[10:13]
	v_mfma_f32_16x16x32_bf16 v[10:13], v[188:191], v[238:241], v[10:13]
	v_mfma_f32_16x16x32_bf16 v[26:29], v[184:187], v[226:229], v[26:29]
	v_mfma_f32_16x16x32_bf16 v[26:29], v[188:191], v[230:233], v[26:29]
	v_mfma_f32_16x16x32_bf16 v[44:47], v[184:187], v[216:219], v[44:47]
	v_mfma_f32_16x16x32_bf16 v[44:47], v[188:191], v[222:225], v[44:47]
	v_mfma_f32_16x16x32_bf16 v[60:63], v[184:187], v[208:211], v[60:63]
	v_mfma_f32_16x16x32_bf16 v[60:63], v[188:191], v[212:215], v[60:63]
	s_setprio 0
	s_setprio 1
	v_mfma_f32_16x16x32_bf16 v[56:59], v[192:195], v[208:211], v[56:59]
	v_mfma_f32_16x16x32_bf16 v[56:59], v[196:199], v[212:215], v[56:59]
	v_mfma_f32_16x16x32_bf16 v[40:43], v[192:195], v[216:219], v[40:43]
	v_mfma_f32_16x16x32_bf16 v[40:43], v[196:199], v[222:225], v[40:43]
	v_mfma_f32_16x16x32_bf16 v[22:25], v[192:195], v[226:229], v[22:25]
	v_mfma_f32_16x16x32_bf16 v[22:25], v[196:199], v[230:233], v[22:25]
	v_mfma_f32_16x16x32_bf16 v[6:9], v[192:195], v[234:237], v[6:9]
	v_mfma_f32_16x16x32_bf16 v[6:9], v[196:199], v[238:241], v[6:9]
	v_mfma_f32_16x16x32_bf16 v[2:5], v[200:203], v[234:237], v[2:5]
	v_mfma_f32_16x16x32_bf16 v[2:5], v[204:207], v[238:241], v[2:5]
	v_mfma_f32_16x16x32_bf16 v[18:21], v[200:203], v[226:229], v[18:21]
	v_mfma_f32_16x16x32_bf16 v[18:21], v[204:207], v[230:233], v[18:21]
	v_mfma_f32_16x16x32_bf16 v[36:39], v[200:203], v[216:219], v[36:39]
	v_mfma_f32_16x16x32_bf16 v[36:39], v[204:207], v[222:225], v[36:39]
	v_mfma_f32_16x16x32_bf16 v[52:55], v[200:203], v[208:211], v[52:55]
	v_mfma_f32_16x16x32_bf16 v[52:55], v[204:207], v[212:215], v[52:55]
	s_setprio 0
	s_barrier
	s_add_i32 s27, 0, 0x18000
	v_add_u32_e32 v157, s27, v154
	s_add_i32 s30, 0, 0x1c000
	ds_read_b128 v[158:161], v157
	ds_read_b128 v[180:183], v157 offset:1024
	ds_read_b128 v[184:187], v157 offset:2048
	ds_read_b128 v[188:191], v157 offset:3072
	v_add_u32_e32 v157, s30, v154
	ds_read_b128 v[192:195], v157
	ds_read_b128 v[196:199], v157 offset:1024
	ds_read_b128 v[200:203], v157 offset:2048
	ds_read_b128 v[204:207], v157 offset:3072
	s_add_u32 s28, s66, 0x80000
	s_addc_u32 s29, s67, 0
	s_mov_b32 m0, s14
	v_lshl_add_u64 v[246:247], s[28:29], 0, v[142:143]
	ds_read_b128 v[208:211], v156 offset:32768
	ds_read_b128 v[212:215], v156 offset:33792
	ds_read_b128 v[216:219], v156 offset:34816
	ds_read_b128 v[222:225], v156 offset:35840
	ds_read_b128 v[226:229], v156 offset:36864
	ds_read_b128 v[230:233], v156 offset:37888
	ds_read_b128 v[234:237], v156 offset:38912
	ds_read_b128 v[238:241], v156 offset:39936
	global_load_lds_dwordx4 v[246:247], off
	v_lshl_add_u64 v[246:247], s[28:29], 0, v[144:145]
	s_mov_b32 m0, s15
	s_nop 0
	global_load_lds_dwordx4 v[246:247], off
	s_waitcnt vmcnt(8)
	s_waitcnt lgkmcnt(0)
	s_barrier
	s_setprio 1
	s_waitcnt lgkmcnt(0)
	v_mfma_f32_16x16x32_bf16 v[128:131], v[158:161], v[208:211], v[128:131]
	v_mfma_f32_16x16x32_bf16 v[128:131], v[180:183], v[212:215], v[128:131]
	v_mfma_f32_16x16x32_bf16 v[112:115], v[158:161], v[216:219], v[112:115]
	v_mfma_f32_16x16x32_bf16 v[112:115], v[180:183], v[222:225], v[112:115]
	v_mfma_f32_16x16x32_bf16 v[96:99], v[158:161], v[226:229], v[96:99]
	v_mfma_f32_16x16x32_bf16 v[96:99], v[180:183], v[230:233], v[96:99]
	v_mfma_f32_16x16x32_bf16 v[80:83], v[158:161], v[234:237], v[80:83]
	v_mfma_f32_16x16x32_bf16 v[80:83], v[180:183], v[238:241], v[80:83]
	v_mfma_f32_16x16x32_bf16 v[76:79], v[184:187], v[234:237], v[76:79]
	v_mfma_f32_16x16x32_bf16 v[76:79], v[188:191], v[238:241], v[76:79]
	v_mfma_f32_16x16x32_bf16 v[92:95], v[184:187], v[226:229], v[92:95]
	v_mfma_f32_16x16x32_bf16 v[92:95], v[188:191], v[230:233], v[92:95]
	v_mfma_f32_16x16x32_bf16 v[108:111], v[184:187], v[216:219], v[108:111]
	v_mfma_f32_16x16x32_bf16 v[108:111], v[188:191], v[222:225], v[108:111]
	v_mfma_f32_16x16x32_bf16 v[124:127], v[184:187], v[208:211], v[124:127]
	v_mfma_f32_16x16x32_bf16 v[124:127], v[188:191], v[212:215], v[124:127]
	s_setprio 0
	s_setprio 1
	v_mfma_f32_16x16x32_bf16 v[120:123], v[192:195], v[208:211], v[120:123]
	v_mfma_f32_16x16x32_bf16 v[120:123], v[196:199], v[212:215], v[120:123]
	v_mfma_f32_16x16x32_bf16 v[104:107], v[192:195], v[216:219], v[104:107]
	v_mfma_f32_16x16x32_bf16 v[104:107], v[196:199], v[222:225], v[104:107]
	v_mfma_f32_16x16x32_bf16 v[88:91], v[192:195], v[226:229], v[88:91]
	v_mfma_f32_16x16x32_bf16 v[88:91], v[196:199], v[230:233], v[88:91]
	v_mfma_f32_16x16x32_bf16 v[72:75], v[192:195], v[234:237], v[72:75]
	v_mfma_f32_16x16x32_bf16 v[72:75], v[196:199], v[238:241], v[72:75]
	v_mfma_f32_16x16x32_bf16 v[68:71], v[200:203], v[234:237], v[68:71]
	v_mfma_f32_16x16x32_bf16 v[68:71], v[204:207], v[238:241], v[68:71]
	v_mfma_f32_16x16x32_bf16 v[84:87], v[200:203], v[226:229], v[84:87]
	v_mfma_f32_16x16x32_bf16 v[84:87], v[204:207], v[230:233], v[84:87]
	v_mfma_f32_16x16x32_bf16 v[100:103], v[200:203], v[216:219], v[100:103]
	v_mfma_f32_16x16x32_bf16 v[100:103], v[204:207], v[222:225], v[100:103]
	v_mfma_f32_16x16x32_bf16 v[116:119], v[200:203], v[208:211], v[116:119]
	v_mfma_f32_16x16x32_bf16 v[116:119], v[204:207], v[212:215], v[116:119]
	s_setprio 0
	s_barrier
	s_add_i32 s27, s27, s11
	v_lshl_add_u64 v[152:153], v[152:153], 0, s[78:79]
	s_mov_b32 m0, s27
	ds_read_b128 v[208:211], v156 offset:49152
	ds_read_b128 v[212:215], v156 offset:50176
	ds_read_b128 v[216:219], v156 offset:51200
	ds_read_b128 v[222:225], v156 offset:52224
	ds_read_b128 v[226:229], v156 offset:53248
	ds_read_b128 v[230:233], v156 offset:54272
	ds_read_b128 v[234:237], v156 offset:55296
	ds_read_b128 v[238:241], v156 offset:56320
	global_load_lds_dwordx4 v[152:153], off
	s_add_i32 m0, s27, 0x2000
	s_add_u32 s28, s54, 0x80080
	v_lshl_add_u64 v[152:153], v[162:163], 0, s[78:79]
	s_addc_u32 s29, s55, 0
	s_add_i32 s27, s30, s11
	global_load_lds_dwordx4 v[152:153], off
	v_lshl_add_u64 v[152:153], s[28:29], 0, v[34:35]
	s_mov_b32 m0, s27
	s_nop 0
	global_load_lds_dwordx4 v[152:153], off
	v_lshl_add_u64 v[152:153], s[28:29], 0, v[146:147]
	s_add_i32 m0, s27, 0x2000
	s_nop 0
	global_load_lds_dwordx4 v[152:153], off
	v_lshl_add_u64 v[152:153], v[242:243], 0, s[78:79]
	s_mov_b32 m0, s16
	s_nop 0
	global_load_lds_dwordx4 v[152:153], off
	v_lshl_add_u64 v[152:153], v[244:245], 0, s[78:79]
	s_mov_b32 m0, s17
	s_nop 0
	global_load_lds_dwordx4 v[152:153], off
	s_waitcnt vmcnt(8)
	s_waitcnt lgkmcnt(0)
	s_barrier
	s_setprio 1
	s_waitcnt lgkmcnt(0)
	v_mfma_f32_16x16x32_bf16 v[64:67], v[158:161], v[208:211], v[64:67]
	v_mfma_f32_16x16x32_bf16 v[64:67], v[180:183], v[212:215], v[64:67]
	v_mfma_f32_16x16x32_bf16 v[48:51], v[158:161], v[216:219], v[48:51]
	v_mfma_f32_16x16x32_bf16 v[48:51], v[180:183], v[222:225], v[48:51]
	v_mfma_f32_16x16x32_bf16 v[30:33], v[158:161], v[226:229], v[30:33]
	v_mfma_f32_16x16x32_bf16 v[30:33], v[180:183], v[230:233], v[30:33]
	v_mfma_f32_16x16x32_bf16 v[14:17], v[158:161], v[234:237], v[14:17]
	v_mfma_f32_16x16x32_bf16 v[14:17], v[180:183], v[238:241], v[14:17]
	v_mfma_f32_16x16x32_bf16 v[10:13], v[184:187], v[234:237], v[10:13]
	v_mfma_f32_16x16x32_bf16 v[10:13], v[188:191], v[238:241], v[10:13]
	v_mfma_f32_16x16x32_bf16 v[26:29], v[184:187], v[226:229], v[26:29]
	v_mfma_f32_16x16x32_bf16 v[26:29], v[188:191], v[230:233], v[26:29]
	v_mfma_f32_16x16x32_bf16 v[44:47], v[184:187], v[216:219], v[44:47]
	v_mfma_f32_16x16x32_bf16 v[44:47], v[188:191], v[222:225], v[44:47]
	v_mfma_f32_16x16x32_bf16 v[60:63], v[184:187], v[208:211], v[60:63]
	v_mfma_f32_16x16x32_bf16 v[60:63], v[188:191], v[212:215], v[60:63]
	s_setprio 0
	s_setprio 1
	v_mfma_f32_16x16x32_bf16 v[56:59], v[192:195], v[208:211], v[56:59]
	v_mfma_f32_16x16x32_bf16 v[56:59], v[196:199], v[212:215], v[56:59]
	v_mfma_f32_16x16x32_bf16 v[40:43], v[192:195], v[216:219], v[40:43]
	v_mfma_f32_16x16x32_bf16 v[40:43], v[196:199], v[222:225], v[40:43]
	v_mfma_f32_16x16x32_bf16 v[22:25], v[192:195], v[226:229], v[22:25]
	v_mfma_f32_16x16x32_bf16 v[22:25], v[196:199], v[230:233], v[22:25]
	v_mfma_f32_16x16x32_bf16 v[6:9], v[192:195], v[234:237], v[6:9]
	v_mfma_f32_16x16x32_bf16 v[6:9], v[196:199], v[238:241], v[6:9]
	v_mfma_f32_16x16x32_bf16 v[2:5], v[200:203], v[234:237], v[2:5]
	v_mfma_f32_16x16x32_bf16 v[2:5], v[204:207], v[238:241], v[2:5]
	v_mfma_f32_16x16x32_bf16 v[18:21], v[200:203], v[226:229], v[18:21]
	v_mfma_f32_16x16x32_bf16 v[18:21], v[204:207], v[230:233], v[18:21]
	v_mfma_f32_16x16x32_bf16 v[36:39], v[200:203], v[216:219], v[36:39]
	v_mfma_f32_16x16x32_bf16 v[36:39], v[204:207], v[222:225], v[36:39]
	v_mfma_f32_16x16x32_bf16 v[52:55], v[200:203], v[208:211], v[52:55]
	v_mfma_f32_16x16x32_bf16 v[52:55], v[204:207], v[212:215], v[52:55]
	s_setprio 0
	s_barrier
	s_add_i32 s26, s26, 2
	s_add_u32 s24, s24, 0x100
	s_addc_u32 s25, s25, 0
	s_add_u32 s62, s62, 0x100
	s_addc_u32 s63, s63, 0
	s_cmp_gt_u32 s26, 29
	s_cbranch_scc0 .LBB0_985
	s_and_b64 vcc, exec, s[36:37]
	s_cbranch_vccz .LBB0_988
	s_barrier

.LBB0_1064:
	s_add_u32 s27, s62, 0xffe00080
	s_addc_u32 s28, s63, -1
	s_add_i32 s29, 0, 0x10000
	s_cmpk_eq_i32 s26, 0x7c
	s_cselect_b32 s67, s20, s28
	s_cselect_b32 s66, s21, s27
	v_add_u32_e32 v152, s29, v154
	s_cselect_b32 s55, s22, s25
	s_cselect_b32 s54, s23, s24
	s_add_i32 s27, 0, 0x14000
	ds_read_b128 v[158:161], v152
	ds_read_b128 v[180:183], v152 offset:1024
	ds_read_b128 v[184:187], v152 offset:2048
	ds_read_b128 v[188:191], v152 offset:3072
	v_add_u32_e32 v152, s27, v154
	ds_read_b128 v[192:195], v152
	ds_read_b128 v[196:199], v152 offset:1024
	ds_read_b128 v[200:203], v152 offset:2048
	ds_read_b128 v[204:207], v152 offset:3072
	v_lshl_add_u64 v[152:153], s[62:63], 0, v[150:151]
	s_add_i32 m0, s12, 0xc000
	ds_read_b128 v[208:211], v156
	ds_read_b128 v[212:215], v156 offset:1024
	ds_read_b128 v[216:219], v156 offset:2048
	ds_read_b128 v[222:225], v156 offset:3072
	ds_read_b128 v[226:229], v156 offset:4096
	ds_read_b128 v[230:233], v156 offset:5120
	ds_read_b128 v[234:237], v156 offset:6144
	ds_read_b128 v[238:241], v156 offset:7168
	global_load_lds_dwordx4 v[152:153], off
	v_lshl_add_u64 v[152:153], s[62:63], 0, v[148:149]
	s_add_i32 m0, s12, 0xe000
	s_nop 0
	global_load_lds_dwordx4 v[152:153], off
	s_waitcnt vmcnt(8)
	s_waitcnt lgkmcnt(0)
	s_barrier
	s_setprio 1
	s_waitcnt lgkmcnt(0)
	v_mfma_f32_16x16x32_bf16 v[128:131], v[158:161], v[208:211], v[128:131]
	v_mfma_f32_16x16x32_bf16 v[128:131], v[180:183], v[212:215], v[128:131]
	v_mfma_f32_16x16x32_bf16 v[120:123], v[158:161], v[216:219], v[120:123]
	v_mfma_f32_16x16x32_bf16 v[120:123], v[180:183], v[222:225], v[120:123]
	v_mfma_f32_16x16x32_bf16 v[104:107], v[158:161], v[226:229], v[104:107]
	v_mfma_f32_16x16x32_bf16 v[104:107], v[180:183], v[230:233], v[104:107]
	v_mfma_f32_16x16x32_bf16 v[88:91], v[158:161], v[234:237], v[88:91]
	v_mfma_f32_16x16x32_bf16 v[88:91], v[180:183], v[238:241], v[88:91]
	v_mfma_f32_16x16x32_bf16 v[80:83], v[184:187], v[234:237], v[80:83]
	v_mfma_f32_16x16x32_bf16 v[80:83], v[188:191], v[238:241], v[80:83]
	v_mfma_f32_16x16x32_bf16 v[96:99], v[184:187], v[226:229], v[96:99]
	v_mfma_f32_16x16x32_bf16 v[96:99], v[188:191], v[230:233], v[96:99]
	v_mfma_f32_16x16x32_bf16 v[112:115], v[184:187], v[216:219], v[112:115]
	v_mfma_f32_16x16x32_bf16 v[112:115], v[188:191], v[222:225], v[112:115]
	v_mfma_f32_16x16x32_bf16 v[124:127], v[184:187], v[208:211], v[124:127]
	v_mfma_f32_16x16x32_bf16 v[124:127], v[188:191], v[212:215], v[124:127]
	s_setprio 0
	s_setprio 1
	v_mfma_f32_16x16x32_bf16 v[116:119], v[192:195], v[208:211], v[116:119]
	v_mfma_f32_16x16x32_bf16 v[116:119], v[196:199], v[212:215], v[116:119]
	v_mfma_f32_16x16x32_bf16 v[100:103], v[192:195], v[216:219], v[100:103]
	v_mfma_f32_16x16x32_bf16 v[100:103], v[196:199], v[222:225], v[100:103]
	v_mfma_f32_16x16x32_bf16 v[84:87], v[192:195], v[226:229], v[84:87]
	v_mfma_f32_16x16x32_bf16 v[84:87], v[196:199], v[230:233], v[84:87]
	v_mfma_f32_16x16x32_bf16 v[72:75], v[192:195], v[234:237], v[72:75]
	v_mfma_f32_16x16x32_bf16 v[72:75], v[196:199], v[238:241], v[72:75]
	v_mfma_f32_16x16x32_bf16 v[68:71], v[200:203], v[234:237], v[68:71]
	v_mfma_f32_16x16x32_bf16 v[68:71], v[204:207], v[238:241], v[68:71]
	v_mfma_f32_16x16x32_bf16 v[76:79], v[200:203], v[226:229], v[76:79]
	v_mfma_f32_16x16x32_bf16 v[76:79], v[204:207], v[230:233], v[76:79]
	v_mfma_f32_16x16x32_bf16 v[92:95], v[200:203], v[216:219], v[92:95]
	v_mfma_f32_16x16x32_bf16 v[92:95], v[204:207], v[222:225], v[92:95]
	v_mfma_f32_16x16x32_bf16 v[108:111], v[200:203], v[208:211], v[108:111]
	v_mfma_f32_16x16x32_bf16 v[108:111], v[204:207], v[212:215], v[108:111]
	s_setprio 0
	s_barrier
	s_add_i32 s28, s29, s11
	v_lshl_add_u64 v[152:153], s[54:55], 0, v[34:35]
	s_mov_b32 m0, s28
	ds_read_b128 v[208:211], v156 offset:16384
	ds_read_b128 v[212:215], v156 offset:17408
	ds_read_b128 v[216:219], v156 offset:18432
	ds_read_b128 v[222:225], v156 offset:19456
	ds_read_b128 v[226:229], v156 offset:20480
	ds_read_b128 v[230:233], v156 offset:21504
	ds_read_b128 v[234:237], v156 offset:22528
	ds_read_b128 v[238:241], v156 offset:23552
	global_load_lds_dwordx4 v[152:153], off
	s_add_i32 m0, s28, 0x2000
	s_add_u32 s28, s54, 0x200000
	v_lshl_add_u64 v[162:163], s[54:55], 0, v[146:147]
	s_addc_u32 s29, s55, 0
	s_add_i32 s27, s27, s11
	global_load_lds_dwordx4 v[162:163], off
	v_lshl_add_u64 v[242:243], s[28:29], 0, v[34:35]
	s_mov_b32 m0, s27
	v_lshl_add_u64 v[244:245], s[66:67], 0, v[144:145]
	global_load_lds_dwordx4 v[242:243], off
	v_lshl_add_u64 v[242:243], s[28:29], 0, v[146:147]
	s_add_i32 m0, s27, 0x2000
	s_nop 0
	global_load_lds_dwordx4 v[242:243], off
	v_lshl_add_u64 v[242:243], s[66:67], 0, v[142:143]
	s_mov_b32 m0, s12
	s_nop 0
	global_load_lds_dwordx4 v[242:243], off
	s_mov_b32 m0, s13
	s_nop 0
	global_load_lds_dwordx4 v[244:245], off
	s_waitcnt vmcnt(8)
	s_waitcnt lgkmcnt(0)
	s_barrier
	s_setprio 1
	s_waitcnt lgkmcnt(0)
	v_mfma_f32_16x16x32_bf16 v[64:67], v[158:161], v[208:211], v[64:67]
	v_mfma_f32_16x16x32_bf16 v[64:67], v[180:183], v[212:215], v[64:67]
	v_mfma_f32_16x16x32_bf16 v[56:59], v[158:161], v[216:219], v[56:59]
	v_mfma_f32_16x16x32_bf16 v[56:59], v[180:183], v[222:225], v[56:59]
	v_mfma_f32_16x16x32_bf16 v[40:43], v[158:161], v[226:229], v[40:43]
	v_mfma_f32_16x16x32_bf16 v[40:43], v[180:183], v[230:233], v[40:43]
	v_mfma_f32_16x16x32_bf16 v[22:25], v[158:161], v[234:237], v[22:25]
	v_mfma_f32_16x16x32_bf16 v[22:25], v[180:183], v[238:241], v[22:25]
	v_mfma_f32_16x16x32_bf16 v[14:17], v[184:187], v[234:237], v[14:17]
	v_mfma_f32_16x16x32_bf16 v[14:17], v[188:191], v[238:241], v[14:17]
	v_mfma_f32_16x16x32_bf16 v[30:33], v[184:187], v[226:229], v[30:33]
	v_mfma_f32_16x16x32_bf16 v[30:33], v[188:191], v[230:233], v[30:33]
	v_mfma_f32_16x16x32_bf16 v[48:51], v[184:187], v[216:219], v[48:51]
	v_mfma_f32_16x16x32_bf16 v[48:51], v[188:191], v[222:225], v[48:51]
	v_mfma_f32_16x16x32_bf16 v[60:63], v[184:187], v[208:211], v[60:63]
	v_mfma_f32_16x16x32_bf16 v[60:63], v[188:191], v[212:215], v[60:63]
	s_setprio 0
	s_setprio 1
	v_mfma_f32_16x16x32_bf16 v[52:55], v[192:195], v[208:211], v[52:55]
	v_mfma_f32_16x16x32_bf16 v[52:55], v[196:199], v[212:215], v[52:55]
	v_mfma_f32_16x16x32_bf16 v[36:39], v[192:195], v[216:219], v[36:39]
	v_mfma_f32_16x16x32_bf16 v[36:39], v[196:199], v[222:225], v[36:39]
	v_mfma_f32_16x16x32_bf16 v[18:21], v[192:195], v[226:229], v[18:21]
	v_mfma_f32_16x16x32_bf16 v[18:21], v[196:199], v[230:233], v[18:21]
	v_mfma_f32_16x16x32_bf16 v[6:9], v[192:195], v[234:237], v[6:9]
	v_mfma_f32_16x16x32_bf16 v[6:9], v[196:199], v[238:241], v[6:9]
	v_mfma_f32_16x16x32_bf16 v[2:5], v[200:203], v[234:237], v[2:5]
	v_mfma_f32_16x16x32_bf16 v[2:5], v[204:207], v[238:241], v[2:5]
	v_mfma_f32_16x16x32_bf16 v[10:13], v[200:203], v[226:229], v[10:13]
	v_mfma_f32_16x16x32_bf16 v[10:13], v[204:207], v[230:233], v[10:13]
	v_mfma_f32_16x16x32_bf16 v[26:29], v[200:203], v[216:219], v[26:29]
	v_mfma_f32_16x16x32_bf16 v[26:29], v[204:207], v[222:225], v[26:29]
	v_mfma_f32_16x16x32_bf16 v[44:47], v[200:203], v[208:211], v[44:47]
	v_mfma_f32_16x16x32_bf16 v[44:47], v[204:207], v[212:215], v[44:47]
	s_setprio 0
	s_barrier
	s_add_i32 s27, 0, 0x18000
	v_add_u32_e32 v157, s27, v154
	s_add_i32 s30, 0, 0x1c000
	ds_read_b128 v[158:161], v157
	ds_read_b128 v[180:183], v157 offset:1024
	ds_read_b128 v[184:187], v157 offset:2048
	ds_read_b128 v[188:191], v157 offset:3072
	v_add_u32_e32 v157, s30, v154
	ds_read_b128 v[192:195], v157
	ds_read_b128 v[196:199], v157 offset:1024
	ds_read_b128 v[200:203], v157 offset:2048
	ds_read_b128 v[204:207], v157 offset:3072
	s_add_u32 s28, s66, 0x200000
	s_addc_u32 s29, s67, 0
	s_mov_b32 m0, s14
	v_lshl_add_u64 v[246:247], s[28:29], 0, v[142:143]
	ds_read_b128 v[208:211], v156 offset:32768
	ds_read_b128 v[212:215], v156 offset:33792
	ds_read_b128 v[216:219], v156 offset:34816
	ds_read_b128 v[222:225], v156 offset:35840
	ds_read_b128 v[226:229], v156 offset:36864
	ds_read_b128 v[230:233], v156 offset:37888
	ds_read_b128 v[234:237], v156 offset:38912
	ds_read_b128 v[238:241], v156 offset:39936
	global_load_lds_dwordx4 v[246:247], off
	v_lshl_add_u64 v[246:247], s[28:29], 0, v[144:145]
	s_mov_b32 m0, s15
	s_nop 0
	global_load_lds_dwordx4 v[246:247], off
	s_waitcnt vmcnt(8)
	s_waitcnt lgkmcnt(0)
	s_barrier
	s_setprio 1
	s_waitcnt lgkmcnt(0)
	v_mfma_f32_16x16x32_bf16 v[128:131], v[158:161], v[208:211], v[128:131]
	v_mfma_f32_16x16x32_bf16 v[128:131], v[180:183], v[212:215], v[128:131]
	v_mfma_f32_16x16x32_bf16 v[120:123], v[158:161], v[216:219], v[120:123]
	v_mfma_f32_16x16x32_bf16 v[120:123], v[180:183], v[222:225], v[120:123]
	v_mfma_f32_16x16x32_bf16 v[104:107], v[158:161], v[226:229], v[104:107]
	v_mfma_f32_16x16x32_bf16 v[104:107], v[180:183], v[230:233], v[104:107]
	v_mfma_f32_16x16x32_bf16 v[88:91], v[158:161], v[234:237], v[88:91]
	v_mfma_f32_16x16x32_bf16 v[88:91], v[180:183], v[238:241], v[88:91]
	v_mfma_f32_16x16x32_bf16 v[80:83], v[184:187], v[234:237], v[80:83]
	v_mfma_f32_16x16x32_bf16 v[80:83], v[188:191], v[238:241], v[80:83]
	v_mfma_f32_16x16x32_bf16 v[96:99], v[184:187], v[226:229], v[96:99]
	v_mfma_f32_16x16x32_bf16 v[96:99], v[188:191], v[230:233], v[96:99]
	v_mfma_f32_16x16x32_bf16 v[112:115], v[184:187], v[216:219], v[112:115]
	v_mfma_f32_16x16x32_bf16 v[112:115], v[188:191], v[222:225], v[112:115]
	v_mfma_f32_16x16x32_bf16 v[124:127], v[184:187], v[208:211], v[124:127]
	v_mfma_f32_16x16x32_bf16 v[124:127], v[188:191], v[212:215], v[124:127]
	s_setprio 0
	s_setprio 1
	v_mfma_f32_16x16x32_bf16 v[116:119], v[192:195], v[208:211], v[116:119]
	v_mfma_f32_16x16x32_bf16 v[116:119], v[196:199], v[212:215], v[116:119]
	v_mfma_f32_16x16x32_bf16 v[100:103], v[192:195], v[216:219], v[100:103]
	v_mfma_f32_16x16x32_bf16 v[100:103], v[196:199], v[222:225], v[100:103]
	v_mfma_f32_16x16x32_bf16 v[84:87], v[192:195], v[226:229], v[84:87]
	v_mfma_f32_16x16x32_bf16 v[84:87], v[196:199], v[230:233], v[84:87]
	v_mfma_f32_16x16x32_bf16 v[72:75], v[192:195], v[234:237], v[72:75]
	v_mfma_f32_16x16x32_bf16 v[72:75], v[196:199], v[238:241], v[72:75]
	v_mfma_f32_16x16x32_bf16 v[68:71], v[200:203], v[234:237], v[68:71]
	v_mfma_f32_16x16x32_bf16 v[68:71], v[204:207], v[238:241], v[68:71]
	v_mfma_f32_16x16x32_bf16 v[76:79], v[200:203], v[226:229], v[76:79]
	v_mfma_f32_16x16x32_bf16 v[76:79], v[204:207], v[230:233], v[76:79]
	v_mfma_f32_16x16x32_bf16 v[92:95], v[200:203], v[216:219], v[92:95]
	v_mfma_f32_16x16x32_bf16 v[92:95], v[204:207], v[222:225], v[92:95]
	v_mfma_f32_16x16x32_bf16 v[108:111], v[200:203], v[208:211], v[108:111]
	v_mfma_f32_16x16x32_bf16 v[108:111], v[204:207], v[212:215], v[108:111]
	s_setprio 0
	s_barrier
	s_add_i32 s27, s27, s11
	v_lshl_add_u64 v[152:153], v[152:153], 0, s[78:79]
	s_mov_b32 m0, s27
	ds_read_b128 v[208:211], v156 offset:49152
	ds_read_b128 v[212:215], v156 offset:50176
	ds_read_b128 v[216:219], v156 offset:51200
	ds_read_b128 v[222:225], v156 offset:52224
	ds_read_b128 v[226:229], v156 offset:53248
	ds_read_b128 v[230:233], v156 offset:54272
	ds_read_b128 v[234:237], v156 offset:55296
	ds_read_b128 v[238:241], v156 offset:56320
	global_load_lds_dwordx4 v[152:153], off
	s_add_i32 m0, s27, 0x2000
	s_add_u32 s28, s54, 0x200080
	v_lshl_add_u64 v[152:153], v[162:163], 0, s[78:79]
	s_addc_u32 s29, s55, 0
	s_add_i32 s27, s30, s11
	global_load_lds_dwordx4 v[152:153], off
	v_lshl_add_u64 v[152:153], s[28:29], 0, v[34:35]
	s_mov_b32 m0, s27
	s_nop 0
	global_load_lds_dwordx4 v[152:153], off
	v_lshl_add_u64 v[152:153], s[28:29], 0, v[146:147]
	s_add_i32 m0, s27, 0x2000
	s_nop 0
	global_load_lds_dwordx4 v[152:153], off
	v_lshl_add_u64 v[152:153], v[242:243], 0, s[78:79]
	s_mov_b32 m0, s16
	s_nop 0
	global_load_lds_dwordx4 v[152:153], off
	v_lshl_add_u64 v[152:153], v[244:245], 0, s[78:79]
	s_mov_b32 m0, s17
	s_nop 0
	global_load_lds_dwordx4 v[152:153], off
	s_waitcnt vmcnt(8)
	s_waitcnt lgkmcnt(0)
	s_barrier
	s_setprio 1
	s_waitcnt lgkmcnt(0)
	v_mfma_f32_16x16x32_bf16 v[64:67], v[158:161], v[208:211], v[64:67]
	v_mfma_f32_16x16x32_bf16 v[64:67], v[180:183], v[212:215], v[64:67]
	v_mfma_f32_16x16x32_bf16 v[56:59], v[158:161], v[216:219], v[56:59]
	v_mfma_f32_16x16x32_bf16 v[56:59], v[180:183], v[222:225], v[56:59]
	v_mfma_f32_16x16x32_bf16 v[40:43], v[158:161], v[226:229], v[40:43]
	v_mfma_f32_16x16x32_bf16 v[40:43], v[180:183], v[230:233], v[40:43]
	v_mfma_f32_16x16x32_bf16 v[22:25], v[158:161], v[234:237], v[22:25]
	v_mfma_f32_16x16x32_bf16 v[22:25], v[180:183], v[238:241], v[22:25]
	v_mfma_f32_16x16x32_bf16 v[14:17], v[184:187], v[234:237], v[14:17]
	v_mfma_f32_16x16x32_bf16 v[14:17], v[188:191], v[238:241], v[14:17]
	v_mfma_f32_16x16x32_bf16 v[30:33], v[184:187], v[226:229], v[30:33]
	v_mfma_f32_16x16x32_bf16 v[30:33], v[188:191], v[230:233], v[30:33]
	v_mfma_f32_16x16x32_bf16 v[48:51], v[184:187], v[216:219], v[48:51]
	v_mfma_f32_16x16x32_bf16 v[48:51], v[188:191], v[222:225], v[48:51]
	v_mfma_f32_16x16x32_bf16 v[60:63], v[184:187], v[208:211], v[60:63]
	v_mfma_f32_16x16x32_bf16 v[60:63], v[188:191], v[212:215], v[60:63]
	s_setprio 0
	s_setprio 1
	v_mfma_f32_16x16x32_bf16 v[52:55], v[192:195], v[208:211], v[52:55]
	v_mfma_f32_16x16x32_bf16 v[52:55], v[196:199], v[212:215], v[52:55]
	v_mfma_f32_16x16x32_bf16 v[36:39], v[192:195], v[216:219], v[36:39]
	v_mfma_f32_16x16x32_bf16 v[36:39], v[196:199], v[222:225], v[36:39]
	v_mfma_f32_16x16x32_bf16 v[18:21], v[192:195], v[226:229], v[18:21]
	v_mfma_f32_16x16x32_bf16 v[18:21], v[196:199], v[230:233], v[18:21]
	v_mfma_f32_16x16x32_bf16 v[6:9], v[192:195], v[234:237], v[6:9]
	v_mfma_f32_16x16x32_bf16 v[6:9], v[196:199], v[238:241], v[6:9]
	v_mfma_f32_16x16x32_bf16 v[2:5], v[200:203], v[234:237], v[2:5]
	v_mfma_f32_16x16x32_bf16 v[2:5], v[204:207], v[238:241], v[2:5]
	v_mfma_f32_16x16x32_bf16 v[10:13], v[200:203], v[226:229], v[10:13]
	v_mfma_f32_16x16x32_bf16 v[10:13], v[204:207], v[230:233], v[10:13]
	v_mfma_f32_16x16x32_bf16 v[26:29], v[200:203], v[216:219], v[26:29]
	v_mfma_f32_16x16x32_bf16 v[26:29], v[204:207], v[222:225], v[26:29]
	v_mfma_f32_16x16x32_bf16 v[44:47], v[200:203], v[208:211], v[44:47]
	v_mfma_f32_16x16x32_bf16 v[44:47], v[204:207], v[212:215], v[44:47]
	s_setprio 0
	s_barrier
	s_add_i32 s26, s26, 2
	s_add_u32 s24, s24, 0x100
	s_addc_u32 s25, s25, 0
	s_add_u32 s62, s62, 0x100
	s_addc_u32 s63, s63, 0
	s_cmpk_gt_u32 s26, 0x7d
	s_cbranch_scc0 .LBB0_1064
	s_and_b64 vcc, exec, s[44:45]
	s_cbranch_vccz .LBB0_1067
	s_barrier

.LBB0_1207:
	s_add_u32 s30, s90, 0xfff80080
	s_addc_u32 s31, s91, -1
	s_add_i32 s40, 0, 0x10000
	s_cmp_eq_u32 s29, 28
	s_cselect_b32 vcc_hi, s23, s31
	s_cselect_b32 vcc_lo, s24, s30
	v_add_u32_e32 v142, s40, v146
	s_cselect_b32 s55, s25, s28
	s_cselect_b32 s54, s26, s27
	s_add_i32 s44, 0, 0x14000
	ds_read_b128 v[150:153], v142
	ds_read_b128 v[154:157], v142 offset:1024
	ds_read_b128 v[158:161], v142 offset:2048
	ds_read_b128 v[162:165], v142 offset:3072
	v_add_u32_e32 v142, s44, v146
	ds_read_b128 v[166:169], v142
	ds_read_b128 v[170:173], v142 offset:1024
	ds_read_b128 v[174:177], v142 offset:2048
	ds_read_b128 v[178:181], v142 offset:3072
	v_lshl_add_u64 v[144:145], s[90:91], 0, v[138:139]
	s_add_i32 m0, s15, 0xc000
	ds_read_b128 v[182:185], v148
	ds_read_b128 v[186:189], v148 offset:1024
	ds_read_b128 v[190:193], v148 offset:2048
	ds_read_b128 v[210:213], v148 offset:3072
	ds_read_b128 v[214:217], v148 offset:4096
	ds_read_b128 v[230:233], v148 offset:5120
	ds_read_b128 v[234:237], v148 offset:6144
	ds_read_b128 v[238:241], v148 offset:7168
	global_load_lds_dwordx4 v[144:145], off
	v_lshl_add_u64 v[144:145], s[90:91], 0, v[136:137]
	s_add_i32 m0, s15, 0xe000
	s_nop 0
	global_load_lds_dwordx4 v[144:145], off
	s_waitcnt vmcnt(8)
	s_waitcnt lgkmcnt(0)
	s_barrier
	s_setprio 1
	s_waitcnt lgkmcnt(0)
	v_mfma_f32_16x16x32_bf16 v[126:129], v[150:153], v[182:185], v[126:129]
	v_mfma_f32_16x16x32_bf16 v[126:129], v[154:157], v[186:189], v[126:129]
	v_mfma_f32_16x16x32_bf16 v[114:117], v[150:153], v[190:193], v[114:117]
	v_mfma_f32_16x16x32_bf16 v[114:117], v[154:157], v[210:213], v[114:117]
	v_mfma_f32_16x16x32_bf16 v[98:101], v[150:153], v[214:217], v[98:101]
	v_mfma_f32_16x16x32_bf16 v[98:101], v[154:157], v[230:233], v[98:101]
	v_mfma_f32_16x16x32_bf16 v[82:85], v[150:153], v[234:237], v[82:85]
	v_mfma_f32_16x16x32_bf16 v[82:85], v[154:157], v[238:241], v[82:85]
	v_mfma_f32_16x16x32_bf16 v[74:77], v[158:161], v[234:237], v[74:77]
	v_mfma_f32_16x16x32_bf16 v[74:77], v[162:165], v[238:241], v[74:77]
	v_mfma_f32_16x16x32_bf16 v[90:93], v[158:161], v[214:217], v[90:93]
	v_mfma_f32_16x16x32_bf16 v[90:93], v[162:165], v[230:233], v[90:93]
	v_mfma_f32_16x16x32_bf16 v[106:109], v[158:161], v[190:193], v[106:109]
	v_mfma_f32_16x16x32_bf16 v[106:109], v[162:165], v[210:213], v[106:109]
	v_mfma_f32_16x16x32_bf16 v[122:125], v[158:161], v[182:185], v[122:125]
	v_mfma_f32_16x16x32_bf16 v[122:125], v[162:165], v[186:189], v[122:125]
	s_setprio 0
	s_setprio 1
	v_mfma_f32_16x16x32_bf16 v[118:121], v[166:169], v[182:185], v[118:121]
	v_mfma_f32_16x16x32_bf16 v[118:121], v[170:173], v[186:189], v[118:121]
	v_mfma_f32_16x16x32_bf16 v[102:105], v[166:169], v[190:193], v[102:105]
	v_mfma_f32_16x16x32_bf16 v[102:105], v[170:173], v[210:213], v[102:105]
	v_mfma_f32_16x16x32_bf16 v[86:89], v[166:169], v[214:217], v[86:89]
	v_mfma_f32_16x16x32_bf16 v[86:89], v[170:173], v[230:233], v[86:89]
	v_mfma_f32_16x16x32_bf16 v[70:73], v[166:169], v[234:237], v[70:73]
	v_mfma_f32_16x16x32_bf16 v[70:73], v[170:173], v[238:241], v[70:73]
	v_mfma_f32_16x16x32_bf16 v[66:69], v[174:177], v[234:237], v[66:69]
	v_mfma_f32_16x16x32_bf16 v[66:69], v[178:181], v[238:241], v[66:69]
	v_mfma_f32_16x16x32_bf16 v[78:81], v[174:177], v[214:217], v[78:81]
	v_mfma_f32_16x16x32_bf16 v[78:81], v[178:181], v[230:233], v[78:81]
	v_mfma_f32_16x16x32_bf16 v[94:97], v[174:177], v[190:193], v[94:97]
	v_mfma_f32_16x16x32_bf16 v[94:97], v[178:181], v[210:213], v[94:97]
	v_mfma_f32_16x16x32_bf16 v[110:113], v[174:177], v[182:185], v[110:113]
	v_mfma_f32_16x16x32_bf16 v[110:113], v[178:181], v[186:189], v[110:113]
	s_setprio 0
	s_barrier
	s_add_i32 s30, s40, s10
	v_lshl_add_u64 v[144:145], s[54:55], 0, v[194:195]
	s_mov_b32 m0, s30
	ds_read_b128 v[182:185], v148 offset:16384
	ds_read_b128 v[186:189], v148 offset:17408
	ds_read_b128 v[190:193], v148 offset:18432
	ds_read_b128 v[210:213], v148 offset:19456
	ds_read_b128 v[214:217], v148 offset:20480
	ds_read_b128 v[230:233], v148 offset:21504
	ds_read_b128 v[234:237], v148 offset:22528
	ds_read_b128 v[238:241], v148 offset:23552
	global_load_lds_dwordx4 v[144:145], off
	s_add_i32 m0, s30, 0x2000
	s_add_u32 s30, s54, 0x80000
	v_lshl_add_u64 v[218:219], s[54:55], 0, v[130:131]
	s_addc_u32 s31, s55, 0
	s_add_i32 s40, s44, s10
	global_load_lds_dwordx4 v[218:219], off
	v_lshl_add_u64 v[242:243], s[30:31], 0, v[194:195]
	s_mov_b32 m0, s40
	v_lshl_add_u64 v[244:245], vcc, 0, v[132:133]
	global_load_lds_dwordx4 v[242:243], off
	v_lshl_add_u64 v[242:243], s[30:31], 0, v[130:131]
	s_add_i32 m0, s40, 0x2000
	s_nop 0
	global_load_lds_dwordx4 v[242:243], off
	v_lshl_add_u64 v[242:243], vcc, 0, v[134:135]
	s_mov_b32 m0, s15
	s_nop 0
	global_load_lds_dwordx4 v[242:243], off
	s_mov_b32 m0, s16
	s_nop 0
	global_load_lds_dwordx4 v[244:245], off
	s_waitcnt vmcnt(8)
	s_waitcnt lgkmcnt(0)
	s_barrier
	s_setprio 1
	s_waitcnt lgkmcnt(0)
	v_mfma_f32_16x16x32_bf16 v[62:65], v[150:153], v[182:185], v[62:65]
	v_mfma_f32_16x16x32_bf16 v[62:65], v[154:157], v[186:189], v[62:65]
	v_mfma_f32_16x16x32_bf16 v[50:53], v[150:153], v[190:193], v[50:53]
	v_mfma_f32_16x16x32_bf16 v[50:53], v[154:157], v[210:213], v[50:53]
	v_mfma_f32_16x16x32_bf16 v[34:37], v[150:153], v[214:217], v[34:37]
	v_mfma_f32_16x16x32_bf16 v[34:37], v[154:157], v[230:233], v[34:37]
	v_mfma_f32_16x16x32_bf16 v[18:21], v[150:153], v[234:237], v[18:21]
	v_mfma_f32_16x16x32_bf16 v[18:21], v[154:157], v[238:241], v[18:21]
	v_mfma_f32_16x16x32_bf16 v[10:13], v[158:161], v[234:237], v[10:13]
	v_mfma_f32_16x16x32_bf16 v[10:13], v[162:165], v[238:241], v[10:13]
	v_mfma_f32_16x16x32_bf16 v[26:29], v[158:161], v[214:217], v[26:29]
	v_mfma_f32_16x16x32_bf16 v[26:29], v[162:165], v[230:233], v[26:29]
	v_mfma_f32_16x16x32_bf16 v[42:45], v[158:161], v[190:193], v[42:45]
	v_mfma_f32_16x16x32_bf16 v[42:45], v[162:165], v[210:213], v[42:45]
	v_mfma_f32_16x16x32_bf16 v[58:61], v[158:161], v[182:185], v[58:61]
	v_mfma_f32_16x16x32_bf16 v[58:61], v[162:165], v[186:189], v[58:61]
	s_setprio 0
	s_setprio 1
	v_mfma_f32_16x16x32_bf16 v[54:57], v[166:169], v[182:185], v[54:57]
	v_mfma_f32_16x16x32_bf16 v[54:57], v[170:173], v[186:189], v[54:57]
	v_mfma_f32_16x16x32_bf16 v[38:41], v[166:169], v[190:193], v[38:41]
	v_mfma_f32_16x16x32_bf16 v[38:41], v[170:173], v[210:213], v[38:41]
	v_mfma_f32_16x16x32_bf16 v[22:25], v[166:169], v[214:217], v[22:25]
	v_mfma_f32_16x16x32_bf16 v[22:25], v[170:173], v[230:233], v[22:25]
	v_mfma_f32_16x16x32_bf16 v[6:9], v[166:169], v[234:237], v[6:9]
	v_mfma_f32_16x16x32_bf16 v[6:9], v[170:173], v[238:241], v[6:9]
	v_mfma_f32_16x16x32_bf16 v[2:5], v[174:177], v[234:237], v[2:5]
	v_mfma_f32_16x16x32_bf16 v[2:5], v[178:181], v[238:241], v[2:5]
	v_mfma_f32_16x16x32_bf16 v[14:17], v[174:177], v[214:217], v[14:17]
	v_mfma_f32_16x16x32_bf16 v[14:17], v[178:181], v[230:233], v[14:17]
	v_mfma_f32_16x16x32_bf16 v[30:33], v[174:177], v[190:193], v[30:33]
	v_mfma_f32_16x16x32_bf16 v[30:33], v[178:181], v[210:213], v[30:33]
	v_mfma_f32_16x16x32_bf16 v[46:49], v[174:177], v[182:185], v[46:49]
	v_mfma_f32_16x16x32_bf16 v[46:49], v[178:181], v[186:189], v[46:49]
	s_setprio 0
	s_barrier
	s_add_i32 s40, 0, 0x18000
	v_add_u32_e32 v142, s40, v146
	s_add_i32 s44, 0, 0x1c000
	ds_read_b128 v[150:153], v142
	ds_read_b128 v[154:157], v142 offset:1024
	ds_read_b128 v[158:161], v142 offset:2048
	ds_read_b128 v[162:165], v142 offset:3072
	v_add_u32_e32 v142, s44, v146
	ds_read_b128 v[166:169], v142
	ds_read_b128 v[170:173], v142 offset:1024
	ds_read_b128 v[174:177], v142 offset:2048
	ds_read_b128 v[178:181], v142 offset:3072
	s_add_u32 s30, vcc_lo, 0x80000
	s_addc_u32 s31, vcc_hi, 0
	s_mov_b32 m0, s17
	v_lshl_add_u64 v[246:247], s[30:31], 0, v[134:135]
	ds_read_b128 v[182:185], v148 offset:32768
	ds_read_b128 v[186:189], v148 offset:33792
	ds_read_b128 v[190:193], v148 offset:34816
	ds_read_b128 v[210:213], v148 offset:35840
	ds_read_b128 v[214:217], v148 offset:36864
	ds_read_b128 v[230:233], v148 offset:37888
	ds_read_b128 v[234:237], v148 offset:38912
	ds_read_b128 v[238:241], v148 offset:39936
	global_load_lds_dwordx4 v[246:247], off
	v_lshl_add_u64 v[246:247], s[30:31], 0, v[132:133]
	s_mov_b32 m0, s18
	s_nop 0
	global_load_lds_dwordx4 v[246:247], off
	s_waitcnt vmcnt(8)
	s_waitcnt lgkmcnt(0)
	s_barrier
	s_setprio 1
	s_waitcnt lgkmcnt(0)
	v_mfma_f32_16x16x32_bf16 v[126:129], v[150:153], v[182:185], v[126:129]
	v_mfma_f32_16x16x32_bf16 v[126:129], v[154:157], v[186:189], v[126:129]
	v_mfma_f32_16x16x32_bf16 v[114:117], v[150:153], v[190:193], v[114:117]
	v_mfma_f32_16x16x32_bf16 v[114:117], v[154:157], v[210:213], v[114:117]
	v_mfma_f32_16x16x32_bf16 v[98:101], v[150:153], v[214:217], v[98:101]
	v_mfma_f32_16x16x32_bf16 v[98:101], v[154:157], v[230:233], v[98:101]
	v_mfma_f32_16x16x32_bf16 v[82:85], v[150:153], v[234:237], v[82:85]
	v_mfma_f32_16x16x32_bf16 v[82:85], v[154:157], v[238:241], v[82:85]
	v_mfma_f32_16x16x32_bf16 v[74:77], v[158:161], v[234:237], v[74:77]
	v_mfma_f32_16x16x32_bf16 v[74:77], v[162:165], v[238:241], v[74:77]
	v_mfma_f32_16x16x32_bf16 v[90:93], v[158:161], v[214:217], v[90:93]
	v_mfma_f32_16x16x32_bf16 v[90:93], v[162:165], v[230:233], v[90:93]
	v_mfma_f32_16x16x32_bf16 v[106:109], v[158:161], v[190:193], v[106:109]
	v_mfma_f32_16x16x32_bf16 v[106:109], v[162:165], v[210:213], v[106:109]
	v_mfma_f32_16x16x32_bf16 v[122:125], v[158:161], v[182:185], v[122:125]
	v_mfma_f32_16x16x32_bf16 v[122:125], v[162:165], v[186:189], v[122:125]
	s_setprio 0
	s_setprio 1
	v_mfma_f32_16x16x32_bf16 v[118:121], v[166:169], v[182:185], v[118:121]
	v_mfma_f32_16x16x32_bf16 v[118:121], v[170:173], v[186:189], v[118:121]
	v_mfma_f32_16x16x32_bf16 v[102:105], v[166:169], v[190:193], v[102:105]
	v_mfma_f32_16x16x32_bf16 v[102:105], v[170:173], v[210:213], v[102:105]
	v_mfma_f32_16x16x32_bf16 v[86:89], v[166:169], v[214:217], v[86:89]
	v_mfma_f32_16x16x32_bf16 v[86:89], v[170:173], v[230:233], v[86:89]
	v_mfma_f32_16x16x32_bf16 v[70:73], v[166:169], v[234:237], v[70:73]
	v_mfma_f32_16x16x32_bf16 v[70:73], v[170:173], v[238:241], v[70:73]
	v_mfma_f32_16x16x32_bf16 v[66:69], v[174:177], v[234:237], v[66:69]
	v_mfma_f32_16x16x32_bf16 v[66:69], v[178:181], v[238:241], v[66:69]
	v_mfma_f32_16x16x32_bf16 v[78:81], v[174:177], v[214:217], v[78:81]
	v_mfma_f32_16x16x32_bf16 v[78:81], v[178:181], v[230:233], v[78:81]
	v_mfma_f32_16x16x32_bf16 v[94:97], v[174:177], v[190:193], v[94:97]
	v_mfma_f32_16x16x32_bf16 v[94:97], v[178:181], v[210:213], v[94:97]
	v_mfma_f32_16x16x32_bf16 v[110:113], v[174:177], v[182:185], v[110:113]
	v_mfma_f32_16x16x32_bf16 v[110:113], v[178:181], v[186:189], v[110:113]
	s_setprio 0
	s_barrier
	s_add_i32 s30, s40, s10
	v_lshl_add_u64 v[144:145], v[144:145], 0, s[56:57]
	s_mov_b32 m0, s30
	ds_read_b128 v[182:185], v148 offset:49152
	ds_read_b128 v[186:189], v148 offset:50176
	ds_read_b128 v[190:193], v148 offset:51200
	ds_read_b128 v[210:213], v148 offset:52224
	ds_read_b128 v[214:217], v148 offset:53248
	ds_read_b128 v[230:233], v148 offset:54272
	ds_read_b128 v[234:237], v148 offset:55296
	ds_read_b128 v[238:241], v148 offset:56320
	global_load_lds_dwordx4 v[144:145], off
	s_add_i32 m0, s30, 0x2000
	s_add_u32 s30, s54, 0x80080
	v_lshl_add_u64 v[144:145], v[218:219], 0, s[56:57]
	s_addc_u32 s31, s55, 0
	s_add_i32 s40, s44, s10
	global_load_lds_dwordx4 v[144:145], off
	v_lshl_add_u64 v[144:145], s[30:31], 0, v[194:195]
	s_mov_b32 m0, s40
	s_nop 0
	global_load_lds_dwordx4 v[144:145], off
	v_lshl_add_u64 v[144:145], s[30:31], 0, v[130:131]
	s_add_i32 m0, s40, 0x2000
	s_nop 0
	global_load_lds_dwordx4 v[144:145], off
	v_lshl_add_u64 v[144:145], v[242:243], 0, s[56:57]
	s_mov_b32 m0, s21
	s_nop 0
	global_load_lds_dwordx4 v[144:145], off
	v_lshl_add_u64 v[144:145], v[244:245], 0, s[56:57]
	s_mov_b32 m0, s22
	s_nop 0
	global_load_lds_dwordx4 v[144:145], off
	s_waitcnt vmcnt(8)
	s_waitcnt lgkmcnt(0)
	s_barrier
	s_setprio 1
	s_waitcnt lgkmcnt(0)
	v_mfma_f32_16x16x32_bf16 v[62:65], v[150:153], v[182:185], v[62:65]
	v_mfma_f32_16x16x32_bf16 v[62:65], v[154:157], v[186:189], v[62:65]
	v_mfma_f32_16x16x32_bf16 v[50:53], v[150:153], v[190:193], v[50:53]
	v_mfma_f32_16x16x32_bf16 v[50:53], v[154:157], v[210:213], v[50:53]
	v_mfma_f32_16x16x32_bf16 v[34:37], v[150:153], v[214:217], v[34:37]
	v_mfma_f32_16x16x32_bf16 v[34:37], v[154:157], v[230:233], v[34:37]
	v_mfma_f32_16x16x32_bf16 v[18:21], v[150:153], v[234:237], v[18:21]
	v_mfma_f32_16x16x32_bf16 v[18:21], v[154:157], v[238:241], v[18:21]
	v_mfma_f32_16x16x32_bf16 v[10:13], v[158:161], v[234:237], v[10:13]
	v_mfma_f32_16x16x32_bf16 v[10:13], v[162:165], v[238:241], v[10:13]
	v_mfma_f32_16x16x32_bf16 v[26:29], v[158:161], v[214:217], v[26:29]
	v_mfma_f32_16x16x32_bf16 v[26:29], v[162:165], v[230:233], v[26:29]
	v_mfma_f32_16x16x32_bf16 v[42:45], v[158:161], v[190:193], v[42:45]
	v_mfma_f32_16x16x32_bf16 v[42:45], v[162:165], v[210:213], v[42:45]
	v_mfma_f32_16x16x32_bf16 v[58:61], v[158:161], v[182:185], v[58:61]
	v_mfma_f32_16x16x32_bf16 v[58:61], v[162:165], v[186:189], v[58:61]
	s_setprio 0
	s_setprio 1
	v_mfma_f32_16x16x32_bf16 v[54:57], v[166:169], v[182:185], v[54:57]
	v_mfma_f32_16x16x32_bf16 v[54:57], v[170:173], v[186:189], v[54:57]
	v_mfma_f32_16x16x32_bf16 v[38:41], v[166:169], v[190:193], v[38:41]
	v_mfma_f32_16x16x32_bf16 v[38:41], v[170:173], v[210:213], v[38:41]
	v_mfma_f32_16x16x32_bf16 v[22:25], v[166:169], v[214:217], v[22:25]
	v_mfma_f32_16x16x32_bf16 v[22:25], v[170:173], v[230:233], v[22:25]
	v_mfma_f32_16x16x32_bf16 v[6:9], v[166:169], v[234:237], v[6:9]
	v_mfma_f32_16x16x32_bf16 v[6:9], v[170:173], v[238:241], v[6:9]
	v_mfma_f32_16x16x32_bf16 v[2:5], v[174:177], v[234:237], v[2:5]
	v_mfma_f32_16x16x32_bf16 v[2:5], v[178:181], v[238:241], v[2:5]
	v_mfma_f32_16x16x32_bf16 v[14:17], v[174:177], v[214:217], v[14:17]
	v_mfma_f32_16x16x32_bf16 v[14:17], v[178:181], v[230:233], v[14:17]
	v_mfma_f32_16x16x32_bf16 v[30:33], v[174:177], v[190:193], v[30:33]
	v_mfma_f32_16x16x32_bf16 v[30:33], v[178:181], v[210:213], v[30:33]
	v_mfma_f32_16x16x32_bf16 v[46:49], v[174:177], v[182:185], v[46:49]
	v_mfma_f32_16x16x32_bf16 v[46:49], v[178:181], v[186:189], v[46:49]
	s_setprio 0
	s_barrier
	s_add_i32 s29, s29, 2
	s_add_u32 s27, s27, 0x100
	s_addc_u32 s28, s28, 0
	s_add_u32 s90, s90, 0x100
	s_addc_u32 s91, s91, 0
	s_cmp_gt_u32 s29, 29
	s_cbranch_scc0 .LBB0_1207
	s_and_b64 vcc, exec, s[36:37]
	s_cbranch_vccz .LBB0_1210
	s_barrier

.LBB0_1309:
	s_waitcnt lgkmcnt(7)
	v_mfma_f32_32x32x16_bf16 v[114:129], v[190:193], v[150:153], 0
	v_add_f32_e32 v98, v82, v83
	v_add_f32_e32 v98, v84, v98
	v_add_f32_e32 v98, v85, v98
	v_add_f32_e32 v98, v86, v98
	v_add_u32_e32 v247, s30, v246
	v_add_f32_e32 v98, v87, v98
	v_cvt_pk_bf16_f32 v158, v82, v83
	v_cvt_pk_bf16_f32 v159, v84, v85
	s_nop 0
	v_add_f32_e32 v82, v88, v98
	s_waitcnt lgkmcnt(6)
	v_mfma_f32_32x32x16_bf16 v[98:113], v[182:185], v[150:153], 0
	v_add_f32_e32 v82, v89, v82
	v_add_f32_e32 v82, v90, v82
	v_add_f32_e32 v82, v91, v82
	v_cvt_pk_bf16_f32 v160, v86, v87
	v_cvt_pk_bf16_f32 v161, v88, v89
	s_waitcnt lgkmcnt(5)
	v_mfma_f32_32x32x16_bf16 v[114:129], v[186:189], v[146:149], v[114:129]
	v_add_f32_e32 v82, v92, v82
	v_add_f32_e32 v82, v93, v82
	v_add_f32_e32 v82, v94, v82
	v_add_f32_e32 v82, v95, v82
	v_cvt_pk_bf16_f32 v154, v90, v91
	v_cvt_pk_bf16_f32 v155, v92, v93
	s_waitcnt lgkmcnt(4)
	v_mfma_f32_32x32x16_bf16 v[98:113], v[178:181], v[146:149], v[98:113]
	v_add_f32_e32 v82, v96, v82
	v_add_f32_e32 v82, v97, v82
	v_add_f32_e32 v82, v66, v82
	v_add_f32_e32 v86, v67, v82
	v_cvt_pk_bf16_f32 v156, v94, v95
	v_cvt_pk_bf16_f32 v157, v96, v97
	ds_read_b64_tr_b16 v[82:83], v247 offset:49152
	ds_read_b64_tr_b16 v[84:85], v247 offset:49664
	s_waitcnt lgkmcnt(5)
	v_mfma_f32_32x32x16_bf16 v[114:129], v[174:177], v[142:145], v[114:129]
	v_add_f32_e32 v86, v68, v86
	v_add_f32_e32 v86, v69, v86
	v_add_f32_e32 v86, v70, v86
	v_add_f32_e32 v86, v71, v86
	v_cvt_pk_bf16_f32 v138, v66, v67
	v_cvt_pk_bf16_f32 v139, v68, v69
	ds_read_b64_tr_b16 v[66:67], v247 offset:50176
	ds_read_b64_tr_b16 v[68:69], v247 offset:50688
	s_waitcnt lgkmcnt(6)
	v_mfma_f32_32x32x16_bf16 v[98:113], v[170:173], v[142:145], v[98:113]
	v_add_f32_e32 v86, v72, v86
	v_add_f32_e32 v86, v73, v86
	v_add_f32_e32 v86, v74, v86
	v_add_f32_e32 v86, v75, v86
	v_cvt_pk_bf16_f32 v140, v70, v71
	v_cvt_pk_bf16_f32 v141, v72, v73
	ds_read_b64_tr_b16 v[70:71], v247 offset:51200
	ds_read_b64_tr_b16 v[72:73], v247 offset:51712
	s_waitcnt lgkmcnt(7)
	v_mfma_f32_32x32x16_bf16 v[114:129], v[166:169], v[134:137], v[114:129]
	v_add_f32_e32 v86, v76, v86
	v_add_f32_e32 v86, v77, v86
	v_add_f32_e32 v86, v78, v86
	v_add_f32_e32 v86, v79, v86
	v_cvt_pk_bf16_f32 v130, v74, v75
	v_cvt_pk_bf16_f32 v131, v76, v77
	ds_read_b64_tr_b16 v[74:75], v247 offset:52224
	ds_read_b64_tr_b16 v[76:77], v247 offset:52736
	s_waitcnt lgkmcnt(8)
	v_mfma_f32_32x32x16_bf16 v[98:113], v[162:165], v[134:137], v[98:113]
	v_add_f32_e32 v86, v80, v86
	v_add_f32_e32 v86, v81, v86
	v_add_f32_e32 v86, 0, v86
	v_cvt_pk_bf16_f32 v132, v78, v79
	v_cvt_pk_bf16_f32 v133, v80, v81
	v_lshl_add_u64 v[188:189], v[214:215], 0, s[52:53]
	v_lshl_add_u64 v[78:79], v[188:189], 0, s[70:71]
	s_add_i32 s27, s91, s25
	s_mov_b32 s30, m0
	s_mov_b32 m0, s27
	s_nop 0
	global_load_lds_dwordx4 v[78:79], off
	s_mov_b32 m0, s30
	v_lshl_add_u64 v[78:79], v[188:189], 0, s[72:73]
	v_lshl_add_u64 v[186:187], v[216:217], 0, s[52:53]
	s_addk_i32 s27, 0x2000
	s_mov_b32 s30, m0
	s_mov_b32 m0, s27
	s_nop 0
	global_load_lds_dwordx4 v[78:79], off
	s_mov_b32 m0, s30
	v_lshl_add_u64 v[78:79], v[186:187], 0, s[74:75]
	s_add_i32 s27, s29, s24
	s_mov_b32 s30, m0
	s_mov_b32 m0, s27
	s_nop 0
	global_load_lds_dwordx4 v[78:79], off
	s_mov_b32 m0, s30
	v_lshl_add_u64 v[78:79], v[186:187], 0, s[76:77]
	s_addk_i32 s27, 0x2000
	s_mov_b32 s30, m0
	s_mov_b32 m0, s27
	s_nop 0
	global_load_lds_dwordx4 v[78:79], off
	s_mov_b32 m0, s30
	v_max_f32_e32 v78, v115, v115
	v_max_f32_e32 v79, v114, v114
	v_max_f32_e32 v78, v79, v78
	v_max3_f32 v79, v116, v117, v99
	v_max3_f32 v78, v78, v98, v100
	v_max3_f32 v78, v78, v101, v118
	v_max3_f32 v79, v79, v120, v121
	v_max3_f32 v78, v78, v119, v102
	v_max3_f32 v79, v79, v104, v105
	v_max3_f32 v78, v78, v103, v122
	v_max3_f32 v79, v79, v124, v125
	v_max3_f32 v78, v78, v123, v106
	v_max3_f32 v79, v79, v108, v109
	v_max3_f32 v78, v78, v107, v126
	v_max3_f32 v79, v79, v128, v129
	v_max3_f32 v78, v78, v127, v110
	v_max3_f32 v79, v79, v112, v113
	v_max3_f32 v78, v78, v111, v79
	v_mov_b32_e32 v79, v78
	s_nop 1
	v_permlane32_swap_b32_e32 v78, v79
	v_max_f32_e32 v79, v79, v79
	v_max_f32_e32 v78, v78, v78
	v_max_f32_e32 v78, v78, v79
	v_sub_f32_e32 v78, v78, v243
	v_cmp_lt_f32_e32 vcc, s93, v78
	s_cmp_lg_u64 vcc, 0
	v_add_f32_e32 v190, v250, v86
	s_cselect_b64 s[36:37], -1, 0
	s_cbranch_vccnz .LBB0_1317
.LBB0_1310:
	s_waitcnt lgkmcnt(6)
	v_mfma_f32_32x32x16_bf16 v[18:33], v[158:161], v[82:85], v[18:33]
	v_sub_f32_e32 v78, v114, v243
	v_exp_f32_e32 v114, v78
	v_sub_f32_e32 v78, v115, v243
	v_exp_f32_e32 v115, v78
	ds_read_b64_tr_b16 v[78:79], v247 offset:53248
	ds_read_b64_tr_b16 v[80:81], v247 offset:53760
	s_waitcnt lgkmcnt(6)
	v_mfma_f32_32x32x16_bf16 v[18:33], v[154:157], v[66:69], v[18:33]
	v_sub_f32_e32 v66, v116, v243
	v_exp_f32_e32 v116, v66
	v_sub_f32_e32 v66, v117, v243
	v_exp_f32_e32 v117, v66
	ds_read_b64_tr_b16 v[66:67], v247 offset:54272
	ds_read_b64_tr_b16 v[68:69], v247 offset:54784
	s_waitcnt lgkmcnt(6)
	v_mfma_f32_32x32x16_bf16 v[18:33], v[138:141], v[70:73], v[18:33]
	v_sub_f32_e32 v70, v118, v243
	v_exp_f32_e32 v118, v70
	v_sub_f32_e32 v70, v119, v243
	v_exp_f32_e32 v119, v70
	ds_read_b64_tr_b16 v[70:71], v247 offset:55296
	ds_read_b64_tr_b16 v[72:73], v247 offset:55808
	s_waitcnt lgkmcnt(6)
	v_mfma_f32_32x32x16_bf16 v[18:33], v[130:133], v[74:77], v[18:33]
	v_sub_f32_e32 v74, v120, v243
	v_exp_f32_e32 v120, v74
	v_sub_f32_e32 v74, v121, v243
	v_exp_f32_e32 v121, v74
	ds_read_b64_tr_b16 v[74:75], v247 offset:56320
	ds_read_b64_tr_b16 v[76:77], v247 offset:56832
	s_waitcnt lgkmcnt(6)
	v_mfma_f32_32x32x16_bf16 v[50:65], v[158:161], v[78:81], v[50:65]
	v_sub_f32_e32 v78, v122, v243
	v_exp_f32_e32 v122, v78
	v_sub_f32_e32 v78, v123, v243
	v_exp_f32_e32 v123, v78
	ds_read_b64_tr_b16 v[78:79], v247 offset:57344
	ds_read_b64_tr_b16 v[80:81], v247 offset:57856
	s_waitcnt lgkmcnt(6)
	v_mfma_f32_32x32x16_bf16 v[50:65], v[154:157], v[66:69], v[50:65]
	v_sub_f32_e32 v66, v124, v243
	v_exp_f32_e32 v124, v66
	v_sub_f32_e32 v66, v125, v243
	v_exp_f32_e32 v125, v66
	ds_read_b64_tr_b16 v[82:83], v247 offset:58368
	ds_read_b64_tr_b16 v[84:85], v247 offset:58880
	s_waitcnt lgkmcnt(6)
	v_mfma_f32_32x32x16_bf16 v[50:65], v[138:141], v[70:73], v[50:65]
	v_sub_f32_e32 v66, v126, v243
	v_exp_f32_e32 v126, v66
	v_sub_f32_e32 v66, v127, v243
	v_exp_f32_e32 v127, v66
	ds_read_b64_tr_b16 v[86:87], v247 offset:59392
	ds_read_b64_tr_b16 v[88:89], v247 offset:59904
	s_waitcnt lgkmcnt(6)
	v_mfma_f32_32x32x16_bf16 v[50:65], v[130:133], v[74:77], v[50:65]
	v_sub_f32_e32 v66, v128, v243
	v_exp_f32_e32 v128, v66
	v_sub_f32_e32 v66, v129, v243
	v_exp_f32_e32 v129, v66
	ds_read_b64_tr_b16 v[74:75], v247 offset:60416
	ds_read_b64_tr_b16 v[76:77], v247 offset:60928
	v_add_u32_e32 v90, s29, v245
	ds_read_b128 v[70:73], v90
	ds_read_b128 v[66:69], v90 offset:512
	s_waitcnt lgkmcnt(8)
	v_mfma_f32_32x32x16_bf16 v[34:49], v[158:161], v[78:81], v[34:49]
	v_sub_f32_e32 v78, v98, v243
	v_exp_f32_e32 v98, v78
	v_sub_f32_e32 v78, v99, v243
	v_exp_f32_e32 v99, v78
	ds_read_b64_tr_b16 v[78:79], v247 offset:61440
	ds_read_b64_tr_b16 v[80:81], v247 offset:61952
	ds_read_b128 v[182:185], v90 offset:2048
	ds_read_b128 v[174:177], v90 offset:2560
	s_waitcnt lgkmcnt(10)
	v_mfma_f32_32x32x16_bf16 v[34:49], v[154:157], v[82:85], v[34:49]
	v_sub_f32_e32 v82, v100, v243
	v_exp_f32_e32 v100, v82
	v_sub_f32_e32 v82, v101, v243
	v_exp_f32_e32 v101, v82
	ds_read_b64_tr_b16 v[82:83], v247 offset:62464
	ds_read_b64_tr_b16 v[84:85], v247 offset:62976
	ds_read_b128 v[178:181], v90 offset:4096
	ds_read_b128 v[166:169], v90 offset:4608
	s_waitcnt lgkmcnt(12)
	v_mfma_f32_32x32x16_bf16 v[34:49], v[138:141], v[86:89], v[34:49]
	v_sub_f32_e32 v86, v102, v243
	v_exp_f32_e32 v102, v86
	v_sub_f32_e32 v86, v103, v243
	v_exp_f32_e32 v103, v86
	ds_read_b64_tr_b16 v[86:87], v247 offset:63488
	ds_read_b64_tr_b16 v[88:89], v247 offset:64000
	ds_read_b128 v[170:173], v90 offset:6144
	ds_read_b128 v[162:165], v90 offset:6656
	s_waitcnt lgkmcnt(14)
	v_mfma_f32_32x32x16_bf16 v[34:49], v[130:133], v[74:77], v[34:49]
	v_sub_f32_e32 v74, v104, v243
	v_exp_f32_e32 v104, v74
	v_sub_f32_e32 v74, v105, v243
	v_exp_f32_e32 v105, v74
	ds_read_b64_tr_b16 v[74:75], v247 offset:64512
	ds_read_b64_tr_b16 v[76:77], v247 offset:65024
	s_waitcnt lgkmcnt(12)
	v_mfma_f32_32x32x16_bf16 v[2:17], v[158:161], v[78:81], v[2:17]
	v_sub_f32_e32 v78, v106, v243
	v_exp_f32_e32 v106, v78
	v_sub_f32_e32 v78, v107, v243
	v_exp_f32_e32 v107, v78
	s_waitcnt lgkmcnt(8)
	v_mfma_f32_32x32x16_bf16 v[2:17], v[154:157], v[82:85], v[2:17]
	v_sub_f32_e32 v78, v108, v243
	v_exp_f32_e32 v108, v78
	v_sub_f32_e32 v78, v109, v243
	v_exp_f32_e32 v109, v78
	s_waitcnt lgkmcnt(4)
	v_mfma_f32_32x32x16_bf16 v[2:17], v[138:141], v[86:89], v[2:17]
	v_sub_f32_e32 v78, v110, v243
	v_exp_f32_e32 v110, v78
	v_sub_f32_e32 v78, v111, v243
	v_exp_f32_e32 v111, v78
	s_waitcnt lgkmcnt(0)
	v_mfma_f32_32x32x16_bf16 v[2:17], v[130:133], v[74:77], v[2:17]
	v_sub_f32_e32 v74, v112, v243
	v_exp_f32_e32 v112, v74
	v_sub_f32_e32 v74, v113, v243
	v_exp_f32_e32 v113, v74
	s_waitcnt vmcnt(4) lgkmcnt(0)
	s_barrier
	s_andn2_b64 vcc, exec, s[36:37]
	s_cbranch_vccnz .LBB0_1312
	s_waitcnt lgkmcnt(0)
	ds_read_b128 v[74:77], v213 offset:96
	ds_read_b128 v[78:81], v213 offset:64
	ds_read_b128 v[82:85], v213 offset:32
	ds_read_b128 v[86:89], v213
	s_waitcnt lgkmcnt(3)
	v_pk_mul_f32 v[30:31], v[30:31], v[74:75]
	s_waitcnt lgkmcnt(2)
	v_pk_mul_f32 v[26:27], v[26:27], v[78:79]
	s_waitcnt lgkmcnt(1)
	v_pk_mul_f32 v[22:23], v[22:23], v[82:83]
	v_pk_mul_f32 v[32:33], v[32:33], v[76:77]
	v_pk_mul_f32 v[28:29], v[28:29], v[80:81]
	v_pk_mul_f32 v[24:25], v[24:25], v[84:85]
	s_waitcnt lgkmcnt(0)
	v_pk_mul_f32 v[20:21], v[20:21], v[88:89]
	v_pk_mul_f32 v[18:19], v[18:19], v[86:87]
	v_pk_mul_f32 v[62:63], v[62:63], v[74:75]
	v_pk_mul_f32 v[58:59], v[58:59], v[78:79]
	v_pk_mul_f32 v[54:55], v[54:55], v[82:83]
	v_pk_mul_f32 v[64:65], v[64:65], v[76:77]
	v_pk_mul_f32 v[60:61], v[60:61], v[80:81]
	v_pk_mul_f32 v[56:57], v[56:57], v[84:85]
	v_pk_mul_f32 v[52:53], v[52:53], v[88:89]
	v_pk_mul_f32 v[50:51], v[50:51], v[86:87]
	v_pk_mul_f32 v[46:47], v[46:47], v[74:75]
	v_pk_mul_f32 v[42:43], v[42:43], v[78:79]
	v_pk_mul_f32 v[38:39], v[38:39], v[82:83]
	v_pk_mul_f32 v[48:49], v[48:49], v[76:77]
	v_pk_mul_f32 v[44:45], v[44:45], v[80:81]
	v_pk_mul_f32 v[40:41], v[40:41], v[84:85]
	v_pk_mul_f32 v[36:37], v[36:37], v[88:89]
	v_pk_mul_f32 v[34:35], v[34:35], v[86:87]
	v_pk_mul_f32 v[14:15], v[14:15], v[74:75]
	v_pk_mul_f32 v[10:11], v[10:11], v[78:79]
	v_pk_mul_f32 v[6:7], v[6:7], v[82:83]
	v_pk_mul_f32 v[16:17], v[16:17], v[76:77]
	v_pk_mul_f32 v[12:13], v[12:13], v[80:81]
	v_pk_mul_f32 v[8:9], v[8:9], v[84:85]
	v_pk_mul_f32 v[4:5], v[4:5], v[88:89]
	v_pk_mul_f32 v[2:3], v[2:3], v[86:87]
.LBB0_1312:
	s_add_i32 s27, s29, 0x4000
	s_cmpk_lg_u32 s29, 0x8000
	s_cselect_b32 s27, s27, 0
	v_mfma_f32_32x32x16_bf16 v[82:97], v[70:73], v[150:153], 0
	v_add_f32_e32 v74, v114, v115
	v_add_f32_e32 v74, v116, v74
	v_add_f32_e32 v74, v117, v74
	v_add_f32_e32 v74, v118, v74
	v_add_u32_e32 v247, s91, v246
	v_add_f32_e32 v74, v119, v74
	v_cvt_pk_bf16_f32 v158, v114, v115
	v_cvt_pk_bf16_f32 v159, v116, v117
	s_nop 0
	v_add_f32_e32 v70, v120, v74
	v_add_f32_e32 v70, v121, v70
	v_add_f32_e32 v70, v122, v70
	v_add_f32_e32 v114, v123, v70
	v_mfma_f32_32x32x16_bf16 v[66:81], v[66:69], v[150:153], 0
	v_cvt_pk_bf16_f32 v160, v118, v119
	v_cvt_pk_bf16_f32 v161, v120, v121
	v_mfma_f32_32x32x16_bf16 v[82:97], v[182:185], v[146:149], v[82:97]
	v_add_f32_e32 v114, v124, v114
	v_add_f32_e32 v114, v125, v114
	v_add_f32_e32 v114, v126, v114
	v_add_f32_e32 v114, v127, v114
	v_cvt_pk_bf16_f32 v154, v122, v123
	v_cvt_pk_bf16_f32 v155, v124, v125
	v_mfma_f32_32x32x16_bf16 v[66:81], v[174:177], v[146:149], v[66:81]
	v_add_f32_e32 v114, v128, v114
	v_add_f32_e32 v114, v129, v114
	v_add_f32_e32 v114, v98, v114
	v_add_f32_e32 v118, v99, v114
	v_cvt_pk_bf16_f32 v156, v126, v127
	v_cvt_pk_bf16_f32 v157, v128, v129
	ds_read_b64_tr_b16 v[114:115], v247 offset:49152
	ds_read_b64_tr_b16 v[116:117], v247 offset:49664
	v_mfma_f32_32x32x16_bf16 v[82:97], v[178:181], v[142:145], v[82:97]
	v_add_f32_e32 v118, v100, v118
	v_add_f32_e32 v118, v101, v118
	v_add_f32_e32 v118, v102, v118
	v_add_f32_e32 v118, v103, v118
	v_cvt_pk_bf16_f32 v138, v98, v99
	v_cvt_pk_bf16_f32 v139, v100, v101
	ds_read_b64_tr_b16 v[98:99], v247 offset:50176
	ds_read_b64_tr_b16 v[100:101], v247 offset:50688
	v_mfma_f32_32x32x16_bf16 v[66:81], v[166:169], v[142:145], v[66:81]
	v_add_f32_e32 v118, v104, v118
	v_add_f32_e32 v118, v105, v118
	v_add_f32_e32 v118, v106, v118
	v_add_f32_e32 v118, v107, v118
	v_cvt_pk_bf16_f32 v140, v102, v103
	v_cvt_pk_bf16_f32 v141, v104, v105
	ds_read_b64_tr_b16 v[102:103], v247 offset:51200
	ds_read_b64_tr_b16 v[104:105], v247 offset:51712
	v_mfma_f32_32x32x16_bf16 v[82:97], v[170:173], v[134:137], v[82:97]
	v_add_f32_e32 v118, v108, v118
	v_add_f32_e32 v118, v109, v118
	v_add_f32_e32 v118, v110, v118
	v_add_f32_e32 v118, v111, v118
	v_cvt_pk_bf16_f32 v130, v106, v107
	v_cvt_pk_bf16_f32 v131, v108, v109
	ds_read_b64_tr_b16 v[106:107], v247 offset:52224
	ds_read_b64_tr_b16 v[108:109], v247 offset:52736
	v_mfma_f32_32x32x16_bf16 v[66:81], v[162:165], v[134:137], v[66:81]
	v_add_f32_e32 v118, v112, v118
	v_add_f32_e32 v118, v113, v118
	v_add_f32_e32 v118, 0, v118
	v_cvt_pk_bf16_f32 v132, v110, v111
	v_cvt_pk_bf16_f32 v133, v112, v113
	s_mov_b64 s[30:31], 0x1dd40000
	v_lshl_add_u64 v[110:111], v[188:189], 0, s[30:31]
	s_add_i32 s36, s29, s25
	s_mov_b32 s30, m0
	s_mov_b32 m0, s36
	s_nop 0
	global_load_lds_dwordx4 v[110:111], off
	s_mov_b32 m0, s30
	s_mov_b64 s[30:31], 0x1dd40080
	v_lshl_add_u64 v[110:111], v[188:189], 0, s[30:31]
	s_add_i32 s30, s36, 0x2000
	s_mov_b32 s31, m0
	s_mov_b32 m0, s30
	s_nop 0
	global_load_lds_dwordx4 v[110:111], off
	s_mov_b32 m0, s31
	s_mov_b64 s[30:31], 0x25cc0000
	v_lshl_add_u64 v[110:111], v[186:187], 0, s[30:31]
	s_add_i32 s36, s27, s24
	s_mov_b32 s30, m0
	s_mov_b32 m0, s36
	s_nop 0
	global_load_lds_dwordx4 v[110:111], off
	s_mov_b32 m0, s30
	s_mov_b64 s[30:31], 0x25cc0080
	v_lshl_add_u64 v[110:111], v[186:187], 0, s[30:31]
	s_add_i32 s30, s36, 0x2000
	s_mov_b32 s31, m0
	s_mov_b32 m0, s30
	s_nop 0
	global_load_lds_dwordx4 v[110:111], off
	s_mov_b32 m0, s31
	v_max_f32_e32 v110, v83, v83
	v_max_f32_e32 v111, v82, v82
	v_max_f32_e32 v110, v111, v110
	v_max3_f32 v111, v84, v85, v67
	v_max3_f32 v110, v110, v66, v68
	v_max3_f32 v110, v110, v69, v86
	v_max3_f32 v111, v111, v88, v89
	v_max3_f32 v110, v110, v87, v70
	v_max3_f32 v111, v111, v72, v73
	v_max3_f32 v110, v110, v71, v90
	v_max3_f32 v111, v111, v92, v93
	v_max3_f32 v110, v110, v91, v74
	v_max3_f32 v111, v111, v76, v77
	v_max3_f32 v110, v110, v75, v94
	v_max3_f32 v111, v111, v96, v97
	v_max3_f32 v110, v110, v95, v78
	v_max3_f32 v111, v111, v80, v81
	v_max3_f32 v110, v110, v79, v111
	v_mov_b32_e32 v111, v110
	s_nop 1
	v_permlane32_swap_b32_e32 v110, v111
	v_max_f32_e32 v111, v111, v111
	v_max_f32_e32 v110, v110, v110
	v_max_f32_e32 v110, v110, v111
	v_sub_f32_e32 v110, v110, v243
	v_cmp_lt_f32_e32 vcc, s93, v110
	s_cmp_lg_u64 vcc, 0
	v_add_f32_e32 v250, v190, v118
	s_cselect_b64 s[36:37], -1, 0
	s_cbranch_vccnz .LBB0_1320
.LBB0_1313:
	s_waitcnt lgkmcnt(6)
	v_mfma_f32_32x32x16_bf16 v[18:33], v[158:161], v[114:117], v[18:33]
	v_sub_f32_e32 v82, v82, v243
	v_sub_f32_e32 v83, v83, v243
	v_exp_f32_e32 v82, v82
	v_exp_f32_e32 v83, v83
	ds_read_b64_tr_b16 v[110:111], v247 offset:53248
	ds_read_b64_tr_b16 v[112:113], v247 offset:53760
	s_waitcnt lgkmcnt(6)
	v_mfma_f32_32x32x16_bf16 v[18:33], v[154:157], v[98:101], v[18:33]
	v_sub_f32_e32 v84, v84, v243
	v_sub_f32_e32 v85, v85, v243
	v_exp_f32_e32 v84, v84
	v_exp_f32_e32 v85, v85
	ds_read_b64_tr_b16 v[98:99], v247 offset:54272
	ds_read_b64_tr_b16 v[100:101], v247 offset:54784
	s_waitcnt lgkmcnt(6)
	v_mfma_f32_32x32x16_bf16 v[18:33], v[138:141], v[102:105], v[18:33]
	v_sub_f32_e32 v86, v86, v243
	v_sub_f32_e32 v87, v87, v243
	v_exp_f32_e32 v86, v86
	v_exp_f32_e32 v87, v87
	ds_read_b64_tr_b16 v[102:103], v247 offset:55296
	ds_read_b64_tr_b16 v[104:105], v247 offset:55808
	s_waitcnt lgkmcnt(6)
	v_mfma_f32_32x32x16_bf16 v[18:33], v[130:133], v[106:109], v[18:33]
	v_sub_f32_e32 v88, v88, v243
	v_sub_f32_e32 v89, v89, v243
	v_exp_f32_e32 v88, v88
	v_exp_f32_e32 v89, v89
	ds_read_b64_tr_b16 v[106:107], v247 offset:56320
	ds_read_b64_tr_b16 v[108:109], v247 offset:56832
	s_waitcnt lgkmcnt(6)
	v_mfma_f32_32x32x16_bf16 v[50:65], v[158:161], v[110:113], v[50:65]
	v_sub_f32_e32 v90, v90, v243
	v_sub_f32_e32 v91, v91, v243
	v_exp_f32_e32 v90, v90
	v_exp_f32_e32 v91, v91
	ds_read_b64_tr_b16 v[110:111], v247 offset:57344
	ds_read_b64_tr_b16 v[112:113], v247 offset:57856
	s_waitcnt lgkmcnt(6)
	v_mfma_f32_32x32x16_bf16 v[50:65], v[154:157], v[98:101], v[50:65]
	v_sub_f32_e32 v92, v92, v243
	v_sub_f32_e32 v93, v93, v243
	v_exp_f32_e32 v92, v92
	v_exp_f32_e32 v93, v93
	ds_read_b64_tr_b16 v[98:99], v247 offset:58368
	ds_read_b64_tr_b16 v[100:101], v247 offset:58880
	s_waitcnt lgkmcnt(6)
	v_mfma_f32_32x32x16_bf16 v[50:65], v[138:141], v[102:105], v[50:65]
	v_sub_f32_e32 v94, v94, v243
	v_sub_f32_e32 v95, v95, v243
	v_exp_f32_e32 v94, v94
	v_exp_f32_e32 v95, v95
	ds_read_b64_tr_b16 v[102:103], v247 offset:59392
	ds_read_b64_tr_b16 v[104:105], v247 offset:59904
	s_waitcnt lgkmcnt(6)
	v_mfma_f32_32x32x16_bf16 v[50:65], v[130:133], v[106:109], v[50:65]
	v_sub_f32_e32 v96, v96, v243
	v_sub_f32_e32 v97, v97, v243
	v_exp_f32_e32 v96, v96
	v_exp_f32_e32 v97, v97
	ds_read_b64_tr_b16 v[106:107], v247 offset:60416
	ds_read_b64_tr_b16 v[108:109], v247 offset:60928
	v_add_u32_e32 v114, s27, v245
	ds_read_b128 v[190:193], v114
	ds_read_b128 v[182:185], v114 offset:512
	s_waitcnt lgkmcnt(8)
	v_mfma_f32_32x32x16_bf16 v[34:49], v[158:161], v[110:113], v[34:49]
	v_sub_f32_e32 v66, v66, v243
	v_sub_f32_e32 v67, v67, v243
	v_exp_f32_e32 v66, v66
	v_exp_f32_e32 v67, v67
	ds_read_b64_tr_b16 v[110:111], v247 offset:61440
	ds_read_b64_tr_b16 v[112:113], v247 offset:61952
	ds_read_b128 v[186:189], v114 offset:2048
	ds_read_b128 v[178:181], v114 offset:2560
	s_waitcnt lgkmcnt(10)
	v_mfma_f32_32x32x16_bf16 v[34:49], v[154:157], v[98:101], v[34:49]
	v_sub_f32_e32 v68, v68, v243
	v_sub_f32_e32 v69, v69, v243
	v_exp_f32_e32 v68, v68
	v_exp_f32_e32 v69, v69
	ds_read_b64_tr_b16 v[98:99], v247 offset:62464
	ds_read_b64_tr_b16 v[100:101], v247 offset:62976
	ds_read_b128 v[174:177], v114 offset:4096
	ds_read_b128 v[170:173], v114 offset:4608
	s_waitcnt lgkmcnt(12)
	v_mfma_f32_32x32x16_bf16 v[34:49], v[138:141], v[102:105], v[34:49]
	v_sub_f32_e32 v70, v70, v243
	v_sub_f32_e32 v71, v71, v243
	v_exp_f32_e32 v70, v70
	v_exp_f32_e32 v71, v71
	ds_read_b64_tr_b16 v[102:103], v247 offset:63488
	ds_read_b64_tr_b16 v[104:105], v247 offset:64000
	ds_read_b128 v[166:169], v114 offset:6144
	ds_read_b128 v[162:165], v114 offset:6656
	s_waitcnt lgkmcnt(14)
	v_mfma_f32_32x32x16_bf16 v[34:49], v[130:133], v[106:109], v[34:49]
	v_sub_f32_e32 v72, v72, v243
	v_sub_f32_e32 v73, v73, v243
	v_exp_f32_e32 v72, v72
	v_exp_f32_e32 v73, v73
	ds_read_b64_tr_b16 v[106:107], v247 offset:64512
	ds_read_b64_tr_b16 v[108:109], v247 offset:65024
	s_waitcnt lgkmcnt(12)
	v_mfma_f32_32x32x16_bf16 v[2:17], v[158:161], v[110:113], v[2:17]
	v_sub_f32_e32 v74, v74, v243
	v_sub_f32_e32 v75, v75, v243
	v_exp_f32_e32 v74, v74
	v_exp_f32_e32 v75, v75
	s_waitcnt lgkmcnt(8)
	v_mfma_f32_32x32x16_bf16 v[2:17], v[154:157], v[98:101], v[2:17]
	v_sub_f32_e32 v76, v76, v243
	v_sub_f32_e32 v77, v77, v243
	v_exp_f32_e32 v76, v76
	v_exp_f32_e32 v77, v77
	s_waitcnt lgkmcnt(4)
	v_mfma_f32_32x32x16_bf16 v[2:17], v[138:141], v[102:105], v[2:17]
	v_sub_f32_e32 v78, v78, v243
	v_sub_f32_e32 v79, v79, v243
	v_exp_f32_e32 v78, v78
	v_exp_f32_e32 v79, v79
	s_waitcnt lgkmcnt(0)
	v_mfma_f32_32x32x16_bf16 v[2:17], v[130:133], v[106:109], v[2:17]
	v_sub_f32_e32 v80, v80, v243
	v_sub_f32_e32 v81, v81, v243
	v_exp_f32_e32 v80, v80
	v_exp_f32_e32 v81, v81
	s_waitcnt vmcnt(4) lgkmcnt(0)
	s_barrier
	s_andn2_b64 vcc, exec, s[36:37]
	s_cbranch_vccnz .LBB0_1315
	s_waitcnt lgkmcnt(0)
	ds_read_b128 v[98:101], v213 offset:96
	ds_read_b128 v[102:105], v213 offset:64
	ds_read_b128 v[106:109], v213 offset:32
	ds_read_b128 v[110:113], v213
	s_waitcnt lgkmcnt(3)
	v_pk_mul_f32 v[30:31], v[30:31], v[98:99]
	s_waitcnt lgkmcnt(2)
	v_pk_mul_f32 v[26:27], v[26:27], v[102:103]
	s_waitcnt lgkmcnt(1)
	v_pk_mul_f32 v[22:23], v[22:23], v[106:107]
	v_pk_mul_f32 v[32:33], v[32:33], v[100:101]
	v_pk_mul_f32 v[28:29], v[28:29], v[104:105]
	v_pk_mul_f32 v[24:25], v[24:25], v[108:109]
	s_waitcnt lgkmcnt(0)
	v_pk_mul_f32 v[20:21], v[20:21], v[112:113]
	v_pk_mul_f32 v[18:19], v[18:19], v[110:111]
	v_pk_mul_f32 v[62:63], v[62:63], v[98:99]
	v_pk_mul_f32 v[58:59], v[58:59], v[102:103]
	v_pk_mul_f32 v[54:55], v[54:55], v[106:107]
	v_pk_mul_f32 v[64:65], v[64:65], v[100:101]
	v_pk_mul_f32 v[60:61], v[60:61], v[104:105]
	v_pk_mul_f32 v[56:57], v[56:57], v[108:109]
	v_pk_mul_f32 v[52:53], v[52:53], v[112:113]
	v_pk_mul_f32 v[50:51], v[50:51], v[110:111]
	v_pk_mul_f32 v[46:47], v[46:47], v[98:99]
	v_pk_mul_f32 v[42:43], v[42:43], v[102:103]
	v_pk_mul_f32 v[38:39], v[38:39], v[106:107]
	v_pk_mul_f32 v[48:49], v[48:49], v[100:101]
	v_pk_mul_f32 v[44:45], v[44:45], v[104:105]
	v_pk_mul_f32 v[40:41], v[40:41], v[108:109]
	v_pk_mul_f32 v[36:37], v[36:37], v[112:113]
	v_pk_mul_f32 v[34:35], v[34:35], v[110:111]
	v_pk_mul_f32 v[14:15], v[14:15], v[98:99]
	v_pk_mul_f32 v[10:11], v[10:11], v[102:103]
	v_pk_mul_f32 v[6:7], v[6:7], v[106:107]
	v_pk_mul_f32 v[16:17], v[16:17], v[100:101]
	v_pk_mul_f32 v[12:13], v[12:13], v[104:105]
	v_pk_mul_f32 v[8:9], v[8:9], v[108:109]
	v_pk_mul_f32 v[4:5], v[4:5], v[112:113]
	v_pk_mul_f32 v[2:3], v[2:3], v[110:111]

.LBB0_1465:
	s_add_u32 s27, s88, 0xfff80080
	s_addc_u32 s28, s89, -1
	s_add_i32 s29, 0, 0x10000
	s_cmp_eq_u32 s26, 28
	s_cselect_b32 s91, s20, s28
	s_cselect_b32 s90, s21, s27
	v_add_u32_e32 v140, s29, v143
	s_cselect_b32 s55, s22, s25
	s_cselect_b32 s54, s23, s24
	s_add_i32 s27, 0, 0x14000
	ds_read_b128 v[146:149], v140
	ds_read_b128 v[150:153], v140 offset:1024
	ds_read_b128 v[154:157], v140 offset:2048
	ds_read_b128 v[158:161], v140 offset:3072
	v_add_u32_e32 v140, s27, v143
	ds_read_b128 v[162:165], v140
	ds_read_b128 v[166:169], v140 offset:1024
	ds_read_b128 v[170:173], v140 offset:2048
	ds_read_b128 v[174:177], v140 offset:3072
	v_lshl_add_u64 v[140:141], s[88:89], 0, v[138:139]
	s_add_i32 m0, s12, 0xc000
	ds_read_b128 v[178:181], v145
	ds_read_b128 v[182:185], v145 offset:1024
	ds_read_b128 v[186:189], v145 offset:2048
	ds_read_b128 v[190:193], v145 offset:3072
	ds_read_b128 v[210:213], v145 offset:4096
	ds_read_b128 v[214:217], v145 offset:5120
	ds_read_b128 v[230:233], v145 offset:6144
	ds_read_b128 v[234:237], v145 offset:7168
	global_load_lds_dwordx4 v[140:141], off
	v_lshl_add_u64 v[140:141], s[88:89], 0, v[136:137]
	s_add_i32 m0, s12, 0xe000
	s_nop 0
	global_load_lds_dwordx4 v[140:141], off
	s_waitcnt vmcnt(8)
	s_waitcnt lgkmcnt(0)
	s_barrier
	s_setprio 1
	s_waitcnt lgkmcnt(0)
	v_mfma_f32_16x16x32_bf16 v[126:129], v[146:149], v[178:181], v[126:129]
	v_mfma_f32_16x16x32_bf16 v[126:129], v[150:153], v[182:185], v[126:129]
	v_mfma_f32_16x16x32_bf16 v[118:121], v[146:149], v[186:189], v[118:121]
	v_mfma_f32_16x16x32_bf16 v[118:121], v[150:153], v[190:193], v[118:121]
	v_mfma_f32_16x16x32_bf16 v[102:105], v[146:149], v[210:213], v[102:105]
	v_mfma_f32_16x16x32_bf16 v[102:105], v[150:153], v[214:217], v[102:105]
	v_mfma_f32_16x16x32_bf16 v[86:89], v[146:149], v[230:233], v[86:89]
	v_mfma_f32_16x16x32_bf16 v[86:89], v[150:153], v[234:237], v[86:89]
	v_mfma_f32_16x16x32_bf16 v[78:81], v[154:157], v[230:233], v[78:81]
	v_mfma_f32_16x16x32_bf16 v[78:81], v[158:161], v[234:237], v[78:81]
	v_mfma_f32_16x16x32_bf16 v[94:97], v[154:157], v[210:213], v[94:97]
	v_mfma_f32_16x16x32_bf16 v[94:97], v[158:161], v[214:217], v[94:97]
	v_mfma_f32_16x16x32_bf16 v[110:113], v[154:157], v[186:189], v[110:113]
	v_mfma_f32_16x16x32_bf16 v[110:113], v[158:161], v[190:193], v[110:113]
	v_mfma_f32_16x16x32_bf16 v[122:125], v[154:157], v[178:181], v[122:125]
	v_mfma_f32_16x16x32_bf16 v[122:125], v[158:161], v[182:185], v[122:125]
	s_setprio 0
	s_setprio 1
	v_mfma_f32_16x16x32_bf16 v[114:117], v[162:165], v[178:181], v[114:117]
	v_mfma_f32_16x16x32_bf16 v[114:117], v[166:169], v[182:185], v[114:117]
	v_mfma_f32_16x16x32_bf16 v[98:101], v[162:165], v[186:189], v[98:101]
	v_mfma_f32_16x16x32_bf16 v[98:101], v[166:169], v[190:193], v[98:101]
	v_mfma_f32_16x16x32_bf16 v[82:85], v[162:165], v[210:213], v[82:85]
	v_mfma_f32_16x16x32_bf16 v[82:85], v[166:169], v[214:217], v[82:85]
	v_mfma_f32_16x16x32_bf16 v[70:73], v[162:165], v[230:233], v[70:73]
	v_mfma_f32_16x16x32_bf16 v[70:73], v[166:169], v[234:237], v[70:73]
	v_mfma_f32_16x16x32_bf16 v[66:69], v[170:173], v[230:233], v[66:69]
	v_mfma_f32_16x16x32_bf16 v[66:69], v[174:177], v[234:237], v[66:69]
	v_mfma_f32_16x16x32_bf16 v[74:77], v[170:173], v[210:213], v[74:77]
	v_mfma_f32_16x16x32_bf16 v[74:77], v[174:177], v[214:217], v[74:77]
	v_mfma_f32_16x16x32_bf16 v[90:93], v[170:173], v[186:189], v[90:93]
	v_mfma_f32_16x16x32_bf16 v[90:93], v[174:177], v[190:193], v[90:93]
	v_mfma_f32_16x16x32_bf16 v[106:109], v[170:173], v[178:181], v[106:109]
	v_mfma_f32_16x16x32_bf16 v[106:109], v[174:177], v[182:185], v[106:109]
	s_setprio 0
	s_barrier
	s_add_i32 s28, s29, s11
	v_lshl_add_u64 v[140:141], s[54:55], 0, v[194:195]
	s_mov_b32 m0, s28
	ds_read_b128 v[178:181], v145 offset:16384
	ds_read_b128 v[182:185], v145 offset:17408
	ds_read_b128 v[186:189], v145 offset:18432
	ds_read_b128 v[190:193], v145 offset:19456
	ds_read_b128 v[210:213], v145 offset:20480
	ds_read_b128 v[214:217], v145 offset:21504
	ds_read_b128 v[230:233], v145 offset:22528
	ds_read_b128 v[234:237], v145 offset:23552
	global_load_lds_dwordx4 v[140:141], off
	s_add_i32 m0, s28, 0x2000
	s_add_u32 s28, s54, 0x80000
	v_lshl_add_u64 v[218:219], s[54:55], 0, v[134:135]
	s_addc_u32 s29, s55, 0
	s_add_i32 s27, s27, s11
	global_load_lds_dwordx4 v[218:219], off
	v_lshl_add_u64 v[238:239], s[28:29], 0, v[194:195]
	s_mov_b32 m0, s27
	v_lshl_add_u64 v[240:241], s[90:91], 0, v[132:133]
	global_load_lds_dwordx4 v[238:239], off
	v_lshl_add_u64 v[238:239], s[28:29], 0, v[134:135]
	s_add_i32 m0, s27, 0x2000
	s_nop 0
	global_load_lds_dwordx4 v[238:239], off
	v_lshl_add_u64 v[238:239], s[90:91], 0, v[130:131]
	s_mov_b32 m0, s12
	s_nop 0
	global_load_lds_dwordx4 v[238:239], off
	s_mov_b32 m0, s13
	s_nop 0
	global_load_lds_dwordx4 v[240:241], off
	s_waitcnt vmcnt(8)
	s_waitcnt lgkmcnt(0)
	s_barrier
	s_setprio 1
	s_waitcnt lgkmcnt(0)
	v_mfma_f32_16x16x32_bf16 v[62:65], v[146:149], v[178:181], v[62:65]
	v_mfma_f32_16x16x32_bf16 v[62:65], v[150:153], v[182:185], v[62:65]
	v_mfma_f32_16x16x32_bf16 v[54:57], v[146:149], v[186:189], v[54:57]
	v_mfma_f32_16x16x32_bf16 v[54:57], v[150:153], v[190:193], v[54:57]
	v_mfma_f32_16x16x32_bf16 v[38:41], v[146:149], v[210:213], v[38:41]
	v_mfma_f32_16x16x32_bf16 v[38:41], v[150:153], v[214:217], v[38:41]
	v_mfma_f32_16x16x32_bf16 v[22:25], v[146:149], v[230:233], v[22:25]
	v_mfma_f32_16x16x32_bf16 v[22:25], v[150:153], v[234:237], v[22:25]
	v_mfma_f32_16x16x32_bf16 v[14:17], v[154:157], v[230:233], v[14:17]
	v_mfma_f32_16x16x32_bf16 v[14:17], v[158:161], v[234:237], v[14:17]
	v_mfma_f32_16x16x32_bf16 v[30:33], v[154:157], v[210:213], v[30:33]
	v_mfma_f32_16x16x32_bf16 v[30:33], v[158:161], v[214:217], v[30:33]
	v_mfma_f32_16x16x32_bf16 v[46:49], v[154:157], v[186:189], v[46:49]
	v_mfma_f32_16x16x32_bf16 v[46:49], v[158:161], v[190:193], v[46:49]
	v_mfma_f32_16x16x32_bf16 v[58:61], v[154:157], v[178:181], v[58:61]
	v_mfma_f32_16x16x32_bf16 v[58:61], v[158:161], v[182:185], v[58:61]
	s_setprio 0
	s_setprio 1
	v_mfma_f32_16x16x32_bf16 v[50:53], v[162:165], v[178:181], v[50:53]
	v_mfma_f32_16x16x32_bf16 v[50:53], v[166:169], v[182:185], v[50:53]
	v_mfma_f32_16x16x32_bf16 v[34:37], v[162:165], v[186:189], v[34:37]
	v_mfma_f32_16x16x32_bf16 v[34:37], v[166:169], v[190:193], v[34:37]
	v_mfma_f32_16x16x32_bf16 v[18:21], v[162:165], v[210:213], v[18:21]
	v_mfma_f32_16x16x32_bf16 v[18:21], v[166:169], v[214:217], v[18:21]
	v_mfma_f32_16x16x32_bf16 v[6:9], v[162:165], v[230:233], v[6:9]
	v_mfma_f32_16x16x32_bf16 v[6:9], v[166:169], v[234:237], v[6:9]
	v_mfma_f32_16x16x32_bf16 v[2:5], v[170:173], v[230:233], v[2:5]
	v_mfma_f32_16x16x32_bf16 v[2:5], v[174:177], v[234:237], v[2:5]
	v_mfma_f32_16x16x32_bf16 v[10:13], v[170:173], v[210:213], v[10:13]
	v_mfma_f32_16x16x32_bf16 v[10:13], v[174:177], v[214:217], v[10:13]
	v_mfma_f32_16x16x32_bf16 v[26:29], v[170:173], v[186:189], v[26:29]
	v_mfma_f32_16x16x32_bf16 v[26:29], v[174:177], v[190:193], v[26:29]
	v_mfma_f32_16x16x32_bf16 v[42:45], v[170:173], v[178:181], v[42:45]
	v_mfma_f32_16x16x32_bf16 v[42:45], v[174:177], v[182:185], v[42:45]
	s_setprio 0
	s_barrier
	s_add_i32 s27, 0, 0x18000
	s_add_i32 s30, 0, 0x1c000
	v_add_u32_e32 v158, s27, v143
	v_add_u32_e32 v174, s30, v143
	ds_read_b128 v[146:149], v158
	ds_read_b128 v[150:153], v158 offset:1024
	ds_read_b128 v[154:157], v158 offset:2048
	ds_read_b128 v[158:161], v158 offset:3072
	ds_read_b128 v[162:165], v174
	ds_read_b128 v[166:169], v174 offset:1024
	ds_read_b128 v[170:173], v174 offset:2048
	ds_read_b128 v[174:177], v174 offset:3072
	s_add_u32 s28, s90, 0x80000
	s_addc_u32 s29, s91, 0
	s_mov_b32 m0, s14
	v_lshl_add_u64 v[242:243], s[28:29], 0, v[130:131]
	ds_read_b128 v[178:181], v145 offset:32768
	ds_read_b128 v[182:185], v145 offset:33792
	ds_read_b128 v[186:189], v145 offset:34816
	ds_read_b128 v[190:193], v145 offset:35840
	ds_read_b128 v[210:213], v145 offset:36864
	ds_read_b128 v[214:217], v145 offset:37888
	ds_read_b128 v[230:233], v145 offset:38912
	ds_read_b128 v[234:237], v145 offset:39936
	global_load_lds_dwordx4 v[242:243], off
	v_lshl_add_u64 v[242:243], s[28:29], 0, v[132:133]
	s_mov_b32 m0, s15
	s_nop 0
	global_load_lds_dwordx4 v[242:243], off
	s_waitcnt vmcnt(8)
	s_waitcnt lgkmcnt(0)
	s_barrier
	s_setprio 1
	s_waitcnt lgkmcnt(0)
	v_mfma_f32_16x16x32_bf16 v[126:129], v[146:149], v[178:181], v[126:129]
	v_mfma_f32_16x16x32_bf16 v[126:129], v[150:153], v[182:185], v[126:129]
	v_mfma_f32_16x16x32_bf16 v[118:121], v[146:149], v[186:189], v[118:121]
	v_mfma_f32_16x16x32_bf16 v[118:121], v[150:153], v[190:193], v[118:121]
	v_mfma_f32_16x16x32_bf16 v[102:105], v[146:149], v[210:213], v[102:105]
	v_mfma_f32_16x16x32_bf16 v[102:105], v[150:153], v[214:217], v[102:105]
	v_mfma_f32_16x16x32_bf16 v[86:89], v[146:149], v[230:233], v[86:89]
	v_mfma_f32_16x16x32_bf16 v[86:89], v[150:153], v[234:237], v[86:89]
	v_mfma_f32_16x16x32_bf16 v[78:81], v[154:157], v[230:233], v[78:81]
	v_mfma_f32_16x16x32_bf16 v[78:81], v[158:161], v[234:237], v[78:81]
	v_mfma_f32_16x16x32_bf16 v[94:97], v[154:157], v[210:213], v[94:97]
	v_mfma_f32_16x16x32_bf16 v[94:97], v[158:161], v[214:217], v[94:97]
	v_mfma_f32_16x16x32_bf16 v[110:113], v[154:157], v[186:189], v[110:113]
	v_mfma_f32_16x16x32_bf16 v[110:113], v[158:161], v[190:193], v[110:113]
	v_mfma_f32_16x16x32_bf16 v[122:125], v[154:157], v[178:181], v[122:125]
	v_mfma_f32_16x16x32_bf16 v[122:125], v[158:161], v[182:185], v[122:125]
	s_setprio 0
	s_setprio 1
	v_mfma_f32_16x16x32_bf16 v[114:117], v[162:165], v[178:181], v[114:117]
	v_mfma_f32_16x16x32_bf16 v[114:117], v[166:169], v[182:185], v[114:117]
	v_mfma_f32_16x16x32_bf16 v[98:101], v[162:165], v[186:189], v[98:101]
	v_mfma_f32_16x16x32_bf16 v[98:101], v[166:169], v[190:193], v[98:101]
	v_mfma_f32_16x16x32_bf16 v[82:85], v[162:165], v[210:213], v[82:85]
	v_mfma_f32_16x16x32_bf16 v[82:85], v[166:169], v[214:217], v[82:85]
	v_mfma_f32_16x16x32_bf16 v[70:73], v[162:165], v[230:233], v[70:73]
	v_mfma_f32_16x16x32_bf16 v[70:73], v[166:169], v[234:237], v[70:73]
	v_mfma_f32_16x16x32_bf16 v[66:69], v[170:173], v[230:233], v[66:69]
	v_mfma_f32_16x16x32_bf16 v[66:69], v[174:177], v[234:237], v[66:69]
	v_mfma_f32_16x16x32_bf16 v[74:77], v[170:173], v[210:213], v[74:77]
	v_mfma_f32_16x16x32_bf16 v[74:77], v[174:177], v[214:217], v[74:77]
	v_mfma_f32_16x16x32_bf16 v[90:93], v[170:173], v[186:189], v[90:93]
	v_mfma_f32_16x16x32_bf16 v[90:93], v[174:177], v[190:193], v[90:93]
	v_mfma_f32_16x16x32_bf16 v[106:109], v[170:173], v[178:181], v[106:109]
	v_mfma_f32_16x16x32_bf16 v[106:109], v[174:177], v[182:185], v[106:109]
	s_setprio 0
	s_barrier
	s_add_i32 s27, s27, s11
	v_lshl_add_u64 v[140:141], v[140:141], 0, s[56:57]
	s_mov_b32 m0, s27
	ds_read_b128 v[178:181], v145 offset:49152
	ds_read_b128 v[182:185], v145 offset:50176
	ds_read_b128 v[186:189], v145 offset:51200
	ds_read_b128 v[190:193], v145 offset:52224
	ds_read_b128 v[210:213], v145 offset:53248
	ds_read_b128 v[214:217], v145 offset:54272
	ds_read_b128 v[230:233], v145 offset:55296
	ds_read_b128 v[234:237], v145 offset:56320
	global_load_lds_dwordx4 v[140:141], off
	s_add_i32 m0, s27, 0x2000
	s_add_u32 s28, s54, 0x80080
	v_lshl_add_u64 v[140:141], v[218:219], 0, s[56:57]
	s_addc_u32 s29, s55, 0
	s_add_i32 s27, s30, s11
	global_load_lds_dwordx4 v[140:141], off
	v_lshl_add_u64 v[140:141], s[28:29], 0, v[194:195]
	s_mov_b32 m0, s27
	s_nop 0
	global_load_lds_dwordx4 v[140:141], off
	v_lshl_add_u64 v[140:141], s[28:29], 0, v[134:135]
	s_add_i32 m0, s27, 0x2000
	s_nop 0
	global_load_lds_dwordx4 v[140:141], off
	v_lshl_add_u64 v[140:141], v[238:239], 0, s[56:57]
	s_mov_b32 m0, s16
	s_nop 0
	global_load_lds_dwordx4 v[140:141], off
	v_lshl_add_u64 v[140:141], v[240:241], 0, s[56:57]
	s_mov_b32 m0, s17
	s_nop 0
	global_load_lds_dwordx4 v[140:141], off
	s_waitcnt vmcnt(8)
	s_waitcnt lgkmcnt(0)
	s_barrier
	s_setprio 1
	s_waitcnt lgkmcnt(0)
	v_mfma_f32_16x16x32_bf16 v[62:65], v[146:149], v[178:181], v[62:65]
	v_mfma_f32_16x16x32_bf16 v[62:65], v[150:153], v[182:185], v[62:65]
	v_mfma_f32_16x16x32_bf16 v[54:57], v[146:149], v[186:189], v[54:57]
	v_mfma_f32_16x16x32_bf16 v[54:57], v[150:153], v[190:193], v[54:57]
	v_mfma_f32_16x16x32_bf16 v[38:41], v[146:149], v[210:213], v[38:41]
	v_mfma_f32_16x16x32_bf16 v[38:41], v[150:153], v[214:217], v[38:41]
	v_mfma_f32_16x16x32_bf16 v[22:25], v[146:149], v[230:233], v[22:25]
	v_mfma_f32_16x16x32_bf16 v[22:25], v[150:153], v[234:237], v[22:25]
	v_mfma_f32_16x16x32_bf16 v[14:17], v[154:157], v[230:233], v[14:17]
	v_mfma_f32_16x16x32_bf16 v[14:17], v[158:161], v[234:237], v[14:17]
	v_mfma_f32_16x16x32_bf16 v[30:33], v[154:157], v[210:213], v[30:33]
	v_mfma_f32_16x16x32_bf16 v[30:33], v[158:161], v[214:217], v[30:33]
	v_mfma_f32_16x16x32_bf16 v[46:49], v[154:157], v[186:189], v[46:49]
	v_mfma_f32_16x16x32_bf16 v[46:49], v[158:161], v[190:193], v[46:49]
	v_mfma_f32_16x16x32_bf16 v[58:61], v[154:157], v[178:181], v[58:61]
	v_mfma_f32_16x16x32_bf16 v[58:61], v[158:161], v[182:185], v[58:61]
	s_setprio 0
	s_setprio 1
	v_mfma_f32_16x16x32_bf16 v[50:53], v[162:165], v[178:181], v[50:53]
	v_mfma_f32_16x16x32_bf16 v[50:53], v[166:169], v[182:185], v[50:53]
	v_mfma_f32_16x16x32_bf16 v[34:37], v[162:165], v[186:189], v[34:37]
	v_mfma_f32_16x16x32_bf16 v[34:37], v[166:169], v[190:193], v[34:37]
	v_mfma_f32_16x16x32_bf16 v[18:21], v[162:165], v[210:213], v[18:21]
	v_mfma_f32_16x16x32_bf16 v[18:21], v[166:169], v[214:217], v[18:21]
	v_mfma_f32_16x16x32_bf16 v[6:9], v[162:165], v[230:233], v[6:9]
	v_mfma_f32_16x16x32_bf16 v[6:9], v[166:169], v[234:237], v[6:9]
	v_mfma_f32_16x16x32_bf16 v[2:5], v[170:173], v[230:233], v[2:5]
	v_mfma_f32_16x16x32_bf16 v[2:5], v[174:177], v[234:237], v[2:5]
	v_mfma_f32_16x16x32_bf16 v[10:13], v[170:173], v[210:213], v[10:13]
	v_mfma_f32_16x16x32_bf16 v[10:13], v[174:177], v[214:217], v[10:13]
	v_mfma_f32_16x16x32_bf16 v[26:29], v[170:173], v[186:189], v[26:29]
	v_mfma_f32_16x16x32_bf16 v[26:29], v[174:177], v[190:193], v[26:29]
	v_mfma_f32_16x16x32_bf16 v[42:45], v[170:173], v[178:181], v[42:45]
	v_mfma_f32_16x16x32_bf16 v[42:45], v[174:177], v[182:185], v[42:45]
	s_setprio 0
	s_barrier
	s_add_i32 s26, s26, 2
	s_add_u32 s24, s24, 0x100
	s_addc_u32 s25, s25, 0
	s_add_u32 s88, s88, 0x100
	s_addc_u32 s89, s89, 0
	s_cmp_gt_u32 s26, 29
	s_cbranch_scc0 .LBB0_1465
	s_and_b64 vcc, exec, s[44:45]
	s_cbranch_vccz .LBB0_1468
	s_barrier

.LBB0_1609:
	s_add_u32 s29, s90, 0xfff80080
	s_addc_u32 s30, s91, -1
	s_add_i32 s31, 0, 0x10000
	s_cmp_eq_u32 s28, 28
	s_cselect_b32 vcc_hi, s22, s30
	s_cselect_b32 vcc_lo, s23, s29
	v_add_u32_e32 v140, s31, v143
	s_cselect_b32 s55, s24, s27
	s_cselect_b32 s54, s25, s26
	s_add_i32 s29, 0, 0x14000
	ds_read_b128 v[146:149], v140
	ds_read_b128 v[150:153], v140 offset:1024
	ds_read_b128 v[154:157], v140 offset:2048
	ds_read_b128 v[158:161], v140 offset:3072
	v_add_u32_e32 v140, s29, v143
	ds_read_b128 v[162:165], v140
	ds_read_b128 v[166:169], v140 offset:1024
	ds_read_b128 v[170:173], v140 offset:2048
	ds_read_b128 v[174:177], v140 offset:3072
	v_lshl_add_u64 v[140:141], s[90:91], 0, v[138:139]
	s_add_i32 m0, s14, 0xc000
	ds_read_b128 v[178:181], v145
	ds_read_b128 v[182:185], v145 offset:1024
	ds_read_b128 v[186:189], v145 offset:2048
	ds_read_b128 v[190:193], v145 offset:3072
	ds_read_b128 v[210:213], v145 offset:4096
	ds_read_b128 v[214:217], v145 offset:5120
	ds_read_b128 v[230:233], v145 offset:6144
	ds_read_b128 v[234:237], v145 offset:7168
	global_load_lds_dwordx4 v[140:141], off
	v_lshl_add_u64 v[140:141], s[90:91], 0, v[136:137]
	s_add_i32 m0, s14, 0xe000
	s_nop 0
	global_load_lds_dwordx4 v[140:141], off
	s_waitcnt vmcnt(8)
	s_waitcnt lgkmcnt(0)
	s_barrier
	s_setprio 1
	s_waitcnt lgkmcnt(0)
	v_mfma_f32_16x16x32_bf16 v[126:129], v[146:149], v[178:181], v[126:129]
	v_mfma_f32_16x16x32_bf16 v[126:129], v[150:153], v[182:185], v[126:129]
	v_mfma_f32_16x16x32_bf16 v[110:113], v[146:149], v[186:189], v[110:113]
	v_mfma_f32_16x16x32_bf16 v[110:113], v[150:153], v[190:193], v[110:113]
	v_mfma_f32_16x16x32_bf16 v[94:97], v[146:149], v[210:213], v[94:97]
	v_mfma_f32_16x16x32_bf16 v[94:97], v[150:153], v[214:217], v[94:97]
	v_mfma_f32_16x16x32_bf16 v[78:81], v[146:149], v[230:233], v[78:81]
	v_mfma_f32_16x16x32_bf16 v[78:81], v[150:153], v[234:237], v[78:81]
	v_mfma_f32_16x16x32_bf16 v[74:77], v[154:157], v[230:233], v[74:77]
	v_mfma_f32_16x16x32_bf16 v[74:77], v[158:161], v[234:237], v[74:77]
	v_mfma_f32_16x16x32_bf16 v[90:93], v[154:157], v[210:213], v[90:93]
	v_mfma_f32_16x16x32_bf16 v[90:93], v[158:161], v[214:217], v[90:93]
	v_mfma_f32_16x16x32_bf16 v[106:109], v[154:157], v[186:189], v[106:109]
	v_mfma_f32_16x16x32_bf16 v[106:109], v[158:161], v[190:193], v[106:109]
	v_mfma_f32_16x16x32_bf16 v[122:125], v[154:157], v[178:181], v[122:125]
	v_mfma_f32_16x16x32_bf16 v[122:125], v[158:161], v[182:185], v[122:125]
	s_setprio 0
	s_setprio 1
	v_mfma_f32_16x16x32_bf16 v[118:121], v[162:165], v[178:181], v[118:121]
	v_mfma_f32_16x16x32_bf16 v[118:121], v[166:169], v[182:185], v[118:121]
	v_mfma_f32_16x16x32_bf16 v[102:105], v[162:165], v[186:189], v[102:105]
	v_mfma_f32_16x16x32_bf16 v[102:105], v[166:169], v[190:193], v[102:105]
	v_mfma_f32_16x16x32_bf16 v[86:89], v[162:165], v[210:213], v[86:89]
	v_mfma_f32_16x16x32_bf16 v[86:89], v[166:169], v[214:217], v[86:89]
	v_mfma_f32_16x16x32_bf16 v[70:73], v[162:165], v[230:233], v[70:73]
	v_mfma_f32_16x16x32_bf16 v[70:73], v[166:169], v[234:237], v[70:73]
	v_mfma_f32_16x16x32_bf16 v[66:69], v[170:173], v[230:233], v[66:69]
	v_mfma_f32_16x16x32_bf16 v[66:69], v[174:177], v[234:237], v[66:69]
	v_mfma_f32_16x16x32_bf16 v[82:85], v[170:173], v[210:213], v[82:85]
	v_mfma_f32_16x16x32_bf16 v[82:85], v[174:177], v[214:217], v[82:85]
	v_mfma_f32_16x16x32_bf16 v[98:101], v[170:173], v[186:189], v[98:101]
	v_mfma_f32_16x16x32_bf16 v[98:101], v[174:177], v[190:193], v[98:101]
	v_mfma_f32_16x16x32_bf16 v[114:117], v[170:173], v[178:181], v[114:117]
	v_mfma_f32_16x16x32_bf16 v[114:117], v[174:177], v[182:185], v[114:117]
	s_setprio 0
	s_barrier
	s_add_i32 s30, s31, s13
	v_lshl_add_u64 v[140:141], s[54:55], 0, v[194:195]
	s_mov_b32 m0, s30
	ds_read_b128 v[178:181], v145 offset:16384
	ds_read_b128 v[182:185], v145 offset:17408
	ds_read_b128 v[186:189], v145 offset:18432
	ds_read_b128 v[190:193], v145 offset:19456
	ds_read_b128 v[210:213], v145 offset:20480
	ds_read_b128 v[214:217], v145 offset:21504
	ds_read_b128 v[230:233], v145 offset:22528
	ds_read_b128 v[234:237], v145 offset:23552
	global_load_lds_dwordx4 v[140:141], off
	s_add_i32 m0, s30, 0x2000
	s_add_u32 s30, s54, 0x80000
	v_lshl_add_u64 v[218:219], s[54:55], 0, v[134:135]
	s_addc_u32 s31, s55, 0
	s_add_i32 s29, s29, s13
	global_load_lds_dwordx4 v[218:219], off
	v_lshl_add_u64 v[238:239], s[30:31], 0, v[194:195]
	s_mov_b32 m0, s29
	v_lshl_add_u64 v[240:241], vcc, 0, v[132:133]
	global_load_lds_dwordx4 v[238:239], off
	v_lshl_add_u64 v[238:239], s[30:31], 0, v[134:135]
	s_add_i32 m0, s29, 0x2000
	s_nop 0
	global_load_lds_dwordx4 v[238:239], off
	v_lshl_add_u64 v[238:239], vcc, 0, v[130:131]
	s_mov_b32 m0, s14
	s_nop 0
	global_load_lds_dwordx4 v[238:239], off
	s_mov_b32 m0, s15
	s_nop 0
	global_load_lds_dwordx4 v[240:241], off
	s_waitcnt vmcnt(8)
	s_waitcnt lgkmcnt(0)
	s_barrier
	s_setprio 1
	s_waitcnt lgkmcnt(0)
	v_mfma_f32_16x16x32_bf16 v[62:65], v[146:149], v[178:181], v[62:65]
	v_mfma_f32_16x16x32_bf16 v[62:65], v[150:153], v[182:185], v[62:65]
	v_mfma_f32_16x16x32_bf16 v[46:49], v[146:149], v[186:189], v[46:49]
	v_mfma_f32_16x16x32_bf16 v[46:49], v[150:153], v[190:193], v[46:49]
	v_mfma_f32_16x16x32_bf16 v[30:33], v[146:149], v[210:213], v[30:33]
	v_mfma_f32_16x16x32_bf16 v[30:33], v[150:153], v[214:217], v[30:33]
	v_mfma_f32_16x16x32_bf16 v[14:17], v[146:149], v[230:233], v[14:17]
	v_mfma_f32_16x16x32_bf16 v[14:17], v[150:153], v[234:237], v[14:17]
	v_mfma_f32_16x16x32_bf16 v[10:13], v[154:157], v[230:233], v[10:13]
	v_mfma_f32_16x16x32_bf16 v[10:13], v[158:161], v[234:237], v[10:13]
	v_mfma_f32_16x16x32_bf16 v[26:29], v[154:157], v[210:213], v[26:29]
	v_mfma_f32_16x16x32_bf16 v[26:29], v[158:161], v[214:217], v[26:29]
	v_mfma_f32_16x16x32_bf16 v[42:45], v[154:157], v[186:189], v[42:45]
	v_mfma_f32_16x16x32_bf16 v[42:45], v[158:161], v[190:193], v[42:45]
	v_mfma_f32_16x16x32_bf16 v[58:61], v[154:157], v[178:181], v[58:61]
	v_mfma_f32_16x16x32_bf16 v[58:61], v[158:161], v[182:185], v[58:61]
	s_setprio 0
	s_setprio 1
	v_mfma_f32_16x16x32_bf16 v[54:57], v[162:165], v[178:181], v[54:57]
	v_mfma_f32_16x16x32_bf16 v[54:57], v[166:169], v[182:185], v[54:57]
	v_mfma_f32_16x16x32_bf16 v[38:41], v[162:165], v[186:189], v[38:41]
	v_mfma_f32_16x16x32_bf16 v[38:41], v[166:169], v[190:193], v[38:41]
	v_mfma_f32_16x16x32_bf16 v[22:25], v[162:165], v[210:213], v[22:25]
	v_mfma_f32_16x16x32_bf16 v[22:25], v[166:169], v[214:217], v[22:25]
	v_mfma_f32_16x16x32_bf16 v[6:9], v[162:165], v[230:233], v[6:9]
	v_mfma_f32_16x16x32_bf16 v[6:9], v[166:169], v[234:237], v[6:9]
	v_mfma_f32_16x16x32_bf16 v[2:5], v[170:173], v[230:233], v[2:5]
	v_mfma_f32_16x16x32_bf16 v[2:5], v[174:177], v[234:237], v[2:5]
	v_mfma_f32_16x16x32_bf16 v[18:21], v[170:173], v[210:213], v[18:21]
	v_mfma_f32_16x16x32_bf16 v[18:21], v[174:177], v[214:217], v[18:21]
	v_mfma_f32_16x16x32_bf16 v[34:37], v[170:173], v[186:189], v[34:37]
	v_mfma_f32_16x16x32_bf16 v[34:37], v[174:177], v[190:193], v[34:37]
	v_mfma_f32_16x16x32_bf16 v[50:53], v[170:173], v[178:181], v[50:53]
	v_mfma_f32_16x16x32_bf16 v[50:53], v[174:177], v[182:185], v[50:53]
	s_setprio 0
	s_barrier
	s_add_i32 s29, 0, 0x18000
	s_add_i32 s45, 0, 0x1c000
	v_add_u32_e32 v158, s29, v143
	v_add_u32_e32 v174, s45, v143
	ds_read_b128 v[146:149], v158
	ds_read_b128 v[150:153], v158 offset:1024
	ds_read_b128 v[154:157], v158 offset:2048
	ds_read_b128 v[158:161], v158 offset:3072
	ds_read_b128 v[162:165], v174
	ds_read_b128 v[166:169], v174 offset:1024
	ds_read_b128 v[170:173], v174 offset:2048
	ds_read_b128 v[174:177], v174 offset:3072
	s_add_u32 s30, vcc_lo, 0x80000
	s_addc_u32 s31, vcc_hi, 0
	s_mov_b32 m0, s16
	v_lshl_add_u64 v[242:243], s[30:31], 0, v[130:131]
	ds_read_b128 v[178:181], v145 offset:32768
	ds_read_b128 v[182:185], v145 offset:33792
	ds_read_b128 v[186:189], v145 offset:34816
	ds_read_b128 v[190:193], v145 offset:35840
	ds_read_b128 v[210:213], v145 offset:36864
	ds_read_b128 v[214:217], v145 offset:37888
	ds_read_b128 v[230:233], v145 offset:38912
	ds_read_b128 v[234:237], v145 offset:39936
	global_load_lds_dwordx4 v[242:243], off
	v_lshl_add_u64 v[242:243], s[30:31], 0, v[132:133]
	s_mov_b32 m0, s17
	s_nop 0
	global_load_lds_dwordx4 v[242:243], off
	s_waitcnt vmcnt(8)
	s_waitcnt lgkmcnt(0)
	s_barrier
	s_setprio 1
	s_waitcnt lgkmcnt(0)
	v_mfma_f32_16x16x32_bf16 v[126:129], v[146:149], v[178:181], v[126:129]
	v_mfma_f32_16x16x32_bf16 v[126:129], v[150:153], v[182:185], v[126:129]
	v_mfma_f32_16x16x32_bf16 v[110:113], v[146:149], v[186:189], v[110:113]
	v_mfma_f32_16x16x32_bf16 v[110:113], v[150:153], v[190:193], v[110:113]
	v_mfma_f32_16x16x32_bf16 v[94:97], v[146:149], v[210:213], v[94:97]
	v_mfma_f32_16x16x32_bf16 v[94:97], v[150:153], v[214:217], v[94:97]
	v_mfma_f32_16x16x32_bf16 v[78:81], v[146:149], v[230:233], v[78:81]
	v_mfma_f32_16x16x32_bf16 v[78:81], v[150:153], v[234:237], v[78:81]
	v_mfma_f32_16x16x32_bf16 v[74:77], v[154:157], v[230:233], v[74:77]
	v_mfma_f32_16x16x32_bf16 v[74:77], v[158:161], v[234:237], v[74:77]
	v_mfma_f32_16x16x32_bf16 v[90:93], v[154:157], v[210:213], v[90:93]
	v_mfma_f32_16x16x32_bf16 v[90:93], v[158:161], v[214:217], v[90:93]
	v_mfma_f32_16x16x32_bf16 v[106:109], v[154:157], v[186:189], v[106:109]
	v_mfma_f32_16x16x32_bf16 v[106:109], v[158:161], v[190:193], v[106:109]
	v_mfma_f32_16x16x32_bf16 v[122:125], v[154:157], v[178:181], v[122:125]
	v_mfma_f32_16x16x32_bf16 v[122:125], v[158:161], v[182:185], v[122:125]
	s_setprio 0
	s_setprio 1
	v_mfma_f32_16x16x32_bf16 v[118:121], v[162:165], v[178:181], v[118:121]
	v_mfma_f32_16x16x32_bf16 v[118:121], v[166:169], v[182:185], v[118:121]
	v_mfma_f32_16x16x32_bf16 v[102:105], v[162:165], v[186:189], v[102:105]
	v_mfma_f32_16x16x32_bf16 v[102:105], v[166:169], v[190:193], v[102:105]
	v_mfma_f32_16x16x32_bf16 v[86:89], v[162:165], v[210:213], v[86:89]
	v_mfma_f32_16x16x32_bf16 v[86:89], v[166:169], v[214:217], v[86:89]
	v_mfma_f32_16x16x32_bf16 v[70:73], v[162:165], v[230:233], v[70:73]
	v_mfma_f32_16x16x32_bf16 v[70:73], v[166:169], v[234:237], v[70:73]
	v_mfma_f32_16x16x32_bf16 v[66:69], v[170:173], v[230:233], v[66:69]
	v_mfma_f32_16x16x32_bf16 v[66:69], v[174:177], v[234:237], v[66:69]
	v_mfma_f32_16x16x32_bf16 v[82:85], v[170:173], v[210:213], v[82:85]
	v_mfma_f32_16x16x32_bf16 v[82:85], v[174:177], v[214:217], v[82:85]
	v_mfma_f32_16x16x32_bf16 v[98:101], v[170:173], v[186:189], v[98:101]
	v_mfma_f32_16x16x32_bf16 v[98:101], v[174:177], v[190:193], v[98:101]
	v_mfma_f32_16x16x32_bf16 v[114:117], v[170:173], v[178:181], v[114:117]
	v_mfma_f32_16x16x32_bf16 v[114:117], v[174:177], v[182:185], v[114:117]
	s_setprio 0
	s_barrier
	s_add_i32 s29, s29, s13
	v_lshl_add_u64 v[140:141], v[140:141], 0, s[56:57]
	s_mov_b32 m0, s29
	ds_read_b128 v[178:181], v145 offset:49152
	ds_read_b128 v[182:185], v145 offset:50176
	ds_read_b128 v[186:189], v145 offset:51200
	ds_read_b128 v[190:193], v145 offset:52224
	ds_read_b128 v[210:213], v145 offset:53248
	ds_read_b128 v[214:217], v145 offset:54272
	ds_read_b128 v[230:233], v145 offset:55296
	ds_read_b128 v[234:237], v145 offset:56320
	global_load_lds_dwordx4 v[140:141], off
	s_add_i32 m0, s29, 0x2000
	s_add_u32 s30, s54, 0x80080
	v_lshl_add_u64 v[140:141], v[218:219], 0, s[56:57]
	s_addc_u32 s31, s55, 0
	s_add_i32 s29, s45, s13
	global_load_lds_dwordx4 v[140:141], off
	v_lshl_add_u64 v[140:141], s[30:31], 0, v[194:195]
	s_mov_b32 m0, s29
	s_nop 0
	global_load_lds_dwordx4 v[140:141], off
	v_lshl_add_u64 v[140:141], s[30:31], 0, v[134:135]
	s_add_i32 m0, s29, 0x2000
	s_nop 0
	global_load_lds_dwordx4 v[140:141], off
	v_lshl_add_u64 v[140:141], v[238:239], 0, s[56:57]
	s_mov_b32 m0, s18
	s_nop 0
	global_load_lds_dwordx4 v[140:141], off
	v_lshl_add_u64 v[140:141], v[240:241], 0, s[56:57]
	s_mov_b32 m0, s19
	s_nop 0
	global_load_lds_dwordx4 v[140:141], off
	s_waitcnt vmcnt(8)
	s_waitcnt lgkmcnt(0)
	s_barrier
	s_setprio 1
	s_waitcnt lgkmcnt(0)
	v_mfma_f32_16x16x32_bf16 v[62:65], v[146:149], v[178:181], v[62:65]
	v_mfma_f32_16x16x32_bf16 v[62:65], v[150:153], v[182:185], v[62:65]
	v_mfma_f32_16x16x32_bf16 v[46:49], v[146:149], v[186:189], v[46:49]
	v_mfma_f32_16x16x32_bf16 v[46:49], v[150:153], v[190:193], v[46:49]
	v_mfma_f32_16x16x32_bf16 v[30:33], v[146:149], v[210:213], v[30:33]
	v_mfma_f32_16x16x32_bf16 v[30:33], v[150:153], v[214:217], v[30:33]
	v_mfma_f32_16x16x32_bf16 v[14:17], v[146:149], v[230:233], v[14:17]
	v_mfma_f32_16x16x32_bf16 v[14:17], v[150:153], v[234:237], v[14:17]
	v_mfma_f32_16x16x32_bf16 v[10:13], v[154:157], v[230:233], v[10:13]
	v_mfma_f32_16x16x32_bf16 v[10:13], v[158:161], v[234:237], v[10:13]
	v_mfma_f32_16x16x32_bf16 v[26:29], v[154:157], v[210:213], v[26:29]
	v_mfma_f32_16x16x32_bf16 v[26:29], v[158:161], v[214:217], v[26:29]
	v_mfma_f32_16x16x32_bf16 v[42:45], v[154:157], v[186:189], v[42:45]
	v_mfma_f32_16x16x32_bf16 v[42:45], v[158:161], v[190:193], v[42:45]
	v_mfma_f32_16x16x32_bf16 v[58:61], v[154:157], v[178:181], v[58:61]
	v_mfma_f32_16x16x32_bf16 v[58:61], v[158:161], v[182:185], v[58:61]
	s_setprio 0
	s_setprio 1
	v_mfma_f32_16x16x32_bf16 v[54:57], v[162:165], v[178:181], v[54:57]
	v_mfma_f32_16x16x32_bf16 v[54:57], v[166:169], v[182:185], v[54:57]
	v_mfma_f32_16x16x32_bf16 v[38:41], v[162:165], v[186:189], v[38:41]
	v_mfma_f32_16x16x32_bf16 v[38:41], v[166:169], v[190:193], v[38:41]
	v_mfma_f32_16x16x32_bf16 v[22:25], v[162:165], v[210:213], v[22:25]
	v_mfma_f32_16x16x32_bf16 v[22:25], v[166:169], v[214:217], v[22:25]
	v_mfma_f32_16x16x32_bf16 v[6:9], v[162:165], v[230:233], v[6:9]
	v_mfma_f32_16x16x32_bf16 v[6:9], v[166:169], v[234:237], v[6:9]
	v_mfma_f32_16x16x32_bf16 v[2:5], v[170:173], v[230:233], v[2:5]
	v_mfma_f32_16x16x32_bf16 v[2:5], v[174:177], v[234:237], v[2:5]
	v_mfma_f32_16x16x32_bf16 v[18:21], v[170:173], v[210:213], v[18:21]
	v_mfma_f32_16x16x32_bf16 v[18:21], v[174:177], v[214:217], v[18:21]
	v_mfma_f32_16x16x32_bf16 v[34:37], v[170:173], v[186:189], v[34:37]
	v_mfma_f32_16x16x32_bf16 v[34:37], v[174:177], v[190:193], v[34:37]
	v_mfma_f32_16x16x32_bf16 v[50:53], v[170:173], v[178:181], v[50:53]
	v_mfma_f32_16x16x32_bf16 v[50:53], v[174:177], v[182:185], v[50:53]
	s_setprio 0
	s_barrier
	s_add_i32 s28, s28, 2
	s_add_u32 s26, s26, 0x100
	s_addc_u32 s27, s27, 0
	s_add_u32 s90, s90, 0x100
	s_addc_u32 s91, s91, 0
	s_cmp_gt_u32 s28, 29
	s_cbranch_scc0 .LBB0_1609
	s_and_b64 vcc, exec, s[36:37]
	s_cbranch_vccz .LBB0_1612
	s_barrier

.LBB0_1688:
	s_add_u32 s28, s90, 0xffe00080
	s_addc_u32 s29, s91, -1
	s_add_i32 s30, 0, 0x10000
	s_cmpk_eq_i32 s27, 0x7c
	s_cselect_b32 vcc_hi, s21, s29
	s_cselect_b32 vcc_lo, s22, s28
	v_add_u32_e32 v140, s30, v143
	s_cselect_b32 s55, s23, s26
	s_cselect_b32 s54, s24, s25
	s_add_i32 s31, 0, 0x14000
	ds_read_b128 v[146:149], v140
	ds_read_b128 v[150:153], v140 offset:1024
	ds_read_b128 v[154:157], v140 offset:2048
	ds_read_b128 v[158:161], v140 offset:3072
	v_add_u32_e32 v140, s31, v143
	ds_read_b128 v[162:165], v140
	ds_read_b128 v[166:169], v140 offset:1024
	ds_read_b128 v[170:173], v140 offset:2048
	ds_read_b128 v[174:177], v140 offset:3072
	v_lshl_add_u64 v[140:141], s[90:91], 0, v[138:139]
	s_add_i32 m0, s13, 0xc000
	ds_read_b128 v[178:181], v145
	ds_read_b128 v[182:185], v145 offset:1024
	ds_read_b128 v[186:189], v145 offset:2048
	ds_read_b128 v[190:193], v145 offset:3072
	ds_read_b128 v[210:213], v145 offset:4096
	ds_read_b128 v[214:217], v145 offset:5120
	ds_read_b128 v[230:233], v145 offset:6144
	ds_read_b128 v[234:237], v145 offset:7168
	global_load_lds_dwordx4 v[140:141], off
	v_lshl_add_u64 v[140:141], s[90:91], 0, v[136:137]
	s_add_i32 m0, s13, 0xe000
	s_nop 0
	global_load_lds_dwordx4 v[140:141], off
	s_waitcnt vmcnt(8)
	s_waitcnt lgkmcnt(0)
	s_barrier
	s_setprio 1
	s_waitcnt lgkmcnt(0)
	v_mfma_f32_16x16x32_bf16 v[126:129], v[146:149], v[178:181], v[126:129]
	v_mfma_f32_16x16x32_bf16 v[126:129], v[150:153], v[182:185], v[126:129]
	v_mfma_f32_16x16x32_bf16 v[118:121], v[146:149], v[186:189], v[118:121]
	v_mfma_f32_16x16x32_bf16 v[118:121], v[150:153], v[190:193], v[118:121]
	v_mfma_f32_16x16x32_bf16 v[102:105], v[146:149], v[210:213], v[102:105]
	v_mfma_f32_16x16x32_bf16 v[102:105], v[150:153], v[214:217], v[102:105]
	v_mfma_f32_16x16x32_bf16 v[86:89], v[146:149], v[230:233], v[86:89]
	v_mfma_f32_16x16x32_bf16 v[86:89], v[150:153], v[234:237], v[86:89]
	v_mfma_f32_16x16x32_bf16 v[78:81], v[154:157], v[230:233], v[78:81]
	v_mfma_f32_16x16x32_bf16 v[78:81], v[158:161], v[234:237], v[78:81]
	v_mfma_f32_16x16x32_bf16 v[94:97], v[154:157], v[210:213], v[94:97]
	v_mfma_f32_16x16x32_bf16 v[94:97], v[158:161], v[214:217], v[94:97]
	v_mfma_f32_16x16x32_bf16 v[110:113], v[154:157], v[186:189], v[110:113]
	v_mfma_f32_16x16x32_bf16 v[110:113], v[158:161], v[190:193], v[110:113]
	v_mfma_f32_16x16x32_bf16 v[122:125], v[154:157], v[178:181], v[122:125]
	v_mfma_f32_16x16x32_bf16 v[122:125], v[158:161], v[182:185], v[122:125]
	s_setprio 0
	s_setprio 1
	v_mfma_f32_16x16x32_bf16 v[114:117], v[162:165], v[178:181], v[114:117]
	v_mfma_f32_16x16x32_bf16 v[114:117], v[166:169], v[182:185], v[114:117]
	v_mfma_f32_16x16x32_bf16 v[98:101], v[162:165], v[186:189], v[98:101]
	v_mfma_f32_16x16x32_bf16 v[98:101], v[166:169], v[190:193], v[98:101]
	v_mfma_f32_16x16x32_bf16 v[82:85], v[162:165], v[210:213], v[82:85]
	v_mfma_f32_16x16x32_bf16 v[82:85], v[166:169], v[214:217], v[82:85]
	v_mfma_f32_16x16x32_bf16 v[70:73], v[162:165], v[230:233], v[70:73]
	v_mfma_f32_16x16x32_bf16 v[70:73], v[166:169], v[234:237], v[70:73]
	v_mfma_f32_16x16x32_bf16 v[66:69], v[170:173], v[230:233], v[66:69]
	v_mfma_f32_16x16x32_bf16 v[66:69], v[174:177], v[234:237], v[66:69]
	v_mfma_f32_16x16x32_bf16 v[74:77], v[170:173], v[210:213], v[74:77]
	v_mfma_f32_16x16x32_bf16 v[74:77], v[174:177], v[214:217], v[74:77]
	v_mfma_f32_16x16x32_bf16 v[90:93], v[170:173], v[186:189], v[90:93]
	v_mfma_f32_16x16x32_bf16 v[90:93], v[174:177], v[190:193], v[90:93]
	v_mfma_f32_16x16x32_bf16 v[106:109], v[170:173], v[178:181], v[106:109]
	v_mfma_f32_16x16x32_bf16 v[106:109], v[174:177], v[182:185], v[106:109]
	s_setprio 0
	s_barrier
	s_add_i32 s28, s30, s12
	v_lshl_add_u64 v[140:141], s[54:55], 0, v[194:195]
	s_mov_b32 m0, s28
	ds_read_b128 v[178:181], v145 offset:16384
	ds_read_b128 v[182:185], v145 offset:17408
	ds_read_b128 v[186:189], v145 offset:18432
	ds_read_b128 v[190:193], v145 offset:19456
	ds_read_b128 v[210:213], v145 offset:20480
	ds_read_b128 v[214:217], v145 offset:21504
	ds_read_b128 v[230:233], v145 offset:22528
	ds_read_b128 v[234:237], v145 offset:23552
	global_load_lds_dwordx4 v[140:141], off
	s_add_i32 m0, s28, 0x2000
	s_add_u32 s28, s54, 0x200000
	v_lshl_add_u64 v[218:219], s[54:55], 0, v[134:135]
	s_addc_u32 s29, s55, 0
	s_add_i32 s30, s31, s12
	global_load_lds_dwordx4 v[218:219], off
	v_lshl_add_u64 v[238:239], s[28:29], 0, v[194:195]
	s_mov_b32 m0, s30
	v_lshl_add_u64 v[240:241], vcc, 0, v[132:133]
	global_load_lds_dwordx4 v[238:239], off
	v_lshl_add_u64 v[238:239], s[28:29], 0, v[134:135]
	s_add_i32 m0, s30, 0x2000
	s_nop 0
	global_load_lds_dwordx4 v[238:239], off
	v_lshl_add_u64 v[238:239], vcc, 0, v[130:131]
	s_mov_b32 m0, s13
	s_nop 0
	global_load_lds_dwordx4 v[238:239], off
	s_mov_b32 m0, s14
	s_nop 0
	global_load_lds_dwordx4 v[240:241], off
	s_waitcnt vmcnt(8)
	s_waitcnt lgkmcnt(0)
	s_barrier
	s_setprio 1
	s_waitcnt lgkmcnt(0)
	v_mfma_f32_16x16x32_bf16 v[62:65], v[146:149], v[178:181], v[62:65]
	v_mfma_f32_16x16x32_bf16 v[62:65], v[150:153], v[182:185], v[62:65]
	v_mfma_f32_16x16x32_bf16 v[54:57], v[146:149], v[186:189], v[54:57]
	v_mfma_f32_16x16x32_bf16 v[54:57], v[150:153], v[190:193], v[54:57]
	v_mfma_f32_16x16x32_bf16 v[38:41], v[146:149], v[210:213], v[38:41]
	v_mfma_f32_16x16x32_bf16 v[38:41], v[150:153], v[214:217], v[38:41]
	v_mfma_f32_16x16x32_bf16 v[22:25], v[146:149], v[230:233], v[22:25]
	v_mfma_f32_16x16x32_bf16 v[22:25], v[150:153], v[234:237], v[22:25]
	v_mfma_f32_16x16x32_bf16 v[14:17], v[154:157], v[230:233], v[14:17]
	v_mfma_f32_16x16x32_bf16 v[14:17], v[158:161], v[234:237], v[14:17]
	v_mfma_f32_16x16x32_bf16 v[30:33], v[154:157], v[210:213], v[30:33]
	v_mfma_f32_16x16x32_bf16 v[30:33], v[158:161], v[214:217], v[30:33]
	v_mfma_f32_16x16x32_bf16 v[46:49], v[154:157], v[186:189], v[46:49]
	v_mfma_f32_16x16x32_bf16 v[46:49], v[158:161], v[190:193], v[46:49]
	v_mfma_f32_16x16x32_bf16 v[58:61], v[154:157], v[178:181], v[58:61]
	v_mfma_f32_16x16x32_bf16 v[58:61], v[158:161], v[182:185], v[58:61]
	s_setprio 0
	s_setprio 1
	v_mfma_f32_16x16x32_bf16 v[50:53], v[162:165], v[178:181], v[50:53]
	v_mfma_f32_16x16x32_bf16 v[50:53], v[166:169], v[182:185], v[50:53]
	v_mfma_f32_16x16x32_bf16 v[34:37], v[162:165], v[186:189], v[34:37]
	v_mfma_f32_16x16x32_bf16 v[34:37], v[166:169], v[190:193], v[34:37]
	v_mfma_f32_16x16x32_bf16 v[18:21], v[162:165], v[210:213], v[18:21]
	v_mfma_f32_16x16x32_bf16 v[18:21], v[166:169], v[214:217], v[18:21]
	v_mfma_f32_16x16x32_bf16 v[6:9], v[162:165], v[230:233], v[6:9]
	v_mfma_f32_16x16x32_bf16 v[6:9], v[166:169], v[234:237], v[6:9]
	v_mfma_f32_16x16x32_bf16 v[2:5], v[170:173], v[230:233], v[2:5]
	v_mfma_f32_16x16x32_bf16 v[2:5], v[174:177], v[234:237], v[2:5]
	v_mfma_f32_16x16x32_bf16 v[10:13], v[170:173], v[210:213], v[10:13]
	v_mfma_f32_16x16x32_bf16 v[10:13], v[174:177], v[214:217], v[10:13]
	v_mfma_f32_16x16x32_bf16 v[26:29], v[170:173], v[186:189], v[26:29]
	v_mfma_f32_16x16x32_bf16 v[26:29], v[174:177], v[190:193], v[26:29]
	v_mfma_f32_16x16x32_bf16 v[42:45], v[170:173], v[178:181], v[42:45]
	v_mfma_f32_16x16x32_bf16 v[42:45], v[174:177], v[182:185], v[42:45]
	s_setprio 0
	s_barrier
	s_add_i32 s30, 0, 0x18000
	s_add_i32 s31, 0, 0x1c000
	v_add_u32_e32 v158, s30, v143
	v_add_u32_e32 v174, s31, v143
	ds_read_b128 v[146:149], v158
	ds_read_b128 v[150:153], v158 offset:1024
	ds_read_b128 v[154:157], v158 offset:2048
	ds_read_b128 v[158:161], v158 offset:3072
	ds_read_b128 v[162:165], v174
	ds_read_b128 v[166:169], v174 offset:1024
	ds_read_b128 v[170:173], v174 offset:2048
	ds_read_b128 v[174:177], v174 offset:3072
	s_add_u32 s28, vcc_lo, 0x200000
	s_addc_u32 s29, vcc_hi, 0
	s_mov_b32 m0, s15
	v_lshl_add_u64 v[242:243], s[28:29], 0, v[130:131]
	ds_read_b128 v[178:181], v145 offset:32768
	ds_read_b128 v[182:185], v145 offset:33792
	ds_read_b128 v[186:189], v145 offset:34816
	ds_read_b128 v[190:193], v145 offset:35840
	ds_read_b128 v[210:213], v145 offset:36864
	ds_read_b128 v[214:217], v145 offset:37888
	ds_read_b128 v[230:233], v145 offset:38912
	ds_read_b128 v[234:237], v145 offset:39936
	global_load_lds_dwordx4 v[242:243], off
	v_lshl_add_u64 v[242:243], s[28:29], 0, v[132:133]
	s_mov_b32 m0, s16
	s_nop 0
	global_load_lds_dwordx4 v[242:243], off
	s_waitcnt vmcnt(8)
	s_waitcnt lgkmcnt(0)
	s_barrier
	s_setprio 1
	s_waitcnt lgkmcnt(0)
	v_mfma_f32_16x16x32_bf16 v[126:129], v[146:149], v[178:181], v[126:129]
	v_mfma_f32_16x16x32_bf16 v[126:129], v[150:153], v[182:185], v[126:129]
	v_mfma_f32_16x16x32_bf16 v[118:121], v[146:149], v[186:189], v[118:121]
	v_mfma_f32_16x16x32_bf16 v[118:121], v[150:153], v[190:193], v[118:121]
	v_mfma_f32_16x16x32_bf16 v[102:105], v[146:149], v[210:213], v[102:105]
	v_mfma_f32_16x16x32_bf16 v[102:105], v[150:153], v[214:217], v[102:105]
	v_mfma_f32_16x16x32_bf16 v[86:89], v[146:149], v[230:233], v[86:89]
	v_mfma_f32_16x16x32_bf16 v[86:89], v[150:153], v[234:237], v[86:89]
	v_mfma_f32_16x16x32_bf16 v[78:81], v[154:157], v[230:233], v[78:81]
	v_mfma_f32_16x16x32_bf16 v[78:81], v[158:161], v[234:237], v[78:81]
	v_mfma_f32_16x16x32_bf16 v[94:97], v[154:157], v[210:213], v[94:97]
	v_mfma_f32_16x16x32_bf16 v[94:97], v[158:161], v[214:217], v[94:97]
	v_mfma_f32_16x16x32_bf16 v[110:113], v[154:157], v[186:189], v[110:113]
	v_mfma_f32_16x16x32_bf16 v[110:113], v[158:161], v[190:193], v[110:113]
	v_mfma_f32_16x16x32_bf16 v[122:125], v[154:157], v[178:181], v[122:125]
	v_mfma_f32_16x16x32_bf16 v[122:125], v[158:161], v[182:185], v[122:125]
	s_setprio 0
	s_setprio 1
	v_mfma_f32_16x16x32_bf16 v[114:117], v[162:165], v[178:181], v[114:117]
	v_mfma_f32_16x16x32_bf16 v[114:117], v[166:169], v[182:185], v[114:117]
	v_mfma_f32_16x16x32_bf16 v[98:101], v[162:165], v[186:189], v[98:101]
	v_mfma_f32_16x16x32_bf16 v[98:101], v[166:169], v[190:193], v[98:101]
	v_mfma_f32_16x16x32_bf16 v[82:85], v[162:165], v[210:213], v[82:85]
	v_mfma_f32_16x16x32_bf16 v[82:85], v[166:169], v[214:217], v[82:85]
	v_mfma_f32_16x16x32_bf16 v[70:73], v[162:165], v[230:233], v[70:73]
	v_mfma_f32_16x16x32_bf16 v[70:73], v[166:169], v[234:237], v[70:73]
	v_mfma_f32_16x16x32_bf16 v[66:69], v[170:173], v[230:233], v[66:69]
	v_mfma_f32_16x16x32_bf16 v[66:69], v[174:177], v[234:237], v[66:69]
	v_mfma_f32_16x16x32_bf16 v[74:77], v[170:173], v[210:213], v[74:77]
	v_mfma_f32_16x16x32_bf16 v[74:77], v[174:177], v[214:217], v[74:77]
	v_mfma_f32_16x16x32_bf16 v[90:93], v[170:173], v[186:189], v[90:93]
	v_mfma_f32_16x16x32_bf16 v[90:93], v[174:177], v[190:193], v[90:93]
	v_mfma_f32_16x16x32_bf16 v[106:109], v[170:173], v[178:181], v[106:109]
	v_mfma_f32_16x16x32_bf16 v[106:109], v[174:177], v[182:185], v[106:109]
	s_setprio 0
	s_barrier
	s_add_i32 s28, s30, s12
	v_lshl_add_u64 v[140:141], v[140:141], 0, s[56:57]
	s_mov_b32 m0, s28
	ds_read_b128 v[178:181], v145 offset:49152
	ds_read_b128 v[182:185], v145 offset:50176
	ds_read_b128 v[186:189], v145 offset:51200
	ds_read_b128 v[190:193], v145 offset:52224
	ds_read_b128 v[210:213], v145 offset:53248
	ds_read_b128 v[214:217], v145 offset:54272
	ds_read_b128 v[230:233], v145 offset:55296
	ds_read_b128 v[234:237], v145 offset:56320
	global_load_lds_dwordx4 v[140:141], off
	s_add_i32 m0, s28, 0x2000
	s_add_u32 s28, s54, 0x200080
	v_lshl_add_u64 v[140:141], v[218:219], 0, s[56:57]
	s_addc_u32 s29, s55, 0
	s_add_i32 s30, s31, s12
	global_load_lds_dwordx4 v[140:141], off
	v_lshl_add_u64 v[140:141], s[28:29], 0, v[194:195]
	s_mov_b32 m0, s30
	s_nop 0
	global_load_lds_dwordx4 v[140:141], off
	v_lshl_add_u64 v[140:141], s[28:29], 0, v[134:135]
	s_add_i32 m0, s30, 0x2000
	s_nop 0
	global_load_lds_dwordx4 v[140:141], off
	v_lshl_add_u64 v[140:141], v[238:239], 0, s[56:57]
	s_mov_b32 m0, s17
	s_nop 0
	global_load_lds_dwordx4 v[140:141], off
	v_lshl_add_u64 v[140:141], v[240:241], 0, s[56:57]
	s_mov_b32 m0, s18
	s_nop 0
	global_load_lds_dwordx4 v[140:141], off
	s_waitcnt vmcnt(8)
	s_waitcnt lgkmcnt(0)
	s_barrier
	s_setprio 1
	s_waitcnt lgkmcnt(0)
	v_mfma_f32_16x16x32_bf16 v[62:65], v[146:149], v[178:181], v[62:65]
	v_mfma_f32_16x16x32_bf16 v[62:65], v[150:153], v[182:185], v[62:65]
	v_mfma_f32_16x16x32_bf16 v[54:57], v[146:149], v[186:189], v[54:57]
	v_mfma_f32_16x16x32_bf16 v[54:57], v[150:153], v[190:193], v[54:57]
	v_mfma_f32_16x16x32_bf16 v[38:41], v[146:149], v[210:213], v[38:41]
	v_mfma_f32_16x16x32_bf16 v[38:41], v[150:153], v[214:217], v[38:41]
	v_mfma_f32_16x16x32_bf16 v[22:25], v[146:149], v[230:233], v[22:25]
	v_mfma_f32_16x16x32_bf16 v[22:25], v[150:153], v[234:237], v[22:25]
	v_mfma_f32_16x16x32_bf16 v[14:17], v[154:157], v[230:233], v[14:17]
	v_mfma_f32_16x16x32_bf16 v[14:17], v[158:161], v[234:237], v[14:17]
	v_mfma_f32_16x16x32_bf16 v[30:33], v[154:157], v[210:213], v[30:33]
	v_mfma_f32_16x16x32_bf16 v[30:33], v[158:161], v[214:217], v[30:33]
	v_mfma_f32_16x16x32_bf16 v[46:49], v[154:157], v[186:189], v[46:49]
	v_mfma_f32_16x16x32_bf16 v[46:49], v[158:161], v[190:193], v[46:49]
	v_mfma_f32_16x16x32_bf16 v[58:61], v[154:157], v[178:181], v[58:61]
	v_mfma_f32_16x16x32_bf16 v[58:61], v[158:161], v[182:185], v[58:61]
	s_setprio 0
	s_setprio 1
	v_mfma_f32_16x16x32_bf16 v[50:53], v[162:165], v[178:181], v[50:53]
	v_mfma_f32_16x16x32_bf16 v[50:53], v[166:169], v[182:185], v[50:53]
	v_mfma_f32_16x16x32_bf16 v[34:37], v[162:165], v[186:189], v[34:37]
	v_mfma_f32_16x16x32_bf16 v[34:37], v[166:169], v[190:193], v[34:37]
	v_mfma_f32_16x16x32_bf16 v[18:21], v[162:165], v[210:213], v[18:21]
	v_mfma_f32_16x16x32_bf16 v[18:21], v[166:169], v[214:217], v[18:21]
	v_mfma_f32_16x16x32_bf16 v[6:9], v[162:165], v[230:233], v[6:9]
	v_mfma_f32_16x16x32_bf16 v[6:9], v[166:169], v[234:237], v[6:9]
	v_mfma_f32_16x16x32_bf16 v[2:5], v[170:173], v[230:233], v[2:5]
	v_mfma_f32_16x16x32_bf16 v[2:5], v[174:177], v[234:237], v[2:5]
	v_mfma_f32_16x16x32_bf16 v[10:13], v[170:173], v[210:213], v[10:13]
	v_mfma_f32_16x16x32_bf16 v[10:13], v[174:177], v[214:217], v[10:13]
	v_mfma_f32_16x16x32_bf16 v[26:29], v[170:173], v[186:189], v[26:29]
	v_mfma_f32_16x16x32_bf16 v[26:29], v[174:177], v[190:193], v[26:29]
	v_mfma_f32_16x16x32_bf16 v[42:45], v[170:173], v[178:181], v[42:45]
	v_mfma_f32_16x16x32_bf16 v[42:45], v[174:177], v[182:185], v[42:45]
	s_setprio 0
	s_barrier
	s_add_i32 s27, s27, 2
	s_add_u32 s25, s25, 0x100
	s_addc_u32 s26, s26, 0
	s_add_u32 s90, s90, 0x100
	s_addc_u32 s91, s91, 0
	s_cmpk_gt_u32 s27, 0x7d
	s_cbranch_scc0 .LBB0_1688
	s_and_b64 vcc, exec, s[52:53]
	s_cbranch_vccz .LBB0_1691
	s_barrier
